# K-loop with accumulate chains: the six-piece load segments run at priority 0 again (the loading wave no longer outranks the MFMA wave for vector issue)
# baseline (speedup 1.0000x reference)
.LBB0_322:
	s_ashr_i32 s43, s42, 31
	s_lshl_b64 s[46:47], s[42:43], 19
	s_add_u32 s46, s12, s46
	s_addc_u32 s47, s13, s47
	s_and_b64 s[48:49], s[4:5], exec
	s_cselect_b32 s18, s47, s7
	s_cselect_b32 s43, s46, s6
	s_ashr_i32 s45, s44, 31
	s_lshl_b64 s[48:49], s[44:45], 19
	s_add_u32 s48, s59, s48
	s_addc_u32 s49, s60, s49
	s_and_b64 s[50:51], s[4:5], exec
	s_cselect_b32 s45, s49, s9
	s_cselect_b32 s55, s48, s8
	s_add_u32 s6, s6, 0x40080
	s_addc_u32 s7, s7, 0
	s_add_u32 s56, s8, 0x100
	s_addc_u32 s57, s9, 0
	s_mov_b32 s78, -2
	ds_read_b128 v[96:99], v209
	ds_read_b128 v[100:103], v209 offset:1024
	ds_read_b128 v[120:123], v209 offset:2048
	ds_read_b128 v[124:127], v209 offset:3072
	ds_read_b128 v[144:147], v210
	ds_read_b128 v[148:151], v210 offset:1024
	ds_read_b128 v[152:155], v210 offset:2048
	ds_read_b128 v[156:159], v210 offset:3072
	s_add_u32 s8, s6, 0xfffc0080
	s_addc_u32 s9, s7, -1
	s_cmp_eq_u32 s78, 12
	s_cselect_b32 s51, s18, s9
	s_cselect_b32 s50, s43, s8
	s_cselect_b32 s9, s45, s57
	s_cselect_b32 s8, s55, s56
	v_lshl_add_u64 v[206:207], s[6:7], 0, v[170:171]
	s_add_i32 m0, s17, 0xc000
	ds_read_b128 v[178:181], v211
	ds_read_b128 v[182:185], v211 offset:1024
	ds_read_b128 v[186:189], v211 offset:2048
	ds_read_b128 v[190:193], v211 offset:3072
	ds_read_b128 v[194:197], v211 offset:4096
	ds_read_b128 v[198:201], v211 offset:5120
	ds_read_b128 v[202:205], v211 offset:6144
	ds_read_b128 v[218:221], v211 offset:7168
	global_load_lds_dwordx4 v[206:207], off
	s_add_i32 m0, s17, 0xe000
	v_lshl_add_u64 v[206:207], s[6:7], 0, v[172:173]
	global_load_lds_dwordx4 v[206:207], off
	s_waitcnt vmcnt(8) lgkmcnt(0)
	s_barrier
	s_setprio 1
	v_mfma_f32_16x16x32_bf16 v[140:143], v[96:99], v[178:181], 0
	v_mfma_f32_16x16x32_bf16 v[140:143], v[100:103], v[182:185], v[140:143]
	v_mfma_f32_16x16x32_bf16 v[116:119], v[96:99], v[186:189], 0
	v_mfma_f32_16x16x32_bf16 v[116:119], v[100:103], v[190:193], v[116:119]
	v_mfma_f32_16x16x32_bf16 v[92:95], v[96:99], v[194:197], 0
	v_mfma_f32_16x16x32_bf16 v[92:95], v[100:103], v[198:201], v[92:95]
	v_mfma_f32_16x16x32_bf16 v[76:79], v[96:99], v[202:205], 0
	v_mfma_f32_16x16x32_bf16 v[76:79], v[100:103], v[218:221], v[76:79]
	v_mfma_f32_16x16x32_bf16 v[136:139], v[120:123], v[178:181], 0
	v_mfma_f32_16x16x32_bf16 v[136:139], v[124:127], v[182:185], v[136:139]
	v_mfma_f32_16x16x32_bf16 v[112:115], v[120:123], v[186:189], 0
	v_mfma_f32_16x16x32_bf16 v[112:115], v[124:127], v[190:193], v[112:115]
	v_mfma_f32_16x16x32_bf16 v[88:91], v[120:123], v[194:197], 0
	v_mfma_f32_16x16x32_bf16 v[88:91], v[124:127], v[198:201], v[88:91]
	v_mfma_f32_16x16x32_bf16 v[72:75], v[120:123], v[202:205], 0
	v_mfma_f32_16x16x32_bf16 v[72:75], v[124:127], v[218:221], v[72:75]
	v_mfma_f32_16x16x32_bf16 v[132:135], v[144:147], v[178:181], 0
	v_mfma_f32_16x16x32_bf16 v[132:135], v[148:151], v[182:185], v[132:135]
	v_mfma_f32_16x16x32_bf16 v[108:111], v[144:147], v[186:189], 0
	v_mfma_f32_16x16x32_bf16 v[108:111], v[148:151], v[190:193], v[108:111]
	v_mfma_f32_16x16x32_bf16 v[84:87], v[144:147], v[194:197], 0
	v_mfma_f32_16x16x32_bf16 v[84:87], v[148:151], v[198:201], v[84:87]
	v_mfma_f32_16x16x32_bf16 v[68:71], v[144:147], v[202:205], 0
	v_mfma_f32_16x16x32_bf16 v[68:71], v[148:151], v[218:221], v[68:71]
	v_mfma_f32_16x16x32_bf16 v[128:131], v[152:155], v[178:181], 0
	v_mfma_f32_16x16x32_bf16 v[128:131], v[156:159], v[182:185], v[128:131]
	v_mfma_f32_16x16x32_bf16 v[104:107], v[152:155], v[186:189], 0
	v_mfma_f32_16x16x32_bf16 v[104:107], v[156:159], v[190:193], v[104:107]
	s_setprio 2
	s_barrier
	v_mfma_f32_16x16x32_bf16 v[80:83], v[152:155], v[194:197], 0
	v_mfma_f32_16x16x32_bf16 v[80:83], v[156:159], v[198:201], v[80:83]
	v_mfma_f32_16x16x32_bf16 v[64:67], v[152:155], v[202:205], 0
	v_mfma_f32_16x16x32_bf16 v[64:67], v[156:159], v[218:221], v[64:67]
	s_setprio 0
	s_add_i32 s79, s73, s61
	v_lshl_add_u64 v[206:207], s[8:9], 0, v[162:163]
	s_mov_b32 m0, s79
	ds_read_b128 v[178:181], v211 offset:16384
	ds_read_b128 v[182:185], v211 offset:17408
	ds_read_b128 v[186:189], v211 offset:18432
	ds_read_b128 v[190:193], v211 offset:19456
	ds_read_b128 v[194:197], v211 offset:20480
	ds_read_b128 v[198:201], v211 offset:21504
	ds_read_b128 v[202:205], v211 offset:22528
	ds_read_b128 v[218:221], v211 offset:23552
	global_load_lds_dwordx4 v[206:207], off
	s_add_i32 m0, s79, 0x2000
	s_add_u32 s80, s8, 0x40000
	v_lshl_add_u64 v[222:223], s[8:9], 0, v[166:167]
	s_addc_u32 s81, s9, 0
	s_add_i32 s79, s74, s61
	global_load_lds_dwordx4 v[222:223], off
	v_lshl_add_u64 v[224:225], s[80:81], 0, v[162:163]
	s_mov_b32 m0, s79
	v_lshl_add_u64 v[226:227], s[50:51], 0, v[164:165]
	global_load_lds_dwordx4 v[224:225], off
	s_add_i32 m0, s79, 0x2000
	v_lshl_add_u64 v[224:225], s[80:81], 0, v[166:167]
	global_load_lds_dwordx4 v[224:225], off
	s_mov_b32 m0, s17
	v_lshl_add_u64 v[224:225], s[50:51], 0, v[160:161]
	global_load_lds_dwordx4 v[224:225], off
	s_mov_b32 m0, s62
	s_nop 0
	global_load_lds_dwordx4 v[226:227], off
	s_waitcnt vmcnt(8) lgkmcnt(0)
	s_barrier
	s_setprio 1
	v_mfma_f32_16x16x32_bf16 v[60:63], v[96:99], v[178:181], 0
	v_mfma_f32_16x16x32_bf16 v[60:63], v[100:103], v[182:185], v[60:63]
	v_mfma_f32_16x16x32_bf16 v[44:47], v[96:99], v[186:189], 0
	v_mfma_f32_16x16x32_bf16 v[44:47], v[100:103], v[190:193], v[44:47]
	v_mfma_f32_16x16x32_bf16 v[28:31], v[96:99], v[194:197], 0
	v_mfma_f32_16x16x32_bf16 v[28:31], v[100:103], v[198:201], v[28:31]
	v_mfma_f32_16x16x32_bf16 v[12:15], v[96:99], v[202:205], 0
	v_mfma_f32_16x16x32_bf16 v[12:15], v[100:103], v[218:221], v[12:15]
	v_mfma_f32_16x16x32_bf16 v[56:59], v[120:123], v[178:181], 0
	v_mfma_f32_16x16x32_bf16 v[56:59], v[124:127], v[182:185], v[56:59]
	v_mfma_f32_16x16x32_bf16 v[40:43], v[120:123], v[186:189], 0
	v_mfma_f32_16x16x32_bf16 v[40:43], v[124:127], v[190:193], v[40:43]
	v_mfma_f32_16x16x32_bf16 v[24:27], v[120:123], v[194:197], 0
	v_mfma_f32_16x16x32_bf16 v[24:27], v[124:127], v[198:201], v[24:27]
	v_mfma_f32_16x16x32_bf16 v[8:11], v[120:123], v[202:205], 0
	v_mfma_f32_16x16x32_bf16 v[8:11], v[124:127], v[218:221], v[8:11]
	v_mfma_f32_16x16x32_bf16 v[52:55], v[144:147], v[178:181], 0
	v_mfma_f32_16x16x32_bf16 v[52:55], v[148:151], v[182:185], v[52:55]
	v_mfma_f32_16x16x32_bf16 v[36:39], v[144:147], v[186:189], 0
	v_mfma_f32_16x16x32_bf16 v[36:39], v[148:151], v[190:193], v[36:39]
	v_mfma_f32_16x16x32_bf16 v[20:23], v[144:147], v[194:197], 0
	v_mfma_f32_16x16x32_bf16 v[20:23], v[148:151], v[198:201], v[20:23]
	v_mfma_f32_16x16x32_bf16 v[4:7], v[144:147], v[202:205], 0
	v_mfma_f32_16x16x32_bf16 v[4:7], v[148:151], v[218:221], v[4:7]
	v_mfma_f32_16x16x32_bf16 v[48:51], v[152:155], v[178:181], 0
	v_mfma_f32_16x16x32_bf16 v[48:51], v[156:159], v[182:185], v[48:51]
	v_mfma_f32_16x16x32_bf16 v[32:35], v[152:155], v[186:189], 0
	v_mfma_f32_16x16x32_bf16 v[32:35], v[156:159], v[190:193], v[32:35]
	s_setprio 2
	s_barrier
	v_mfma_f32_16x16x32_bf16 v[16:19], v[152:155], v[194:197], 0
	v_mfma_f32_16x16x32_bf16 v[16:19], v[156:159], v[198:201], v[16:19]
	v_mfma_f32_16x16x32_bf16 v[0:3], v[152:155], v[202:205], 0
	v_mfma_f32_16x16x32_bf16 v[0:3], v[156:159], v[218:221], v[0:3]
	s_setprio 0
	s_add_i32 s79, 0, 0x18000
	s_add_i32 s80, 0, 0x1c000
	v_add_u32_e32 v124, s79, v208
	v_add_u32_e32 v156, s80, v208
	ds_read_b128 v[96:99], v124
	ds_read_b128 v[100:103], v124 offset:1024
	ds_read_b128 v[120:123], v124 offset:2048
	ds_read_b128 v[124:127], v124 offset:3072
	ds_read_b128 v[144:147], v156
	ds_read_b128 v[148:151], v156 offset:1024
	ds_read_b128 v[152:155], v156 offset:2048
	ds_read_b128 v[156:159], v156 offset:3072
	s_add_u32 s50, s50, 0x40000
	s_addc_u32 s51, s51, 0
	s_mov_b32 m0, s63
	v_lshl_add_u64 v[228:229], s[50:51], 0, v[160:161]
	ds_read_b128 v[178:181], v211 offset:32768
	ds_read_b128 v[182:185], v211 offset:33792
	ds_read_b128 v[186:189], v211 offset:34816
	ds_read_b128 v[190:193], v211 offset:35840
	ds_read_b128 v[194:197], v211 offset:36864
	ds_read_b128 v[198:201], v211 offset:37888
	ds_read_b128 v[202:205], v211 offset:38912
	ds_read_b128 v[218:221], v211 offset:39936
	global_load_lds_dwordx4 v[228:229], off
	s_mov_b32 m0, s64
	v_lshl_add_u64 v[228:229], s[50:51], 0, v[164:165]
	global_load_lds_dwordx4 v[228:229], off
	s_waitcnt vmcnt(8) lgkmcnt(0)
	s_barrier
	s_setprio 1
	v_mfma_f32_16x16x32_bf16 v[140:143], v[96:99], v[178:181], v[140:143]
	v_mfma_f32_16x16x32_bf16 v[140:143], v[100:103], v[182:185], v[140:143]
	v_mfma_f32_16x16x32_bf16 v[116:119], v[96:99], v[186:189], v[116:119]
	v_mfma_f32_16x16x32_bf16 v[116:119], v[100:103], v[190:193], v[116:119]
	v_mfma_f32_16x16x32_bf16 v[92:95], v[96:99], v[194:197], v[92:95]
	v_mfma_f32_16x16x32_bf16 v[92:95], v[100:103], v[198:201], v[92:95]
	v_mfma_f32_16x16x32_bf16 v[76:79], v[96:99], v[202:205], v[76:79]
	v_mfma_f32_16x16x32_bf16 v[76:79], v[100:103], v[218:221], v[76:79]
	v_mfma_f32_16x16x32_bf16 v[136:139], v[120:123], v[178:181], v[136:139]
	v_mfma_f32_16x16x32_bf16 v[136:139], v[124:127], v[182:185], v[136:139]
	v_mfma_f32_16x16x32_bf16 v[112:115], v[120:123], v[186:189], v[112:115]
	v_mfma_f32_16x16x32_bf16 v[112:115], v[124:127], v[190:193], v[112:115]
	v_mfma_f32_16x16x32_bf16 v[88:91], v[120:123], v[194:197], v[88:91]
	v_mfma_f32_16x16x32_bf16 v[88:91], v[124:127], v[198:201], v[88:91]
	v_mfma_f32_16x16x32_bf16 v[72:75], v[120:123], v[202:205], v[72:75]
	v_mfma_f32_16x16x32_bf16 v[72:75], v[124:127], v[218:221], v[72:75]
	v_mfma_f32_16x16x32_bf16 v[132:135], v[144:147], v[178:181], v[132:135]
	v_mfma_f32_16x16x32_bf16 v[132:135], v[148:151], v[182:185], v[132:135]
	v_mfma_f32_16x16x32_bf16 v[108:111], v[144:147], v[186:189], v[108:111]
	v_mfma_f32_16x16x32_bf16 v[108:111], v[148:151], v[190:193], v[108:111]
	v_mfma_f32_16x16x32_bf16 v[84:87], v[144:147], v[194:197], v[84:87]
	v_mfma_f32_16x16x32_bf16 v[84:87], v[148:151], v[198:201], v[84:87]
	v_mfma_f32_16x16x32_bf16 v[68:71], v[144:147], v[202:205], v[68:71]
	v_mfma_f32_16x16x32_bf16 v[68:71], v[148:151], v[218:221], v[68:71]
	v_mfma_f32_16x16x32_bf16 v[128:131], v[152:155], v[178:181], v[128:131]
	v_mfma_f32_16x16x32_bf16 v[128:131], v[156:159], v[182:185], v[128:131]
	v_mfma_f32_16x16x32_bf16 v[104:107], v[152:155], v[186:189], v[104:107]
	v_mfma_f32_16x16x32_bf16 v[104:107], v[156:159], v[190:193], v[104:107]
	s_setprio 2
	s_barrier
	v_mfma_f32_16x16x32_bf16 v[80:83], v[152:155], v[194:197], v[80:83]
	v_mfma_f32_16x16x32_bf16 v[80:83], v[156:159], v[198:201], v[80:83]
	v_mfma_f32_16x16x32_bf16 v[64:67], v[152:155], v[202:205], v[64:67]
	v_mfma_f32_16x16x32_bf16 v[64:67], v[156:159], v[218:221], v[64:67]
	s_setprio 0
	s_add_i32 s50, s79, s61
	v_lshl_add_u64 v[206:207], v[206:207], 0, s[36:37]
	s_mov_b32 m0, s50
	ds_read_b128 v[178:181], v211 offset:49152
	ds_read_b128 v[182:185], v211 offset:50176
	ds_read_b128 v[186:189], v211 offset:51200
	ds_read_b128 v[190:193], v211 offset:52224
	ds_read_b128 v[194:197], v211 offset:53248
	ds_read_b128 v[198:201], v211 offset:54272
	ds_read_b128 v[202:205], v211 offset:55296
	ds_read_b128 v[218:221], v211 offset:56320
	global_load_lds_dwordx4 v[206:207], off
	s_add_i32 m0, s50, 0x2000
	s_add_u32 s8, s8, 0x40080
	v_lshl_add_u64 v[206:207], v[222:223], 0, s[36:37]
	s_addc_u32 s9, s9, 0
	s_add_i32 s50, s80, s61
	global_load_lds_dwordx4 v[206:207], off
	s_mov_b32 m0, s50
	v_lshl_add_u64 v[206:207], s[8:9], 0, v[162:163]
	global_load_lds_dwordx4 v[206:207], off
	s_add_i32 m0, s50, 0x2000
	v_lshl_add_u64 v[206:207], s[8:9], 0, v[166:167]
	global_load_lds_dwordx4 v[206:207], off
	s_mov_b32 m0, s68
	v_lshl_add_u64 v[206:207], v[224:225], 0, s[36:37]
	global_load_lds_dwordx4 v[206:207], off
	s_mov_b32 m0, s69
	v_lshl_add_u64 v[206:207], v[226:227], 0, s[36:37]
	global_load_lds_dwordx4 v[206:207], off
	s_waitcnt vmcnt(8) lgkmcnt(0)
	s_barrier
	s_setprio 1
	v_mfma_f32_16x16x32_bf16 v[60:63], v[96:99], v[178:181], v[60:63]
	v_mfma_f32_16x16x32_bf16 v[60:63], v[100:103], v[182:185], v[60:63]
	v_mfma_f32_16x16x32_bf16 v[44:47], v[96:99], v[186:189], v[44:47]
	v_mfma_f32_16x16x32_bf16 v[44:47], v[100:103], v[190:193], v[44:47]
	v_mfma_f32_16x16x32_bf16 v[28:31], v[96:99], v[194:197], v[28:31]
	v_mfma_f32_16x16x32_bf16 v[28:31], v[100:103], v[198:201], v[28:31]
	v_mfma_f32_16x16x32_bf16 v[12:15], v[96:99], v[202:205], v[12:15]
	v_mfma_f32_16x16x32_bf16 v[12:15], v[100:103], v[218:221], v[12:15]
	v_mfma_f32_16x16x32_bf16 v[56:59], v[120:123], v[178:181], v[56:59]
	v_mfma_f32_16x16x32_bf16 v[56:59], v[124:127], v[182:185], v[56:59]
	v_mfma_f32_16x16x32_bf16 v[40:43], v[120:123], v[186:189], v[40:43]
	v_mfma_f32_16x16x32_bf16 v[40:43], v[124:127], v[190:193], v[40:43]
	v_mfma_f32_16x16x32_bf16 v[24:27], v[120:123], v[194:197], v[24:27]
	v_mfma_f32_16x16x32_bf16 v[24:27], v[124:127], v[198:201], v[24:27]
	v_mfma_f32_16x16x32_bf16 v[8:11], v[120:123], v[202:205], v[8:11]
	v_mfma_f32_16x16x32_bf16 v[8:11], v[124:127], v[218:221], v[8:11]
	v_mfma_f32_16x16x32_bf16 v[52:55], v[144:147], v[178:181], v[52:55]
	v_mfma_f32_16x16x32_bf16 v[52:55], v[148:151], v[182:185], v[52:55]
	v_mfma_f32_16x16x32_bf16 v[36:39], v[144:147], v[186:189], v[36:39]
	v_mfma_f32_16x16x32_bf16 v[36:39], v[148:151], v[190:193], v[36:39]
	v_mfma_f32_16x16x32_bf16 v[20:23], v[144:147], v[194:197], v[20:23]
	v_mfma_f32_16x16x32_bf16 v[20:23], v[148:151], v[198:201], v[20:23]
	v_mfma_f32_16x16x32_bf16 v[4:7], v[144:147], v[202:205], v[4:7]
	v_mfma_f32_16x16x32_bf16 v[4:7], v[148:151], v[218:221], v[4:7]
	v_mfma_f32_16x16x32_bf16 v[48:51], v[152:155], v[178:181], v[48:51]
	v_mfma_f32_16x16x32_bf16 v[48:51], v[156:159], v[182:185], v[48:51]
	v_mfma_f32_16x16x32_bf16 v[32:35], v[152:155], v[186:189], v[32:35]
	v_mfma_f32_16x16x32_bf16 v[32:35], v[156:159], v[190:193], v[32:35]
	s_setprio 2
	s_barrier
	v_mfma_f32_16x16x32_bf16 v[16:19], v[152:155], v[194:197], v[16:19]
	v_mfma_f32_16x16x32_bf16 v[16:19], v[156:159], v[198:201], v[16:19]
	v_mfma_f32_16x16x32_bf16 v[0:3], v[152:155], v[202:205], v[0:3]
	v_mfma_f32_16x16x32_bf16 v[0:3], v[156:159], v[218:221], v[0:3]
	s_setprio 0
	s_add_i32 s78, s78, 2
	s_add_u32 s6, s6, 0x100
	s_addc_u32 s7, s7, 0
	s_add_u32 s56, s56, 0x100
	s_addc_u32 s57, s57, 0
	s_cmp_gt_u32 s78, 13
.LBB0_323:
	ds_read_b128 v[96:99], v209
	ds_read_b128 v[100:103], v209 offset:1024
	ds_read_b128 v[120:123], v209 offset:2048
	ds_read_b128 v[124:127], v209 offset:3072
	ds_read_b128 v[144:147], v210
	ds_read_b128 v[148:151], v210 offset:1024
	ds_read_b128 v[152:155], v210 offset:2048
	ds_read_b128 v[156:159], v210 offset:3072
	s_add_u32 s8, s6, 0xfffc0080
	s_addc_u32 s9, s7, -1
	s_cmp_eq_u32 s78, 12
	s_cselect_b32 s51, s18, s9
	s_cselect_b32 s50, s43, s8
	s_cselect_b32 s9, s45, s57
	s_cselect_b32 s8, s55, s56
	v_lshl_add_u64 v[206:207], s[6:7], 0, v[170:171]
	s_add_i32 m0, s17, 0xc000
	ds_read_b128 v[178:181], v211
	ds_read_b128 v[182:185], v211 offset:1024
	ds_read_b128 v[186:189], v211 offset:2048
	ds_read_b128 v[190:193], v211 offset:3072
	ds_read_b128 v[194:197], v211 offset:4096
	ds_read_b128 v[198:201], v211 offset:5120
	ds_read_b128 v[202:205], v211 offset:6144
	ds_read_b128 v[218:221], v211 offset:7168
	global_load_lds_dwordx4 v[206:207], off
	s_add_i32 m0, s17, 0xe000
	v_lshl_add_u64 v[206:207], s[6:7], 0, v[172:173]
	global_load_lds_dwordx4 v[206:207], off
	s_waitcnt vmcnt(8) lgkmcnt(0)
	s_barrier
	s_setprio 1
	v_mfma_f32_16x16x32_bf16 v[140:143], v[96:99], v[178:181], v[140:143]
	v_mfma_f32_16x16x32_bf16 v[140:143], v[100:103], v[182:185], v[140:143]
	v_mfma_f32_16x16x32_bf16 v[116:119], v[96:99], v[186:189], v[116:119]
	v_mfma_f32_16x16x32_bf16 v[116:119], v[100:103], v[190:193], v[116:119]
	v_mfma_f32_16x16x32_bf16 v[92:95], v[96:99], v[194:197], v[92:95]
	v_mfma_f32_16x16x32_bf16 v[92:95], v[100:103], v[198:201], v[92:95]
	v_mfma_f32_16x16x32_bf16 v[76:79], v[96:99], v[202:205], v[76:79]
	v_mfma_f32_16x16x32_bf16 v[76:79], v[100:103], v[218:221], v[76:79]
	v_mfma_f32_16x16x32_bf16 v[136:139], v[120:123], v[178:181], v[136:139]
	v_mfma_f32_16x16x32_bf16 v[136:139], v[124:127], v[182:185], v[136:139]
	v_mfma_f32_16x16x32_bf16 v[112:115], v[120:123], v[186:189], v[112:115]
	v_mfma_f32_16x16x32_bf16 v[112:115], v[124:127], v[190:193], v[112:115]
	v_mfma_f32_16x16x32_bf16 v[88:91], v[120:123], v[194:197], v[88:91]
	v_mfma_f32_16x16x32_bf16 v[88:91], v[124:127], v[198:201], v[88:91]
	v_mfma_f32_16x16x32_bf16 v[72:75], v[120:123], v[202:205], v[72:75]
	v_mfma_f32_16x16x32_bf16 v[72:75], v[124:127], v[218:221], v[72:75]
	v_mfma_f32_16x16x32_bf16 v[132:135], v[144:147], v[178:181], v[132:135]
	v_mfma_f32_16x16x32_bf16 v[132:135], v[148:151], v[182:185], v[132:135]
	v_mfma_f32_16x16x32_bf16 v[108:111], v[144:147], v[186:189], v[108:111]
	v_mfma_f32_16x16x32_bf16 v[108:111], v[148:151], v[190:193], v[108:111]
	v_mfma_f32_16x16x32_bf16 v[84:87], v[144:147], v[194:197], v[84:87]
	v_mfma_f32_16x16x32_bf16 v[84:87], v[148:151], v[198:201], v[84:87]
	v_mfma_f32_16x16x32_bf16 v[68:71], v[144:147], v[202:205], v[68:71]
	v_mfma_f32_16x16x32_bf16 v[68:71], v[148:151], v[218:221], v[68:71]
	v_mfma_f32_16x16x32_bf16 v[128:131], v[152:155], v[178:181], v[128:131]
	v_mfma_f32_16x16x32_bf16 v[128:131], v[156:159], v[182:185], v[128:131]
	v_mfma_f32_16x16x32_bf16 v[104:107], v[152:155], v[186:189], v[104:107]
	v_mfma_f32_16x16x32_bf16 v[104:107], v[156:159], v[190:193], v[104:107]
	s_setprio 2
	s_barrier
	v_mfma_f32_16x16x32_bf16 v[80:83], v[152:155], v[194:197], v[80:83]
	v_mfma_f32_16x16x32_bf16 v[80:83], v[156:159], v[198:201], v[80:83]
	v_mfma_f32_16x16x32_bf16 v[64:67], v[152:155], v[202:205], v[64:67]
	v_mfma_f32_16x16x32_bf16 v[64:67], v[156:159], v[218:221], v[64:67]
	s_setprio 0
	s_add_i32 s79, s73, s61
	v_lshl_add_u64 v[206:207], s[8:9], 0, v[162:163]
	s_mov_b32 m0, s79
	ds_read_b128 v[178:181], v211 offset:16384
	ds_read_b128 v[182:185], v211 offset:17408
	ds_read_b128 v[186:189], v211 offset:18432
	ds_read_b128 v[190:193], v211 offset:19456
	ds_read_b128 v[194:197], v211 offset:20480
	ds_read_b128 v[198:201], v211 offset:21504
	ds_read_b128 v[202:205], v211 offset:22528
	ds_read_b128 v[218:221], v211 offset:23552
	global_load_lds_dwordx4 v[206:207], off
	s_add_i32 m0, s79, 0x2000
	s_add_u32 s80, s8, 0x40000
	v_lshl_add_u64 v[222:223], s[8:9], 0, v[166:167]
	s_addc_u32 s81, s9, 0
	s_add_i32 s79, s74, s61
	global_load_lds_dwordx4 v[222:223], off
	v_lshl_add_u64 v[224:225], s[80:81], 0, v[162:163]
	s_mov_b32 m0, s79
	v_lshl_add_u64 v[226:227], s[50:51], 0, v[164:165]
	global_load_lds_dwordx4 v[224:225], off
	s_add_i32 m0, s79, 0x2000
	v_lshl_add_u64 v[224:225], s[80:81], 0, v[166:167]
	global_load_lds_dwordx4 v[224:225], off
	s_mov_b32 m0, s17
	v_lshl_add_u64 v[224:225], s[50:51], 0, v[160:161]
	global_load_lds_dwordx4 v[224:225], off
	s_mov_b32 m0, s62
	s_nop 0
	global_load_lds_dwordx4 v[226:227], off
	s_waitcnt vmcnt(8) lgkmcnt(0)
	s_barrier
	s_setprio 1
	v_mfma_f32_16x16x32_bf16 v[60:63], v[96:99], v[178:181], v[60:63]
	v_mfma_f32_16x16x32_bf16 v[60:63], v[100:103], v[182:185], v[60:63]
	v_mfma_f32_16x16x32_bf16 v[44:47], v[96:99], v[186:189], v[44:47]
	v_mfma_f32_16x16x32_bf16 v[44:47], v[100:103], v[190:193], v[44:47]
	v_mfma_f32_16x16x32_bf16 v[28:31], v[96:99], v[194:197], v[28:31]
	v_mfma_f32_16x16x32_bf16 v[28:31], v[100:103], v[198:201], v[28:31]
	v_mfma_f32_16x16x32_bf16 v[12:15], v[96:99], v[202:205], v[12:15]
	v_mfma_f32_16x16x32_bf16 v[12:15], v[100:103], v[218:221], v[12:15]
	v_mfma_f32_16x16x32_bf16 v[56:59], v[120:123], v[178:181], v[56:59]
	v_mfma_f32_16x16x32_bf16 v[56:59], v[124:127], v[182:185], v[56:59]
	v_mfma_f32_16x16x32_bf16 v[40:43], v[120:123], v[186:189], v[40:43]
	v_mfma_f32_16x16x32_bf16 v[40:43], v[124:127], v[190:193], v[40:43]
	v_mfma_f32_16x16x32_bf16 v[24:27], v[120:123], v[194:197], v[24:27]
	v_mfma_f32_16x16x32_bf16 v[24:27], v[124:127], v[198:201], v[24:27]
	v_mfma_f32_16x16x32_bf16 v[8:11], v[120:123], v[202:205], v[8:11]
	v_mfma_f32_16x16x32_bf16 v[8:11], v[124:127], v[218:221], v[8:11]
	v_mfma_f32_16x16x32_bf16 v[52:55], v[144:147], v[178:181], v[52:55]
	v_mfma_f32_16x16x32_bf16 v[52:55], v[148:151], v[182:185], v[52:55]
	v_mfma_f32_16x16x32_bf16 v[36:39], v[144:147], v[186:189], v[36:39]
	v_mfma_f32_16x16x32_bf16 v[36:39], v[148:151], v[190:193], v[36:39]
	v_mfma_f32_16x16x32_bf16 v[20:23], v[144:147], v[194:197], v[20:23]
	v_mfma_f32_16x16x32_bf16 v[20:23], v[148:151], v[198:201], v[20:23]
	v_mfma_f32_16x16x32_bf16 v[4:7], v[144:147], v[202:205], v[4:7]
	v_mfma_f32_16x16x32_bf16 v[4:7], v[148:151], v[218:221], v[4:7]
	v_mfma_f32_16x16x32_bf16 v[48:51], v[152:155], v[178:181], v[48:51]
	v_mfma_f32_16x16x32_bf16 v[48:51], v[156:159], v[182:185], v[48:51]
	v_mfma_f32_16x16x32_bf16 v[32:35], v[152:155], v[186:189], v[32:35]
	v_mfma_f32_16x16x32_bf16 v[32:35], v[156:159], v[190:193], v[32:35]
	s_setprio 2
	s_barrier
	v_mfma_f32_16x16x32_bf16 v[16:19], v[152:155], v[194:197], v[16:19]
	v_mfma_f32_16x16x32_bf16 v[16:19], v[156:159], v[198:201], v[16:19]
	v_mfma_f32_16x16x32_bf16 v[0:3], v[152:155], v[202:205], v[0:3]
	v_mfma_f32_16x16x32_bf16 v[0:3], v[156:159], v[218:221], v[0:3]
	s_setprio 0
	s_add_i32 s79, 0, 0x18000
	s_add_i32 s80, 0, 0x1c000
	v_add_u32_e32 v124, s79, v208
	v_add_u32_e32 v156, s80, v208
	ds_read_b128 v[96:99], v124
	ds_read_b128 v[100:103], v124 offset:1024
	ds_read_b128 v[120:123], v124 offset:2048
	ds_read_b128 v[124:127], v124 offset:3072
	ds_read_b128 v[144:147], v156
	ds_read_b128 v[148:151], v156 offset:1024
	ds_read_b128 v[152:155], v156 offset:2048
	ds_read_b128 v[156:159], v156 offset:3072
	s_add_u32 s50, s50, 0x40000
	s_addc_u32 s51, s51, 0
	s_mov_b32 m0, s63
	v_lshl_add_u64 v[228:229], s[50:51], 0, v[160:161]
	ds_read_b128 v[178:181], v211 offset:32768
	ds_read_b128 v[182:185], v211 offset:33792
	ds_read_b128 v[186:189], v211 offset:34816
	ds_read_b128 v[190:193], v211 offset:35840
	ds_read_b128 v[194:197], v211 offset:36864
	ds_read_b128 v[198:201], v211 offset:37888
	ds_read_b128 v[202:205], v211 offset:38912
	ds_read_b128 v[218:221], v211 offset:39936
	global_load_lds_dwordx4 v[228:229], off
	s_mov_b32 m0, s64
	v_lshl_add_u64 v[228:229], s[50:51], 0, v[164:165]
	global_load_lds_dwordx4 v[228:229], off
	s_waitcnt vmcnt(8) lgkmcnt(0)
	s_barrier
	s_setprio 1
	v_mfma_f32_16x16x32_bf16 v[140:143], v[96:99], v[178:181], v[140:143]
	v_mfma_f32_16x16x32_bf16 v[140:143], v[100:103], v[182:185], v[140:143]
	v_mfma_f32_16x16x32_bf16 v[116:119], v[96:99], v[186:189], v[116:119]
	v_mfma_f32_16x16x32_bf16 v[116:119], v[100:103], v[190:193], v[116:119]
	v_mfma_f32_16x16x32_bf16 v[92:95], v[96:99], v[194:197], v[92:95]
	v_mfma_f32_16x16x32_bf16 v[92:95], v[100:103], v[198:201], v[92:95]
	v_mfma_f32_16x16x32_bf16 v[76:79], v[96:99], v[202:205], v[76:79]
	v_mfma_f32_16x16x32_bf16 v[76:79], v[100:103], v[218:221], v[76:79]
	v_mfma_f32_16x16x32_bf16 v[136:139], v[120:123], v[178:181], v[136:139]
	v_mfma_f32_16x16x32_bf16 v[136:139], v[124:127], v[182:185], v[136:139]
	v_mfma_f32_16x16x32_bf16 v[112:115], v[120:123], v[186:189], v[112:115]
	v_mfma_f32_16x16x32_bf16 v[112:115], v[124:127], v[190:193], v[112:115]
	v_mfma_f32_16x16x32_bf16 v[88:91], v[120:123], v[194:197], v[88:91]
	v_mfma_f32_16x16x32_bf16 v[88:91], v[124:127], v[198:201], v[88:91]
	v_mfma_f32_16x16x32_bf16 v[72:75], v[120:123], v[202:205], v[72:75]
	v_mfma_f32_16x16x32_bf16 v[72:75], v[124:127], v[218:221], v[72:75]
	v_mfma_f32_16x16x32_bf16 v[132:135], v[144:147], v[178:181], v[132:135]
	v_mfma_f32_16x16x32_bf16 v[132:135], v[148:151], v[182:185], v[132:135]
	v_mfma_f32_16x16x32_bf16 v[108:111], v[144:147], v[186:189], v[108:111]
	v_mfma_f32_16x16x32_bf16 v[108:111], v[148:151], v[190:193], v[108:111]
	v_mfma_f32_16x16x32_bf16 v[84:87], v[144:147], v[194:197], v[84:87]
	v_mfma_f32_16x16x32_bf16 v[84:87], v[148:151], v[198:201], v[84:87]
	v_mfma_f32_16x16x32_bf16 v[68:71], v[144:147], v[202:205], v[68:71]
	v_mfma_f32_16x16x32_bf16 v[68:71], v[148:151], v[218:221], v[68:71]
	v_mfma_f32_16x16x32_bf16 v[128:131], v[152:155], v[178:181], v[128:131]
	v_mfma_f32_16x16x32_bf16 v[128:131], v[156:159], v[182:185], v[128:131]
	v_mfma_f32_16x16x32_bf16 v[104:107], v[152:155], v[186:189], v[104:107]
	v_mfma_f32_16x16x32_bf16 v[104:107], v[156:159], v[190:193], v[104:107]
	s_setprio 2
	s_barrier
	v_mfma_f32_16x16x32_bf16 v[80:83], v[152:155], v[194:197], v[80:83]
	v_mfma_f32_16x16x32_bf16 v[80:83], v[156:159], v[198:201], v[80:83]
	v_mfma_f32_16x16x32_bf16 v[64:67], v[152:155], v[202:205], v[64:67]
	v_mfma_f32_16x16x32_bf16 v[64:67], v[156:159], v[218:221], v[64:67]
	s_setprio 0
	s_add_i32 s50, s79, s61
	v_lshl_add_u64 v[206:207], v[206:207], 0, s[36:37]
	s_mov_b32 m0, s50
	ds_read_b128 v[178:181], v211 offset:49152
	ds_read_b128 v[182:185], v211 offset:50176
	ds_read_b128 v[186:189], v211 offset:51200
	ds_read_b128 v[190:193], v211 offset:52224
	ds_read_b128 v[194:197], v211 offset:53248
	ds_read_b128 v[198:201], v211 offset:54272
	ds_read_b128 v[202:205], v211 offset:55296
	ds_read_b128 v[218:221], v211 offset:56320
	global_load_lds_dwordx4 v[206:207], off
	s_add_i32 m0, s50, 0x2000
	s_add_u32 s8, s8, 0x40080
	v_lshl_add_u64 v[206:207], v[222:223], 0, s[36:37]
	s_addc_u32 s9, s9, 0
	s_add_i32 s50, s80, s61
	global_load_lds_dwordx4 v[206:207], off
	s_mov_b32 m0, s50
	v_lshl_add_u64 v[206:207], s[8:9], 0, v[162:163]
	global_load_lds_dwordx4 v[206:207], off
	s_add_i32 m0, s50, 0x2000
	v_lshl_add_u64 v[206:207], s[8:9], 0, v[166:167]
	global_load_lds_dwordx4 v[206:207], off
	s_mov_b32 m0, s68
	v_lshl_add_u64 v[206:207], v[224:225], 0, s[36:37]
	global_load_lds_dwordx4 v[206:207], off
	s_mov_b32 m0, s69
	v_lshl_add_u64 v[206:207], v[226:227], 0, s[36:37]
	global_load_lds_dwordx4 v[206:207], off
	s_waitcnt vmcnt(8) lgkmcnt(0)
	s_barrier
	s_setprio 1
	v_mfma_f32_16x16x32_bf16 v[60:63], v[96:99], v[178:181], v[60:63]
	v_mfma_f32_16x16x32_bf16 v[60:63], v[100:103], v[182:185], v[60:63]
	v_mfma_f32_16x16x32_bf16 v[44:47], v[96:99], v[186:189], v[44:47]
	v_mfma_f32_16x16x32_bf16 v[44:47], v[100:103], v[190:193], v[44:47]
	v_mfma_f32_16x16x32_bf16 v[28:31], v[96:99], v[194:197], v[28:31]
	v_mfma_f32_16x16x32_bf16 v[28:31], v[100:103], v[198:201], v[28:31]
	v_mfma_f32_16x16x32_bf16 v[12:15], v[96:99], v[202:205], v[12:15]
	v_mfma_f32_16x16x32_bf16 v[12:15], v[100:103], v[218:221], v[12:15]
	v_mfma_f32_16x16x32_bf16 v[56:59], v[120:123], v[178:181], v[56:59]
	v_mfma_f32_16x16x32_bf16 v[56:59], v[124:127], v[182:185], v[56:59]
	v_mfma_f32_16x16x32_bf16 v[40:43], v[120:123], v[186:189], v[40:43]
	v_mfma_f32_16x16x32_bf16 v[40:43], v[124:127], v[190:193], v[40:43]
	v_mfma_f32_16x16x32_bf16 v[24:27], v[120:123], v[194:197], v[24:27]
	v_mfma_f32_16x16x32_bf16 v[24:27], v[124:127], v[198:201], v[24:27]
	v_mfma_f32_16x16x32_bf16 v[8:11], v[120:123], v[202:205], v[8:11]
	v_mfma_f32_16x16x32_bf16 v[8:11], v[124:127], v[218:221], v[8:11]
	v_mfma_f32_16x16x32_bf16 v[52:55], v[144:147], v[178:181], v[52:55]
	v_mfma_f32_16x16x32_bf16 v[52:55], v[148:151], v[182:185], v[52:55]
	v_mfma_f32_16x16x32_bf16 v[36:39], v[144:147], v[186:189], v[36:39]
	v_mfma_f32_16x16x32_bf16 v[36:39], v[148:151], v[190:193], v[36:39]
	v_mfma_f32_16x16x32_bf16 v[20:23], v[144:147], v[194:197], v[20:23]
	v_mfma_f32_16x16x32_bf16 v[20:23], v[148:151], v[198:201], v[20:23]
	v_mfma_f32_16x16x32_bf16 v[4:7], v[144:147], v[202:205], v[4:7]
	v_mfma_f32_16x16x32_bf16 v[4:7], v[148:151], v[218:221], v[4:7]
	v_mfma_f32_16x16x32_bf16 v[48:51], v[152:155], v[178:181], v[48:51]
	v_mfma_f32_16x16x32_bf16 v[48:51], v[156:159], v[182:185], v[48:51]
	v_mfma_f32_16x16x32_bf16 v[32:35], v[152:155], v[186:189], v[32:35]
	v_mfma_f32_16x16x32_bf16 v[32:35], v[156:159], v[190:193], v[32:35]
	s_setprio 2
	s_barrier
	v_mfma_f32_16x16x32_bf16 v[16:19], v[152:155], v[194:197], v[16:19]
	v_mfma_f32_16x16x32_bf16 v[16:19], v[156:159], v[198:201], v[16:19]
	v_mfma_f32_16x16x32_bf16 v[0:3], v[152:155], v[202:205], v[0:3]
	v_mfma_f32_16x16x32_bf16 v[0:3], v[156:159], v[218:221], v[0:3]
	s_setprio 0
	s_add_i32 s78, s78, 2
	s_add_u32 s6, s6, 0x100
	s_addc_u32 s7, s7, 0
	s_add_u32 s56, s56, 0x100
	s_addc_u32 s57, s57, 0
	s_cmp_gt_u32 s78, 13
	s_cbranch_scc0 .LBB0_323

.LBB0_697:
	s_and_b32 s29, s69, 0x1000
	s_add_i32 s70, s66, s29
	s_ashr_i32 s29, s28, 31
	ds_read_b128 v[0:3], v195 offset:3072
	ds_read_b128 v[4:7], v195 offset:2048
	ds_read_b128 v[8:11], v195 offset:1024
	ds_read_b128 v[12:15], v195
	ds_read_b128 v[16:19], v203 offset:3072
	ds_read_b128 v[20:23], v203 offset:2048
	ds_read_b128 v[24:27], v203 offset:1024
	ds_read_b128 v[28:31], v203
	s_lshl_b64 s[36:37], s[28:29], 20
	s_add_u32 s36, s50, s36
	s_addc_u32 s37, s51, s37
	s_and_b64 s[38:39], s[4:5], exec
	s_cselect_b32 s29, s37, s45
	s_cselect_b32 s71, s36, s44
	s_ashr_i32 s31, s30, 31
	s_lshl_b64 s[38:39], s[30:31], 20
	s_add_u32 s38, s54, s38
	s_addc_u32 s39, s55, s39
	s_and_b64 s[48:49], s[4:5], exec
	s_cselect_b32 s31, s39, s47
	s_cselect_b32 s72, s38, s46
	s_add_u32 s48, s44, 0x80080
	s_addc_u32 s49, s45, 0
	s_add_i32 s73, s56, 0xc000
	v_lshl_add_u64 v[64:65], s[48:49], 0, v[176:177]
	s_mov_b32 m0, s73
	s_add_i32 s74, s56, 0xe000
	ds_read_b128 v[32:35], v211
	ds_read_b128 v[36:39], v211 offset:1024
	ds_read_b128 v[40:43], v211 offset:2048
	ds_read_b128 v[44:47], v211 offset:3072
	ds_read_b128 v[48:51], v211 offset:4096
	ds_read_b128 v[52:55], v211 offset:5120
	ds_read_b128 v[56:59], v211 offset:6144
	ds_read_b128 v[60:63], v211 offset:7168
	global_load_lds_dwordx4 v[64:65], off
	s_mov_b32 m0, s74
	v_lshl_add_u64 v[64:65], s[48:49], 0, v[178:179]
	global_load_lds_dwordx4 v[64:65], off
	s_waitcnt vmcnt(8) lgkmcnt(0)
	s_barrier
	s_setprio 1
	v_mfma_f32_16x16x32_bf16 v[88:91], v[28:31], v[56:59], 0
	v_mfma_f32_16x16x32_bf16 v[64:67], v[28:31], v[32:35], 0
	v_mfma_f32_16x16x32_bf16 v[68:71], v[20:23], v[32:35], 0
	v_mfma_f32_16x16x32_bf16 v[72:75], v[28:31], v[40:43], 0
	v_mfma_f32_16x16x32_bf16 v[76:79], v[20:23], v[40:43], 0
	v_mfma_f32_16x16x32_bf16 v[80:83], v[28:31], v[48:51], 0
	v_mfma_f32_16x16x32_bf16 v[84:87], v[20:23], v[48:51], 0
	v_mfma_f32_16x16x32_bf16 v[96:99], v[24:27], v[60:63], v[88:91]
	v_mfma_f32_16x16x32_bf16 v[88:91], v[20:23], v[56:59], 0
	v_mfma_f32_16x16x32_bf16 v[64:67], v[24:27], v[36:39], v[64:67]
	v_mfma_f32_16x16x32_bf16 v[68:71], v[16:19], v[36:39], v[68:71]
	v_mfma_f32_16x16x32_bf16 v[72:75], v[24:27], v[44:47], v[72:75]
	v_mfma_f32_16x16x32_bf16 v[76:79], v[16:19], v[44:47], v[76:79]
	v_mfma_f32_16x16x32_bf16 v[80:83], v[24:27], v[52:55], v[80:83]
	v_mfma_f32_16x16x32_bf16 v[84:87], v[16:19], v[52:55], v[84:87]
	v_mfma_f32_16x16x32_bf16 v[100:103], v[16:19], v[60:63], v[88:91]
	v_mfma_f32_16x16x32_bf16 v[88:91], v[12:15], v[32:35], 0
	v_mfma_f32_16x16x32_bf16 v[32:35], v[4:7], v[32:35], 0
	v_mfma_f32_16x16x32_bf16 v[112:115], v[8:11], v[36:39], v[88:91]
	v_mfma_f32_16x16x32_bf16 v[32:35], v[0:3], v[36:39], v[32:35]
	v_mfma_f32_16x16x32_bf16 v[36:39], v[12:15], v[40:43], 0
	v_mfma_f32_16x16x32_bf16 v[40:43], v[4:7], v[40:43], 0
	v_mfma_f32_16x16x32_bf16 v[36:39], v[8:11], v[44:47], v[36:39]
	v_mfma_f32_16x16x32_bf16 v[40:43], v[0:3], v[44:47], v[40:43]
	v_mfma_f32_16x16x32_bf16 v[44:47], v[12:15], v[48:51], 0
	v_mfma_f32_16x16x32_bf16 v[48:51], v[4:7], v[48:51], 0
	v_mfma_f32_16x16x32_bf16 v[44:47], v[8:11], v[52:55], v[44:47]
	v_mfma_f32_16x16x32_bf16 v[48:51], v[0:3], v[52:55], v[48:51]
	s_setprio 2
	s_barrier
	v_mfma_f32_16x16x32_bf16 v[52:55], v[12:15], v[56:59], 0
	v_mfma_f32_16x16x32_bf16 v[56:59], v[4:7], v[56:59], 0
	v_mfma_f32_16x16x32_bf16 v[52:55], v[8:11], v[60:63], v[52:55]
	v_mfma_f32_16x16x32_bf16 v[56:59], v[0:3], v[60:63], v[56:59]
	s_setprio 0
	s_add_i32 s75, s68, s43
	v_lshl_add_u64 v[174:175], s[46:47], 0, v[176:177]
	s_add_i32 s76, s75, 0x2000
	v_lshl_add_u64 v[128:129], v[174:175], 0, s[24:25]
	s_mov_b32 m0, s75
	v_lshl_add_u64 v[200:201], s[46:47], 0, v[178:179]
	s_add_u32 s48, s46, 0x80100
	ds_read_b128 v[60:63], v211 offset:16384
	ds_read_b128 v[88:91], v211 offset:17408
	ds_read_b128 v[92:95], v211 offset:18432
	ds_read_b128 v[104:107], v211 offset:19456
	ds_read_b128 v[108:111], v211 offset:20480
	ds_read_b128 v[116:119], v211 offset:21504
	ds_read_b128 v[120:123], v211 offset:22528
	ds_read_b128 v[124:127], v211 offset:23552
	global_load_lds_dwordx4 v[128:129], off
	v_lshl_add_u64 v[128:129], v[200:201], 0, s[24:25]
	s_mov_b32 m0, s76
	s_addc_u32 s49, s47, 0
	s_add_i32 s77, s67, s43
	global_load_lds_dwordx4 v[128:129], off
	v_lshl_add_u64 v[128:129], s[48:49], 0, v[176:177]
	s_mov_b32 m0, s77
	s_add_i32 s78, s77, 0x2000
	global_load_lds_dwordx4 v[128:129], off
	v_lshl_add_u64 v[128:129], s[48:49], 0, v[178:179]
	s_mov_b32 m0, s78
	v_lshl_add_u64 v[208:209], s[44:45], 0, v[176:177]
	global_load_lds_dwordx4 v[128:129], off
	v_lshl_add_u64 v[128:129], v[208:209], 0, s[24:25]
	s_mov_b32 m0, s56
	v_lshl_add_u64 v[252:253], s[44:45], 0, v[178:179]
	global_load_lds_dwordx4 v[128:129], off
	s_mov_b32 m0, s57
	v_lshl_add_u64 v[128:129], v[252:253], 0, s[24:25]
	global_load_lds_dwordx4 v[128:129], off
	s_waitcnt vmcnt(8) lgkmcnt(0)
	s_barrier
	s_setprio 1
	v_mfma_f32_16x16x32_bf16 v[134:137], v[20:23], v[60:63], 0
	v_mfma_f32_16x16x32_bf16 v[142:145], v[20:23], v[92:95], 0
	v_mfma_f32_16x16x32_bf16 v[150:153], v[20:23], v[108:111], 0
	v_mfma_f32_16x16x32_bf16 v[20:23], v[20:23], v[120:123], 0
	v_mfma_f32_16x16x32_bf16 v[128:131], v[28:31], v[60:63], 0
	v_mfma_f32_16x16x32_bf16 v[134:137], v[16:19], v[88:91], v[134:137]
	v_mfma_f32_16x16x32_bf16 v[138:141], v[28:31], v[92:95], 0
	v_mfma_f32_16x16x32_bf16 v[142:145], v[16:19], v[104:107], v[142:145]
	v_mfma_f32_16x16x32_bf16 v[146:149], v[28:31], v[108:111], 0
	v_mfma_f32_16x16x32_bf16 v[150:153], v[16:19], v[116:119], v[150:153]
	v_mfma_f32_16x16x32_bf16 v[28:31], v[28:31], v[120:123], 0
	v_mfma_f32_16x16x32_bf16 v[16:19], v[16:19], v[124:127], v[20:23]
	v_mfma_f32_16x16x32_bf16 v[130:133], v[24:27], v[88:91], v[128:131]
	v_mfma_f32_16x16x32_bf16 v[138:141], v[24:27], v[104:107], v[138:141]
	v_mfma_f32_16x16x32_bf16 v[146:149], v[24:27], v[116:119], v[146:149]
	v_mfma_f32_16x16x32_bf16 v[154:157], v[24:27], v[124:127], v[28:31]
	v_mfma_f32_16x16x32_bf16 v[24:27], v[4:7], v[60:63], 0
	v_mfma_f32_16x16x32_bf16 v[158:161], v[0:3], v[88:91], v[24:27]
	v_mfma_f32_16x16x32_bf16 v[24:27], v[12:15], v[92:95], 0
	v_mfma_f32_16x16x32_bf16 v[162:165], v[8:11], v[104:107], v[24:27]
	v_mfma_f32_16x16x32_bf16 v[24:27], v[4:7], v[92:95], 0
	v_mfma_f32_16x16x32_bf16 v[166:169], v[0:3], v[104:107], v[24:27]
	v_mfma_f32_16x16x32_bf16 v[24:27], v[12:15], v[108:111], 0
	v_mfma_f32_16x16x32_bf16 v[20:23], v[12:15], v[60:63], 0
	v_mfma_f32_16x16x32_bf16 v[170:173], v[8:11], v[116:119], v[24:27]
	v_mfma_f32_16x16x32_bf16 v[24:27], v[4:7], v[108:111], 0
	v_mfma_f32_16x16x32_bf16 v[4:7], v[4:7], v[120:123], 0
	v_mfma_f32_16x16x32_bf16 v[20:23], v[8:11], v[88:91], v[20:23]
	s_setprio 2
	s_barrier
	v_mfma_f32_16x16x32_bf16 v[190:193], v[0:3], v[116:119], v[24:27]
	v_mfma_f32_16x16x32_bf16 v[12:15], v[12:15], v[120:123], 0
	v_mfma_f32_16x16x32_bf16 v[0:3], v[0:3], v[124:127], v[4:7]
	v_mfma_f32_16x16x32_bf16 v[196:199], v[8:11], v[124:127], v[12:15]
	s_setprio 0
	s_add_i32 s79, 0, 0x18000
	s_add_i32 s81, 0, 0x1c000
	v_add_u32_e32 v128, s79, v189
	v_add_u32_e32 v129, s81, v189
	ds_read_b128 v[4:7], v128
	ds_read_b128 v[8:11], v128 offset:1024
	ds_read_b128 v[204:207], v128 offset:2048
	ds_read_b128 v[212:215], v128 offset:3072
	ds_read_b128 v[216:219], v129
	ds_read_b128 v[220:223], v129 offset:1024
	ds_read_b128 v[224:227], v129 offset:2048
	ds_read_b128 v[228:231], v129 offset:3072
	s_add_u32 s48, s44, 0x80100
	s_addc_u32 s49, s45, 0
	s_mov_b32 m0, s58
	v_lshl_add_u64 v[88:89], s[48:49], 0, v[176:177]
	ds_read_b128 v[12:15], v211 offset:32768
	ds_read_b128 v[24:27], v211 offset:33792
	ds_read_b128 v[28:31], v211 offset:34816
	ds_read_b128 v[60:63], v211 offset:35840
	ds_read_b128 v[232:235], v211 offset:36864
	ds_read_b128 v[236:239], v211 offset:37888
	ds_read_b128 v[240:243], v211 offset:38912
	ds_read_b128 v[244:247], v211 offset:39936
	global_load_lds_dwordx4 v[88:89], off
	s_mov_b32 m0, s59
	v_lshl_add_u64 v[88:89], s[48:49], 0, v[178:179]
	global_load_lds_dwordx4 v[88:89], off
	s_waitcnt vmcnt(8) lgkmcnt(0)
	s_barrier
	s_setprio 1
	v_mfma_f32_16x16x32_bf16 v[64:67], v[4:7], v[12:15], v[64:67]
	v_mfma_f32_16x16x32_bf16 v[124:127], v[8:11], v[24:27], v[64:67]
	v_mfma_f32_16x16x32_bf16 v[64:67], v[204:207], v[12:15], v[68:71]
	v_mfma_f32_16x16x32_bf16 v[120:123], v[212:215], v[24:27], v[64:67]
	v_mfma_f32_16x16x32_bf16 v[64:67], v[4:7], v[28:31], v[72:75]
	v_mfma_f32_16x16x32_bf16 v[108:111], v[8:11], v[60:63], v[64:67]
	v_mfma_f32_16x16x32_bf16 v[64:67], v[204:207], v[28:31], v[76:79]
	v_mfma_f32_16x16x32_bf16 v[104:107], v[212:215], v[60:63], v[64:67]
	v_mfma_f32_16x16x32_bf16 v[64:67], v[4:7], v[232:235], v[80:83]
	v_mfma_f32_16x16x32_bf16 v[92:95], v[8:11], v[236:239], v[64:67]
	v_mfma_f32_16x16x32_bf16 v[64:67], v[204:207], v[232:235], v[84:87]
	v_mfma_f32_16x16x32_bf16 v[88:91], v[212:215], v[236:239], v[64:67]
	v_mfma_f32_16x16x32_bf16 v[64:67], v[4:7], v[240:243], v[96:99]
	v_mfma_f32_16x16x32_bf16 v[76:79], v[8:11], v[244:247], v[64:67]
	v_mfma_f32_16x16x32_bf16 v[64:67], v[204:207], v[240:243], v[100:103]
	v_mfma_f32_16x16x32_bf16 v[72:75], v[212:215], v[244:247], v[64:67]
	v_mfma_f32_16x16x32_bf16 v[64:67], v[216:219], v[12:15], v[112:115]
	v_mfma_f32_16x16x32_bf16 v[12:15], v[224:227], v[12:15], v[32:35]
	v_mfma_f32_16x16x32_bf16 v[112:115], v[228:231], v[24:27], v[12:15]
	v_mfma_f32_16x16x32_bf16 v[12:15], v[216:219], v[28:31], v[36:39]
	v_mfma_f32_16x16x32_bf16 v[100:103], v[220:223], v[60:63], v[12:15]
	v_mfma_f32_16x16x32_bf16 v[12:15], v[224:227], v[28:31], v[40:43]
	v_mfma_f32_16x16x32_bf16 v[96:99], v[228:231], v[60:63], v[12:15]
	v_mfma_f32_16x16x32_bf16 v[12:15], v[216:219], v[232:235], v[44:47]
	v_mfma_f32_16x16x32_bf16 v[84:87], v[220:223], v[236:239], v[12:15]
	v_mfma_f32_16x16x32_bf16 v[12:15], v[224:227], v[232:235], v[48:51]
	v_mfma_f32_16x16x32_bf16 v[80:83], v[228:231], v[236:239], v[12:15]
	v_mfma_f32_16x16x32_bf16 v[12:15], v[216:219], v[240:243], v[52:55]
	s_setprio 2
	s_barrier
	v_mfma_f32_16x16x32_bf16 v[68:71], v[220:223], v[244:247], v[12:15]
	v_mfma_f32_16x16x32_bf16 v[12:15], v[224:227], v[240:243], v[56:59]
	v_mfma_f32_16x16x32_bf16 v[116:119], v[220:223], v[24:27], v[64:67]
	v_mfma_f32_16x16x32_bf16 v[64:67], v[228:231], v[244:247], v[12:15]
	s_setprio 0
	s_add_i32 s79, s79, s43
	s_add_i32 s80, s79, 0x2000
	s_nop 1
	v_lshl_add_u64 v[12:13], v[174:175], 0, s[26:27]
	s_mov_b32 m0, s79
	s_add_u32 s48, s46, 0x80180
	ds_read_b128 v[32:35], v211 offset:49152
	ds_read_b128 v[36:39], v211 offset:50176
	ds_read_b128 v[232:235], v211 offset:51200
	ds_read_b128 v[236:239], v211 offset:52224
	ds_read_b128 v[240:243], v211 offset:53248
	ds_read_b128 v[244:247], v211 offset:54272
	ds_read_b128 v[248:251], v211 offset:55296
	ds_read_b128 v[184:187], v211 offset:56320
	global_load_lds_dwordx4 v[12:13], off
	v_lshl_add_u64 v[12:13], v[200:201], 0, s[26:27]
	s_mov_b32 m0, s80
	s_addc_u32 s49, s47, 0
	s_add_i32 s81, s81, s43
	global_load_lds_dwordx4 v[12:13], off
	v_lshl_add_u64 v[12:13], s[48:49], 0, v[176:177]
	s_mov_b32 m0, s81
	s_add_i32 s82, s81, 0x2000
	global_load_lds_dwordx4 v[12:13], off
	s_mov_b32 m0, s82
	v_lshl_add_u64 v[12:13], s[48:49], 0, v[178:179]
	global_load_lds_dwordx4 v[12:13], off
	s_mov_b32 m0, s61
	v_lshl_add_u64 v[12:13], v[208:209], 0, s[26:27]
	global_load_lds_dwordx4 v[12:13], off
	s_mov_b32 m0, s62
	v_lshl_add_u64 v[12:13], v[252:253], 0, s[26:27]
	global_load_lds_dwordx4 v[12:13], off
	s_waitcnt vmcnt(8) lgkmcnt(0)
	s_barrier
	s_setprio 1
	v_mfma_f32_16x16x32_bf16 v[12:15], v[4:7], v[32:35], v[130:133]
	v_mfma_f32_16x16x32_bf16 v[60:63], v[8:11], v[36:39], v[12:15]
	v_mfma_f32_16x16x32_bf16 v[12:15], v[204:207], v[32:35], v[134:137]
	v_mfma_f32_16x16x32_bf16 v[56:59], v[212:215], v[36:39], v[12:15]
	v_mfma_f32_16x16x32_bf16 v[12:15], v[4:7], v[232:235], v[138:141]
	v_mfma_f32_16x16x32_bf16 v[44:47], v[8:11], v[236:239], v[12:15]
	v_mfma_f32_16x16x32_bf16 v[12:15], v[204:207], v[232:235], v[142:145]
	v_mfma_f32_16x16x32_bf16 v[40:43], v[212:215], v[236:239], v[12:15]
	v_mfma_f32_16x16x32_bf16 v[12:15], v[4:7], v[240:243], v[146:149]
	v_mfma_f32_16x16x32_bf16 v[28:31], v[8:11], v[244:247], v[12:15]
	v_mfma_f32_16x16x32_bf16 v[12:15], v[204:207], v[240:243], v[150:153]
	v_mfma_f32_16x16x32_bf16 v[4:7], v[4:7], v[248:251], v[154:157]
	v_mfma_f32_16x16x32_bf16 v[24:27], v[212:215], v[244:247], v[12:15]
	v_mfma_f32_16x16x32_bf16 v[12:15], v[8:11], v[184:187], v[4:7]
	v_mfma_f32_16x16x32_bf16 v[4:7], v[204:207], v[248:251], v[16:19]
	v_mfma_f32_16x16x32_bf16 v[8:11], v[212:215], v[184:187], v[4:7]
	v_mfma_f32_16x16x32_bf16 v[4:7], v[216:219], v[32:35], v[20:23]
	v_mfma_f32_16x16x32_bf16 v[52:55], v[220:223], v[36:39], v[4:7]
	v_mfma_f32_16x16x32_bf16 v[4:7], v[224:227], v[32:35], v[158:161]
	v_mfma_f32_16x16x32_bf16 v[48:51], v[228:231], v[36:39], v[4:7]
	v_mfma_f32_16x16x32_bf16 v[4:7], v[216:219], v[232:235], v[162:165]
	v_mfma_f32_16x16x32_bf16 v[36:39], v[220:223], v[236:239], v[4:7]
	v_mfma_f32_16x16x32_bf16 v[4:7], v[224:227], v[232:235], v[166:169]
	v_mfma_f32_16x16x32_bf16 v[32:35], v[228:231], v[236:239], v[4:7]
	v_mfma_f32_16x16x32_bf16 v[4:7], v[216:219], v[240:243], v[170:173]
	v_mfma_f32_16x16x32_bf16 v[20:23], v[220:223], v[244:247], v[4:7]
	v_mfma_f32_16x16x32_bf16 v[4:7], v[224:227], v[240:243], v[190:193]
	v_mfma_f32_16x16x32_bf16 v[16:19], v[228:231], v[244:247], v[4:7]
	s_setprio 2
	s_barrier
	v_mfma_f32_16x16x32_bf16 v[4:7], v[216:219], v[248:251], v[196:199]
	v_mfma_f32_16x16x32_bf16 v[0:3], v[224:227], v[248:251], v[0:3]
	v_mfma_f32_16x16x32_bf16 v[4:7], v[220:223], v[184:187], v[4:7]
	v_mfma_f32_16x16x32_bf16 v[0:3], v[228:231], v[184:187], v[0:3]
	s_setprio 0
	s_add_u32 s44, s44, 0x80180
	s_addc_u32 s45, s45, 0
	s_add_u32 s83, s46, 0x200
	s_addc_u32 s84, s47, 0
	s_mov_b32 s46, 0
	s_add_i32 s85, s46, 2
	s_and_b32 s47, s85, 6
	s_cmp_lg_u32 s47, 0
	s_cbranch_scc1 .LBB0_700
	s_branch .LBB0_699

.LBB0_700:
	ds_read_b128 v[130:133], v203
	ds_read_b128 v[134:137], v203 offset:1024
	ds_read_b128 v[138:141], v203 offset:2048
	ds_read_b128 v[142:145], v203 offset:3072
	ds_read_b128 v[146:149], v195
	ds_read_b128 v[150:153], v195 offset:1024
	ds_read_b128 v[154:157], v195 offset:2048
	ds_read_b128 v[158:161], v195 offset:3072
	s_add_u32 s47, s44, 0xfff80080
	s_addc_u32 s48, s45, -1
	s_cmp_eq_u32 s46, 28
	s_cselect_b32 s49, s29, s48
	s_cselect_b32 s48, s71, s47
	s_cselect_b32 s47, s31, s84
	s_cselect_b32 s46, s72, s83
	s_mov_b32 m0, s73
	v_lshl_add_u64 v[174:175], s[44:45], 0, v[180:181]
	ds_read_b128 v[162:165], v211
	ds_read_b128 v[166:169], v211 offset:1024
	ds_read_b128 v[170:173], v211 offset:2048
	ds_read_b128 v[184:187], v211 offset:3072
	ds_read_b128 v[190:193], v211 offset:4096
	ds_read_b128 v[196:199], v211 offset:5120
	ds_read_b128 v[204:207], v211 offset:6144
	ds_read_b128 v[212:215], v211 offset:7168
	global_load_lds_dwordx4 v[174:175], off
	s_mov_b32 m0, s74
	v_lshl_add_u64 v[174:175], s[44:45], 0, v[182:183]
	global_load_lds_dwordx4 v[174:175], off
	s_waitcnt vmcnt(8) lgkmcnt(0)
	s_barrier
	s_setprio 1
	v_mfma_f32_16x16x32_bf16 v[124:127], v[130:133], v[162:165], v[124:127]
	v_mfma_f32_16x16x32_bf16 v[124:127], v[134:137], v[166:169], v[124:127]
	v_mfma_f32_16x16x32_bf16 v[108:111], v[130:133], v[170:173], v[108:111]
	v_mfma_f32_16x16x32_bf16 v[108:111], v[134:137], v[184:187], v[108:111]
	v_mfma_f32_16x16x32_bf16 v[92:95], v[130:133], v[190:193], v[92:95]
	v_mfma_f32_16x16x32_bf16 v[92:95], v[134:137], v[196:199], v[92:95]
	v_mfma_f32_16x16x32_bf16 v[76:79], v[130:133], v[204:207], v[76:79]
	v_mfma_f32_16x16x32_bf16 v[76:79], v[134:137], v[212:215], v[76:79]
	v_mfma_f32_16x16x32_bf16 v[120:123], v[138:141], v[162:165], v[120:123]
	v_mfma_f32_16x16x32_bf16 v[120:123], v[142:145], v[166:169], v[120:123]
	v_mfma_f32_16x16x32_bf16 v[104:107], v[138:141], v[170:173], v[104:107]
	v_mfma_f32_16x16x32_bf16 v[104:107], v[142:145], v[184:187], v[104:107]
	v_mfma_f32_16x16x32_bf16 v[88:91], v[138:141], v[190:193], v[88:91]
	v_mfma_f32_16x16x32_bf16 v[88:91], v[142:145], v[196:199], v[88:91]
	v_mfma_f32_16x16x32_bf16 v[72:75], v[138:141], v[204:207], v[72:75]
	v_mfma_f32_16x16x32_bf16 v[72:75], v[142:145], v[212:215], v[72:75]
	v_mfma_f32_16x16x32_bf16 v[116:119], v[146:149], v[162:165], v[116:119]
	v_mfma_f32_16x16x32_bf16 v[116:119], v[150:153], v[166:169], v[116:119]
	v_mfma_f32_16x16x32_bf16 v[100:103], v[146:149], v[170:173], v[100:103]
	v_mfma_f32_16x16x32_bf16 v[100:103], v[150:153], v[184:187], v[100:103]
	v_mfma_f32_16x16x32_bf16 v[84:87], v[146:149], v[190:193], v[84:87]
	v_mfma_f32_16x16x32_bf16 v[84:87], v[150:153], v[196:199], v[84:87]
	v_mfma_f32_16x16x32_bf16 v[68:71], v[146:149], v[204:207], v[68:71]
	v_mfma_f32_16x16x32_bf16 v[68:71], v[150:153], v[212:215], v[68:71]
	v_mfma_f32_16x16x32_bf16 v[112:115], v[154:157], v[162:165], v[112:115]
	v_mfma_f32_16x16x32_bf16 v[112:115], v[158:161], v[166:169], v[112:115]
	v_mfma_f32_16x16x32_bf16 v[96:99], v[154:157], v[170:173], v[96:99]
	v_mfma_f32_16x16x32_bf16 v[96:99], v[158:161], v[184:187], v[96:99]
	s_setprio 2
	s_barrier
	v_mfma_f32_16x16x32_bf16 v[80:83], v[154:157], v[190:193], v[80:83]
	v_mfma_f32_16x16x32_bf16 v[80:83], v[158:161], v[196:199], v[80:83]
	v_mfma_f32_16x16x32_bf16 v[64:67], v[154:157], v[204:207], v[64:67]
	v_mfma_f32_16x16x32_bf16 v[64:67], v[158:161], v[212:215], v[64:67]
	s_setprio 0
	s_mov_b32 m0, s75
	v_lshl_add_u64 v[174:175], s[46:47], 0, v[176:177]
	s_add_u32 s86, s46, 0x80000
	ds_read_b128 v[162:165], v211 offset:16384
	ds_read_b128 v[166:169], v211 offset:17408
	ds_read_b128 v[170:173], v211 offset:18432
	ds_read_b128 v[184:187], v211 offset:19456
	ds_read_b128 v[190:193], v211 offset:20480
	ds_read_b128 v[196:199], v211 offset:21504
	ds_read_b128 v[204:207], v211 offset:22528
	ds_read_b128 v[212:215], v211 offset:23552
	global_load_lds_dwordx4 v[174:175], off
	v_lshl_add_u64 v[200:201], s[46:47], 0, v[178:179]
	s_mov_b32 m0, s76
	s_addc_u32 s87, s47, 0
	global_load_lds_dwordx4 v[200:201], off
	v_lshl_add_u64 v[208:209], s[86:87], 0, v[176:177]
	s_mov_b32 m0, s77
	v_lshl_add_u64 v[216:217], s[48:49], 0, v[178:179]
	global_load_lds_dwordx4 v[208:209], off
	s_mov_b32 m0, s78
	v_lshl_add_u64 v[208:209], s[86:87], 0, v[178:179]
	global_load_lds_dwordx4 v[208:209], off
	s_mov_b32 m0, s56
	v_lshl_add_u64 v[208:209], s[48:49], 0, v[176:177]
	global_load_lds_dwordx4 v[208:209], off
	s_mov_b32 m0, s57
	s_nop 0
	global_load_lds_dwordx4 v[216:217], off
	s_waitcnt vmcnt(8) lgkmcnt(0)
	s_barrier
	s_setprio 1
	v_mfma_f32_16x16x32_bf16 v[60:63], v[130:133], v[162:165], v[60:63]
	v_mfma_f32_16x16x32_bf16 v[60:63], v[134:137], v[166:169], v[60:63]
	v_mfma_f32_16x16x32_bf16 v[44:47], v[130:133], v[170:173], v[44:47]
	v_mfma_f32_16x16x32_bf16 v[44:47], v[134:137], v[184:187], v[44:47]
	v_mfma_f32_16x16x32_bf16 v[28:31], v[130:133], v[190:193], v[28:31]
	v_mfma_f32_16x16x32_bf16 v[28:31], v[134:137], v[196:199], v[28:31]
	v_mfma_f32_16x16x32_bf16 v[12:15], v[130:133], v[204:207], v[12:15]
	v_mfma_f32_16x16x32_bf16 v[12:15], v[134:137], v[212:215], v[12:15]
	v_mfma_f32_16x16x32_bf16 v[56:59], v[138:141], v[162:165], v[56:59]
	v_mfma_f32_16x16x32_bf16 v[56:59], v[142:145], v[166:169], v[56:59]
	v_mfma_f32_16x16x32_bf16 v[40:43], v[138:141], v[170:173], v[40:43]
	v_mfma_f32_16x16x32_bf16 v[40:43], v[142:145], v[184:187], v[40:43]
	v_mfma_f32_16x16x32_bf16 v[24:27], v[138:141], v[190:193], v[24:27]
	v_mfma_f32_16x16x32_bf16 v[24:27], v[142:145], v[196:199], v[24:27]
	v_mfma_f32_16x16x32_bf16 v[8:11], v[138:141], v[204:207], v[8:11]
	v_mfma_f32_16x16x32_bf16 v[8:11], v[142:145], v[212:215], v[8:11]
	v_mfma_f32_16x16x32_bf16 v[52:55], v[146:149], v[162:165], v[52:55]
	v_mfma_f32_16x16x32_bf16 v[52:55], v[150:153], v[166:169], v[52:55]
	v_mfma_f32_16x16x32_bf16 v[36:39], v[146:149], v[170:173], v[36:39]
	v_mfma_f32_16x16x32_bf16 v[36:39], v[150:153], v[184:187], v[36:39]
	v_mfma_f32_16x16x32_bf16 v[20:23], v[146:149], v[190:193], v[20:23]
	v_mfma_f32_16x16x32_bf16 v[20:23], v[150:153], v[196:199], v[20:23]
	v_mfma_f32_16x16x32_bf16 v[4:7], v[146:149], v[204:207], v[4:7]
	v_mfma_f32_16x16x32_bf16 v[4:7], v[150:153], v[212:215], v[4:7]
	v_mfma_f32_16x16x32_bf16 v[48:51], v[154:157], v[162:165], v[48:51]
	v_mfma_f32_16x16x32_bf16 v[48:51], v[158:161], v[166:169], v[48:51]
	v_mfma_f32_16x16x32_bf16 v[32:35], v[154:157], v[170:173], v[32:35]
	v_mfma_f32_16x16x32_bf16 v[32:35], v[158:161], v[184:187], v[32:35]
	s_setprio 2
	s_barrier
	v_mfma_f32_16x16x32_bf16 v[16:19], v[154:157], v[190:193], v[16:19]
	v_mfma_f32_16x16x32_bf16 v[16:19], v[158:161], v[196:199], v[16:19]
	v_mfma_f32_16x16x32_bf16 v[0:3], v[154:157], v[204:207], v[0:3]
	v_mfma_f32_16x16x32_bf16 v[0:3], v[158:161], v[212:215], v[0:3]
	s_setprio 0
	ds_read_b128 v[130:133], v128
	ds_read_b128 v[134:137], v128 offset:1024
	ds_read_b128 v[138:141], v128 offset:2048
	ds_read_b128 v[142:145], v128 offset:3072
	ds_read_b128 v[146:149], v129
	ds_read_b128 v[150:153], v129 offset:1024
	ds_read_b128 v[154:157], v129 offset:2048
	ds_read_b128 v[158:161], v129 offset:3072
	s_add_u32 s48, s48, 0x80000
	s_addc_u32 s49, s49, 0
	s_mov_b32 m0, s58
	v_lshl_add_u64 v[218:219], s[48:49], 0, v[176:177]
	ds_read_b128 v[162:165], v211 offset:32768
	ds_read_b128 v[166:169], v211 offset:33792
	ds_read_b128 v[170:173], v211 offset:34816
	ds_read_b128 v[184:187], v211 offset:35840
	ds_read_b128 v[190:193], v211 offset:36864
	ds_read_b128 v[196:199], v211 offset:37888
	ds_read_b128 v[204:207], v211 offset:38912
	ds_read_b128 v[212:215], v211 offset:39936
	global_load_lds_dwordx4 v[218:219], off
	s_mov_b32 m0, s59
	v_lshl_add_u64 v[218:219], s[48:49], 0, v[178:179]
	global_load_lds_dwordx4 v[218:219], off
	s_waitcnt vmcnt(8) lgkmcnt(0)
	s_barrier
	s_setprio 1
	v_mfma_f32_16x16x32_bf16 v[124:127], v[130:133], v[162:165], v[124:127]
	v_mfma_f32_16x16x32_bf16 v[124:127], v[134:137], v[166:169], v[124:127]
	v_mfma_f32_16x16x32_bf16 v[108:111], v[130:133], v[170:173], v[108:111]
	v_mfma_f32_16x16x32_bf16 v[108:111], v[134:137], v[184:187], v[108:111]
	v_mfma_f32_16x16x32_bf16 v[92:95], v[130:133], v[190:193], v[92:95]
	v_mfma_f32_16x16x32_bf16 v[92:95], v[134:137], v[196:199], v[92:95]
	v_mfma_f32_16x16x32_bf16 v[76:79], v[130:133], v[204:207], v[76:79]
	v_mfma_f32_16x16x32_bf16 v[76:79], v[134:137], v[212:215], v[76:79]
	v_mfma_f32_16x16x32_bf16 v[120:123], v[138:141], v[162:165], v[120:123]
	v_mfma_f32_16x16x32_bf16 v[120:123], v[142:145], v[166:169], v[120:123]
	v_mfma_f32_16x16x32_bf16 v[104:107], v[138:141], v[170:173], v[104:107]
	v_mfma_f32_16x16x32_bf16 v[104:107], v[142:145], v[184:187], v[104:107]
	v_mfma_f32_16x16x32_bf16 v[88:91], v[138:141], v[190:193], v[88:91]
	v_mfma_f32_16x16x32_bf16 v[88:91], v[142:145], v[196:199], v[88:91]
	v_mfma_f32_16x16x32_bf16 v[72:75], v[138:141], v[204:207], v[72:75]
	v_mfma_f32_16x16x32_bf16 v[72:75], v[142:145], v[212:215], v[72:75]
	v_mfma_f32_16x16x32_bf16 v[116:119], v[146:149], v[162:165], v[116:119]
	v_mfma_f32_16x16x32_bf16 v[116:119], v[150:153], v[166:169], v[116:119]
	v_mfma_f32_16x16x32_bf16 v[100:103], v[146:149], v[170:173], v[100:103]
	v_mfma_f32_16x16x32_bf16 v[100:103], v[150:153], v[184:187], v[100:103]
	v_mfma_f32_16x16x32_bf16 v[84:87], v[146:149], v[190:193], v[84:87]
	v_mfma_f32_16x16x32_bf16 v[84:87], v[150:153], v[196:199], v[84:87]
	v_mfma_f32_16x16x32_bf16 v[68:71], v[146:149], v[204:207], v[68:71]
	v_mfma_f32_16x16x32_bf16 v[68:71], v[150:153], v[212:215], v[68:71]
	v_mfma_f32_16x16x32_bf16 v[112:115], v[154:157], v[162:165], v[112:115]
	v_mfma_f32_16x16x32_bf16 v[112:115], v[158:161], v[166:169], v[112:115]
	v_mfma_f32_16x16x32_bf16 v[96:99], v[154:157], v[170:173], v[96:99]
	v_mfma_f32_16x16x32_bf16 v[96:99], v[158:161], v[184:187], v[96:99]
	s_setprio 2
	s_barrier
	v_mfma_f32_16x16x32_bf16 v[80:83], v[154:157], v[190:193], v[80:83]
	v_mfma_f32_16x16x32_bf16 v[80:83], v[158:161], v[196:199], v[80:83]
	v_mfma_f32_16x16x32_bf16 v[64:67], v[154:157], v[204:207], v[64:67]
	v_mfma_f32_16x16x32_bf16 v[64:67], v[158:161], v[212:215], v[64:67]
	s_setprio 0
	s_mov_b32 m0, s79
	v_lshl_add_u64 v[174:175], v[174:175], 0, s[20:21]
	s_add_u32 s46, s46, 0x80080
	ds_read_b128 v[162:165], v211 offset:49152
	ds_read_b128 v[166:169], v211 offset:50176
	ds_read_b128 v[170:173], v211 offset:51200
	ds_read_b128 v[184:187], v211 offset:52224
	ds_read_b128 v[190:193], v211 offset:53248
	ds_read_b128 v[196:199], v211 offset:54272
	ds_read_b128 v[204:207], v211 offset:55296
	ds_read_b128 v[212:215], v211 offset:56320
	global_load_lds_dwordx4 v[174:175], off
	v_lshl_add_u64 v[174:175], v[200:201], 0, s[20:21]
	s_mov_b32 m0, s80
	s_addc_u32 s47, s47, 0
	global_load_lds_dwordx4 v[174:175], off
	s_mov_b32 m0, s81
	v_lshl_add_u64 v[174:175], s[46:47], 0, v[176:177]
	global_load_lds_dwordx4 v[174:175], off
	s_mov_b32 m0, s82
	v_lshl_add_u64 v[174:175], s[46:47], 0, v[178:179]
	global_load_lds_dwordx4 v[174:175], off
	s_mov_b32 m0, s61
	v_lshl_add_u64 v[174:175], v[208:209], 0, s[20:21]
	global_load_lds_dwordx4 v[174:175], off
	s_mov_b32 m0, s62
	v_lshl_add_u64 v[174:175], v[216:217], 0, s[20:21]
	global_load_lds_dwordx4 v[174:175], off
	s_waitcnt vmcnt(8) lgkmcnt(0)
	s_barrier
	s_setprio 1
	v_mfma_f32_16x16x32_bf16 v[60:63], v[130:133], v[162:165], v[60:63]
	v_mfma_f32_16x16x32_bf16 v[60:63], v[134:137], v[166:169], v[60:63]
	v_mfma_f32_16x16x32_bf16 v[44:47], v[130:133], v[170:173], v[44:47]
	v_mfma_f32_16x16x32_bf16 v[44:47], v[134:137], v[184:187], v[44:47]
	v_mfma_f32_16x16x32_bf16 v[28:31], v[130:133], v[190:193], v[28:31]
	v_mfma_f32_16x16x32_bf16 v[28:31], v[134:137], v[196:199], v[28:31]
	v_mfma_f32_16x16x32_bf16 v[12:15], v[130:133], v[204:207], v[12:15]
	v_mfma_f32_16x16x32_bf16 v[12:15], v[134:137], v[212:215], v[12:15]
	v_mfma_f32_16x16x32_bf16 v[56:59], v[138:141], v[162:165], v[56:59]
	v_mfma_f32_16x16x32_bf16 v[56:59], v[142:145], v[166:169], v[56:59]
	v_mfma_f32_16x16x32_bf16 v[40:43], v[138:141], v[170:173], v[40:43]
	v_mfma_f32_16x16x32_bf16 v[40:43], v[142:145], v[184:187], v[40:43]
	v_mfma_f32_16x16x32_bf16 v[24:27], v[138:141], v[190:193], v[24:27]
	v_mfma_f32_16x16x32_bf16 v[24:27], v[142:145], v[196:199], v[24:27]
	v_mfma_f32_16x16x32_bf16 v[8:11], v[138:141], v[204:207], v[8:11]
	v_mfma_f32_16x16x32_bf16 v[8:11], v[142:145], v[212:215], v[8:11]
	v_mfma_f32_16x16x32_bf16 v[52:55], v[146:149], v[162:165], v[52:55]
	v_mfma_f32_16x16x32_bf16 v[52:55], v[150:153], v[166:169], v[52:55]
	v_mfma_f32_16x16x32_bf16 v[36:39], v[146:149], v[170:173], v[36:39]
	v_mfma_f32_16x16x32_bf16 v[36:39], v[150:153], v[184:187], v[36:39]
	v_mfma_f32_16x16x32_bf16 v[20:23], v[146:149], v[190:193], v[20:23]
	v_mfma_f32_16x16x32_bf16 v[20:23], v[150:153], v[196:199], v[20:23]
	v_mfma_f32_16x16x32_bf16 v[4:7], v[146:149], v[204:207], v[4:7]
	v_mfma_f32_16x16x32_bf16 v[4:7], v[150:153], v[212:215], v[4:7]
	v_mfma_f32_16x16x32_bf16 v[48:51], v[154:157], v[162:165], v[48:51]
	v_mfma_f32_16x16x32_bf16 v[48:51], v[158:161], v[166:169], v[48:51]
	v_mfma_f32_16x16x32_bf16 v[32:35], v[154:157], v[170:173], v[32:35]
	v_mfma_f32_16x16x32_bf16 v[32:35], v[158:161], v[184:187], v[32:35]
	s_setprio 2
	s_barrier
	v_mfma_f32_16x16x32_bf16 v[16:19], v[154:157], v[190:193], v[16:19]
	v_mfma_f32_16x16x32_bf16 v[16:19], v[158:161], v[196:199], v[16:19]
	v_mfma_f32_16x16x32_bf16 v[0:3], v[154:157], v[204:207], v[0:3]
	v_mfma_f32_16x16x32_bf16 v[0:3], v[158:161], v[212:215], v[0:3]
	s_setprio 0
	s_add_i32 s70, s70, 1
	s_add_u32 s44, s44, 0x100
	s_addc_u32 s45, s45, 0
	s_add_u32 s83, s83, 0x100
	s_addc_u32 s84, s84, 0
	s_cmp_gt_u32 s85, 29
	s_cbranch_scc0 .LBB0_698
	s_lshl_b32 s29, s41, 12
	s_and_b32 s29, s29, 0x1000
	s_add_i32 s29, s29, 0
	v_mbcnt_lo_u32_b32 v128, -1, 0
	v_mbcnt_hi_u32_b32 v128, -1, v128
	s_add_i32 s29, s29, s63
	v_lshlrev_b32_e32 v128, 4, v128
	s_add_i32 s29, s29, 0x20400
	v_and_b32_e32 v128, 0xf0, v128
	v_add_u32_e32 v128, s29, v128
	ds_read2_b32 v[214:215], v128 offset0:3 offset1:67
	ds_read2_b32 v[206:207], v128 offset0:131 offset1:195
	v_add_u32_e32 v128, 12, v128
	ds_read2st64_b32 v[196:197], v128 offset0:8 offset1:9
	ds_read2st64_b32 v[190:191], v128 offset0:10 offset1:11
	s_and_b64 vcc, exec, s[22:23]
	s_waitcnt lgkmcnt(0)
	v_mov_b32_e32 v210, v215
	v_mov_b32_e32 v202, v207
	v_mov_b32_e32 v194, v197
	v_mov_b32_e32 v188, v191
	s_cbranch_vccz .LBB0_703
	s_barrier

.LBB0_783:
	s_ashr_i32 s23, s22, 31
	s_lshl_b64 s[26:27], s[22:23], 19
	s_add_u32 s26, s43, s26
	s_addc_u32 s27, s44, s27
	s_and_b64 s[28:29], s[4:5], exec
	s_cselect_b32 s23, s27, s37
	s_cselect_b32 s31, s26, s36
	s_ashr_i32 s25, s24, 31
	s_lshl_b64 s[28:29], s[24:25], 19
	s_add_u32 s28, s45, s28
	s_addc_u32 s29, s46, s29
	s_and_b64 s[40:41], s[4:5], exec
	s_cselect_b32 s25, s29, s39
	s_cselect_b32 s62, s28, s38
	s_add_u32 s36, s36, 0x40080
	s_addc_u32 s37, s37, 0
	s_add_u32 s63, s38, 0x100
	s_addc_u32 s64, s39, 0
	s_mov_b32 s65, -2
	ds_read_b128 v[144:147], v163
	ds_read_b128 v[148:151], v163 offset:1024
	ds_read_b128 v[152:155], v163 offset:2048
	ds_read_b128 v[156:159], v163 offset:3072
	ds_read_b128 v[168:171], v164
	ds_read_b128 v[172:175], v164 offset:1024
	ds_read_b128 v[176:179], v164 offset:2048
	ds_read_b128 v[180:183], v164 offset:3072
	s_add_u32 s38, s36, 0xfffc0080
	s_addc_u32 s39, s37, -1
	s_cmp_eq_u32 s65, 12
	s_cselect_b32 s41, s23, s39
	s_cselect_b32 s40, s31, s38
	s_cselect_b32 s39, s25, s64
	s_cselect_b32 s38, s62, s63
	v_lshl_add_u64 v[160:161], s[36:37], 0, v[136:137]
	s_add_i32 m0, s50, 0xc000
	ds_read_b128 v[184:187], v165
	ds_read_b128 v[188:191], v165 offset:1024
	ds_read_b128 v[192:195], v165 offset:2048
	ds_read_b128 v[196:199], v165 offset:3072
	ds_read_b128 v[200:203], v165 offset:4096
	ds_read_b128 v[204:207], v165 offset:5120
	ds_read_b128 v[208:211], v165 offset:6144
	ds_read_b128 v[212:215], v165 offset:7168
	global_load_lds_dwordx4 v[160:161], off
	s_add_i32 m0, s50, 0xe000
	v_lshl_add_u64 v[160:161], s[36:37], 0, v[138:139]
	global_load_lds_dwordx4 v[160:161], off
	s_waitcnt vmcnt(8) lgkmcnt(0)
	s_barrier
	s_setprio 1
	v_mfma_f32_16x16x32_bf16 v[124:127], v[144:147], v[184:187], 0
	v_mfma_f32_16x16x32_bf16 v[124:127], v[148:151], v[188:191], v[124:127]
	v_mfma_f32_16x16x32_bf16 v[108:111], v[144:147], v[192:195], 0
	v_mfma_f32_16x16x32_bf16 v[108:111], v[148:151], v[196:199], v[108:111]
	v_mfma_f32_16x16x32_bf16 v[92:95], v[144:147], v[200:203], 0
	v_mfma_f32_16x16x32_bf16 v[92:95], v[148:151], v[204:207], v[92:95]
	v_mfma_f32_16x16x32_bf16 v[76:79], v[144:147], v[208:211], 0
	v_mfma_f32_16x16x32_bf16 v[76:79], v[148:151], v[212:215], v[76:79]
	v_mfma_f32_16x16x32_bf16 v[120:123], v[152:155], v[184:187], 0
	v_mfma_f32_16x16x32_bf16 v[120:123], v[156:159], v[188:191], v[120:123]
	v_mfma_f32_16x16x32_bf16 v[104:107], v[152:155], v[192:195], 0
	v_mfma_f32_16x16x32_bf16 v[104:107], v[156:159], v[196:199], v[104:107]
	v_mfma_f32_16x16x32_bf16 v[88:91], v[152:155], v[200:203], 0
	v_mfma_f32_16x16x32_bf16 v[88:91], v[156:159], v[204:207], v[88:91]
	v_mfma_f32_16x16x32_bf16 v[72:75], v[152:155], v[208:211], 0
	v_mfma_f32_16x16x32_bf16 v[72:75], v[156:159], v[212:215], v[72:75]
	v_mfma_f32_16x16x32_bf16 v[116:119], v[168:171], v[184:187], 0
	v_mfma_f32_16x16x32_bf16 v[116:119], v[172:175], v[188:191], v[116:119]
	v_mfma_f32_16x16x32_bf16 v[100:103], v[168:171], v[192:195], 0
	v_mfma_f32_16x16x32_bf16 v[100:103], v[172:175], v[196:199], v[100:103]
	v_mfma_f32_16x16x32_bf16 v[84:87], v[168:171], v[200:203], 0
	v_mfma_f32_16x16x32_bf16 v[84:87], v[172:175], v[204:207], v[84:87]
	v_mfma_f32_16x16x32_bf16 v[68:71], v[168:171], v[208:211], 0
	v_mfma_f32_16x16x32_bf16 v[68:71], v[172:175], v[212:215], v[68:71]
	v_mfma_f32_16x16x32_bf16 v[112:115], v[176:179], v[184:187], 0
	v_mfma_f32_16x16x32_bf16 v[112:115], v[180:183], v[188:191], v[112:115]
	v_mfma_f32_16x16x32_bf16 v[96:99], v[176:179], v[192:195], 0
	v_mfma_f32_16x16x32_bf16 v[96:99], v[180:183], v[196:199], v[96:99]
	s_setprio 2
	s_barrier
	v_mfma_f32_16x16x32_bf16 v[80:83], v[176:179], v[200:203], 0
	v_mfma_f32_16x16x32_bf16 v[80:83], v[180:183], v[204:207], v[80:83]
	v_mfma_f32_16x16x32_bf16 v[64:67], v[176:179], v[208:211], 0
	v_mfma_f32_16x16x32_bf16 v[64:67], v[180:183], v[212:215], v[64:67]
	s_setprio 0
	s_add_i32 s66, s59, s47
	v_lshl_add_u64 v[160:161], s[38:39], 0, v[132:133]
	s_mov_b32 m0, s66
	ds_read_b128 v[184:187], v165 offset:16384
	ds_read_b128 v[188:191], v165 offset:17408
	ds_read_b128 v[192:195], v165 offset:18432
	ds_read_b128 v[196:199], v165 offset:19456
	ds_read_b128 v[200:203], v165 offset:20480
	ds_read_b128 v[204:207], v165 offset:21504
	ds_read_b128 v[208:211], v165 offset:22528
	ds_read_b128 v[212:215], v165 offset:23552
	global_load_lds_dwordx4 v[160:161], off
	s_add_i32 m0, s66, 0x2000
	s_add_u32 s66, s38, 0x40000
	v_lshl_add_u64 v[216:217], s[38:39], 0, v[128:129]
	s_addc_u32 s67, s39, 0
	s_add_i32 s68, s60, s47
	global_load_lds_dwordx4 v[216:217], off
	v_lshl_add_u64 v[218:219], s[66:67], 0, v[132:133]
	s_mov_b32 m0, s68
	v_lshl_add_u64 v[220:221], s[40:41], 0, v[130:131]
	global_load_lds_dwordx4 v[218:219], off
	s_add_i32 m0, s68, 0x2000
	v_lshl_add_u64 v[218:219], s[66:67], 0, v[128:129]
	global_load_lds_dwordx4 v[218:219], off
	s_mov_b32 m0, s50
	v_lshl_add_u64 v[218:219], s[40:41], 0, v[134:135]
	global_load_lds_dwordx4 v[218:219], off
	s_mov_b32 m0, s51
	s_nop 0
	global_load_lds_dwordx4 v[220:221], off
	s_waitcnt vmcnt(8) lgkmcnt(0)
	s_barrier
	s_setprio 1
	v_mfma_f32_16x16x32_bf16 v[60:63], v[144:147], v[184:187], 0
	v_mfma_f32_16x16x32_bf16 v[60:63], v[148:151], v[188:191], v[60:63]
	v_mfma_f32_16x16x32_bf16 v[44:47], v[144:147], v[192:195], 0
	v_mfma_f32_16x16x32_bf16 v[44:47], v[148:151], v[196:199], v[44:47]
	v_mfma_f32_16x16x32_bf16 v[28:31], v[144:147], v[200:203], 0
	v_mfma_f32_16x16x32_bf16 v[28:31], v[148:151], v[204:207], v[28:31]
	v_mfma_f32_16x16x32_bf16 v[12:15], v[144:147], v[208:211], 0
	v_mfma_f32_16x16x32_bf16 v[12:15], v[148:151], v[212:215], v[12:15]
	v_mfma_f32_16x16x32_bf16 v[56:59], v[152:155], v[184:187], 0
	v_mfma_f32_16x16x32_bf16 v[56:59], v[156:159], v[188:191], v[56:59]
	v_mfma_f32_16x16x32_bf16 v[40:43], v[152:155], v[192:195], 0
	v_mfma_f32_16x16x32_bf16 v[40:43], v[156:159], v[196:199], v[40:43]
	v_mfma_f32_16x16x32_bf16 v[24:27], v[152:155], v[200:203], 0
	v_mfma_f32_16x16x32_bf16 v[24:27], v[156:159], v[204:207], v[24:27]
	v_mfma_f32_16x16x32_bf16 v[8:11], v[152:155], v[208:211], 0
	v_mfma_f32_16x16x32_bf16 v[8:11], v[156:159], v[212:215], v[8:11]
	v_mfma_f32_16x16x32_bf16 v[52:55], v[168:171], v[184:187], 0
	v_mfma_f32_16x16x32_bf16 v[52:55], v[172:175], v[188:191], v[52:55]
	v_mfma_f32_16x16x32_bf16 v[36:39], v[168:171], v[192:195], 0
	v_mfma_f32_16x16x32_bf16 v[36:39], v[172:175], v[196:199], v[36:39]
	v_mfma_f32_16x16x32_bf16 v[20:23], v[168:171], v[200:203], 0
	v_mfma_f32_16x16x32_bf16 v[20:23], v[172:175], v[204:207], v[20:23]
	v_mfma_f32_16x16x32_bf16 v[4:7], v[168:171], v[208:211], 0
	v_mfma_f32_16x16x32_bf16 v[4:7], v[172:175], v[212:215], v[4:7]
	v_mfma_f32_16x16x32_bf16 v[48:51], v[176:179], v[184:187], 0
	v_mfma_f32_16x16x32_bf16 v[48:51], v[180:183], v[188:191], v[48:51]
	v_mfma_f32_16x16x32_bf16 v[32:35], v[176:179], v[192:195], 0
	v_mfma_f32_16x16x32_bf16 v[32:35], v[180:183], v[196:199], v[32:35]
	s_setprio 2
	s_barrier
	v_mfma_f32_16x16x32_bf16 v[16:19], v[176:179], v[200:203], 0
	v_mfma_f32_16x16x32_bf16 v[16:19], v[180:183], v[204:207], v[16:19]
	v_mfma_f32_16x16x32_bf16 v[0:3], v[176:179], v[208:211], 0
	v_mfma_f32_16x16x32_bf16 v[0:3], v[180:183], v[212:215], v[0:3]
	s_setprio 0
	s_add_i32 s66, 0, 0x18000
	s_add_i32 s67, 0, 0x1c000
	v_add_u32_e32 v156, s66, v162
	v_add_u32_e32 v167, s67, v162
	ds_read_b128 v[144:147], v156
	ds_read_b128 v[148:151], v156 offset:1024
	ds_read_b128 v[152:155], v156 offset:2048
	ds_read_b128 v[156:159], v156 offset:3072
	ds_read_b128 v[168:171], v167
	ds_read_b128 v[172:175], v167 offset:1024
	ds_read_b128 v[176:179], v167 offset:2048
	ds_read_b128 v[180:183], v167 offset:3072
	s_add_u32 s40, s40, 0x40000
	s_addc_u32 s41, s41, 0
	s_mov_b32 m0, s54
	v_lshl_add_u64 v[222:223], s[40:41], 0, v[134:135]
	ds_read_b128 v[184:187], v165 offset:32768
	ds_read_b128 v[188:191], v165 offset:33792
	ds_read_b128 v[192:195], v165 offset:34816
	ds_read_b128 v[196:199], v165 offset:35840
	ds_read_b128 v[200:203], v165 offset:36864
	ds_read_b128 v[204:207], v165 offset:37888
	ds_read_b128 v[208:211], v165 offset:38912
	ds_read_b128 v[212:215], v165 offset:39936
	global_load_lds_dwordx4 v[222:223], off
	s_mov_b32 m0, s55
	v_lshl_add_u64 v[222:223], s[40:41], 0, v[130:131]
	global_load_lds_dwordx4 v[222:223], off
	s_waitcnt vmcnt(8) lgkmcnt(0)
	s_barrier
	s_setprio 1
	v_mfma_f32_16x16x32_bf16 v[124:127], v[144:147], v[184:187], v[124:127]
	v_mfma_f32_16x16x32_bf16 v[124:127], v[148:151], v[188:191], v[124:127]
	v_mfma_f32_16x16x32_bf16 v[108:111], v[144:147], v[192:195], v[108:111]
	v_mfma_f32_16x16x32_bf16 v[108:111], v[148:151], v[196:199], v[108:111]
	v_mfma_f32_16x16x32_bf16 v[92:95], v[144:147], v[200:203], v[92:95]
	v_mfma_f32_16x16x32_bf16 v[92:95], v[148:151], v[204:207], v[92:95]
	v_mfma_f32_16x16x32_bf16 v[76:79], v[144:147], v[208:211], v[76:79]
	v_mfma_f32_16x16x32_bf16 v[76:79], v[148:151], v[212:215], v[76:79]
	v_mfma_f32_16x16x32_bf16 v[120:123], v[152:155], v[184:187], v[120:123]
	v_mfma_f32_16x16x32_bf16 v[120:123], v[156:159], v[188:191], v[120:123]
	v_mfma_f32_16x16x32_bf16 v[104:107], v[152:155], v[192:195], v[104:107]
	v_mfma_f32_16x16x32_bf16 v[104:107], v[156:159], v[196:199], v[104:107]
	v_mfma_f32_16x16x32_bf16 v[88:91], v[152:155], v[200:203], v[88:91]
	v_mfma_f32_16x16x32_bf16 v[88:91], v[156:159], v[204:207], v[88:91]
	v_mfma_f32_16x16x32_bf16 v[72:75], v[152:155], v[208:211], v[72:75]
	v_mfma_f32_16x16x32_bf16 v[72:75], v[156:159], v[212:215], v[72:75]
	v_mfma_f32_16x16x32_bf16 v[116:119], v[168:171], v[184:187], v[116:119]
	v_mfma_f32_16x16x32_bf16 v[116:119], v[172:175], v[188:191], v[116:119]
	v_mfma_f32_16x16x32_bf16 v[100:103], v[168:171], v[192:195], v[100:103]
	v_mfma_f32_16x16x32_bf16 v[100:103], v[172:175], v[196:199], v[100:103]
	v_mfma_f32_16x16x32_bf16 v[84:87], v[168:171], v[200:203], v[84:87]
	v_mfma_f32_16x16x32_bf16 v[84:87], v[172:175], v[204:207], v[84:87]
	v_mfma_f32_16x16x32_bf16 v[68:71], v[168:171], v[208:211], v[68:71]
	v_mfma_f32_16x16x32_bf16 v[68:71], v[172:175], v[212:215], v[68:71]
	v_mfma_f32_16x16x32_bf16 v[112:115], v[176:179], v[184:187], v[112:115]
	v_mfma_f32_16x16x32_bf16 v[112:115], v[180:183], v[188:191], v[112:115]
	v_mfma_f32_16x16x32_bf16 v[96:99], v[176:179], v[192:195], v[96:99]
	v_mfma_f32_16x16x32_bf16 v[96:99], v[180:183], v[196:199], v[96:99]
	s_setprio 2
	s_barrier
	v_mfma_f32_16x16x32_bf16 v[80:83], v[176:179], v[200:203], v[80:83]
	v_mfma_f32_16x16x32_bf16 v[80:83], v[180:183], v[204:207], v[80:83]
	v_mfma_f32_16x16x32_bf16 v[64:67], v[176:179], v[208:211], v[64:67]
	v_mfma_f32_16x16x32_bf16 v[64:67], v[180:183], v[212:215], v[64:67]
	s_setprio 0
	s_add_i32 s40, s66, s47
	v_lshl_add_u64 v[160:161], v[160:161], 0, s[16:17]
	s_mov_b32 m0, s40
	ds_read_b128 v[184:187], v165 offset:49152
	ds_read_b128 v[188:191], v165 offset:50176
	ds_read_b128 v[192:195], v165 offset:51200
	ds_read_b128 v[196:199], v165 offset:52224
	ds_read_b128 v[200:203], v165 offset:53248
	ds_read_b128 v[204:207], v165 offset:54272
	ds_read_b128 v[208:211], v165 offset:55296
	ds_read_b128 v[212:215], v165 offset:56320
	global_load_lds_dwordx4 v[160:161], off
	s_add_i32 m0, s40, 0x2000
	s_add_u32 s38, s38, 0x40080
	v_lshl_add_u64 v[160:161], v[216:217], 0, s[16:17]
	s_addc_u32 s39, s39, 0
	s_add_i32 s40, s67, s47
	global_load_lds_dwordx4 v[160:161], off
	s_mov_b32 m0, s40
	v_lshl_add_u64 v[160:161], s[38:39], 0, v[132:133]
	global_load_lds_dwordx4 v[160:161], off
	s_add_i32 m0, s40, 0x2000
	v_lshl_add_u64 v[160:161], s[38:39], 0, v[128:129]
	global_load_lds_dwordx4 v[160:161], off
	s_mov_b32 m0, s57
	v_lshl_add_u64 v[160:161], v[218:219], 0, s[16:17]
	global_load_lds_dwordx4 v[160:161], off
	s_mov_b32 m0, s58
	v_lshl_add_u64 v[160:161], v[220:221], 0, s[16:17]
	global_load_lds_dwordx4 v[160:161], off
	s_waitcnt vmcnt(8) lgkmcnt(0)
	s_barrier
	s_setprio 1
	v_mfma_f32_16x16x32_bf16 v[60:63], v[144:147], v[184:187], v[60:63]
	v_mfma_f32_16x16x32_bf16 v[60:63], v[148:151], v[188:191], v[60:63]
	v_mfma_f32_16x16x32_bf16 v[44:47], v[144:147], v[192:195], v[44:47]
	v_mfma_f32_16x16x32_bf16 v[44:47], v[148:151], v[196:199], v[44:47]
	v_mfma_f32_16x16x32_bf16 v[28:31], v[144:147], v[200:203], v[28:31]
	v_mfma_f32_16x16x32_bf16 v[28:31], v[148:151], v[204:207], v[28:31]
	v_mfma_f32_16x16x32_bf16 v[12:15], v[144:147], v[208:211], v[12:15]
	v_mfma_f32_16x16x32_bf16 v[12:15], v[148:151], v[212:215], v[12:15]
	v_mfma_f32_16x16x32_bf16 v[56:59], v[152:155], v[184:187], v[56:59]
	v_mfma_f32_16x16x32_bf16 v[56:59], v[156:159], v[188:191], v[56:59]
	v_mfma_f32_16x16x32_bf16 v[40:43], v[152:155], v[192:195], v[40:43]
	v_mfma_f32_16x16x32_bf16 v[40:43], v[156:159], v[196:199], v[40:43]
	v_mfma_f32_16x16x32_bf16 v[24:27], v[152:155], v[200:203], v[24:27]
	v_mfma_f32_16x16x32_bf16 v[24:27], v[156:159], v[204:207], v[24:27]
	v_mfma_f32_16x16x32_bf16 v[8:11], v[152:155], v[208:211], v[8:11]
	v_mfma_f32_16x16x32_bf16 v[8:11], v[156:159], v[212:215], v[8:11]
	v_mfma_f32_16x16x32_bf16 v[52:55], v[168:171], v[184:187], v[52:55]
	v_mfma_f32_16x16x32_bf16 v[52:55], v[172:175], v[188:191], v[52:55]
	v_mfma_f32_16x16x32_bf16 v[36:39], v[168:171], v[192:195], v[36:39]
	v_mfma_f32_16x16x32_bf16 v[36:39], v[172:175], v[196:199], v[36:39]
	v_mfma_f32_16x16x32_bf16 v[20:23], v[168:171], v[200:203], v[20:23]
	v_mfma_f32_16x16x32_bf16 v[20:23], v[172:175], v[204:207], v[20:23]
	v_mfma_f32_16x16x32_bf16 v[4:7], v[168:171], v[208:211], v[4:7]
	v_mfma_f32_16x16x32_bf16 v[4:7], v[172:175], v[212:215], v[4:7]
	v_mfma_f32_16x16x32_bf16 v[48:51], v[176:179], v[184:187], v[48:51]
	v_mfma_f32_16x16x32_bf16 v[48:51], v[180:183], v[188:191], v[48:51]
	v_mfma_f32_16x16x32_bf16 v[32:35], v[176:179], v[192:195], v[32:35]
	v_mfma_f32_16x16x32_bf16 v[32:35], v[180:183], v[196:199], v[32:35]
	s_setprio 2
	s_barrier
	v_mfma_f32_16x16x32_bf16 v[16:19], v[176:179], v[200:203], v[16:19]
	v_mfma_f32_16x16x32_bf16 v[16:19], v[180:183], v[204:207], v[16:19]
	v_mfma_f32_16x16x32_bf16 v[0:3], v[176:179], v[208:211], v[0:3]
	v_mfma_f32_16x16x32_bf16 v[0:3], v[180:183], v[212:215], v[0:3]
	s_setprio 0
	s_add_i32 s65, s65, 2
	s_add_u32 s36, s36, 0x100
	s_addc_u32 s37, s37, 0
	s_add_u32 s63, s63, 0x100
	s_addc_u32 s64, s64, 0
	s_cmp_gt_u32 s65, 13
.LBB0_784:
	ds_read_b128 v[144:147], v163
	ds_read_b128 v[148:151], v163 offset:1024
	ds_read_b128 v[152:155], v163 offset:2048
	ds_read_b128 v[156:159], v163 offset:3072
	ds_read_b128 v[168:171], v164
	ds_read_b128 v[172:175], v164 offset:1024
	ds_read_b128 v[176:179], v164 offset:2048
	ds_read_b128 v[180:183], v164 offset:3072
	s_add_u32 s38, s36, 0xfffc0080
	s_addc_u32 s39, s37, -1
	s_cmp_eq_u32 s65, 12
	s_cselect_b32 s41, s23, s39
	s_cselect_b32 s40, s31, s38
	s_cselect_b32 s39, s25, s64
	s_cselect_b32 s38, s62, s63
	v_lshl_add_u64 v[160:161], s[36:37], 0, v[136:137]
	s_add_i32 m0, s50, 0xc000
	ds_read_b128 v[184:187], v165
	ds_read_b128 v[188:191], v165 offset:1024
	ds_read_b128 v[192:195], v165 offset:2048
	ds_read_b128 v[196:199], v165 offset:3072
	ds_read_b128 v[200:203], v165 offset:4096
	ds_read_b128 v[204:207], v165 offset:5120
	ds_read_b128 v[208:211], v165 offset:6144
	ds_read_b128 v[212:215], v165 offset:7168
	global_load_lds_dwordx4 v[160:161], off
	s_add_i32 m0, s50, 0xe000
	v_lshl_add_u64 v[160:161], s[36:37], 0, v[138:139]
	global_load_lds_dwordx4 v[160:161], off
	s_waitcnt vmcnt(8) lgkmcnt(0)
	s_barrier
	s_setprio 1
	v_mfma_f32_16x16x32_bf16 v[124:127], v[144:147], v[184:187], v[124:127]
	v_mfma_f32_16x16x32_bf16 v[124:127], v[148:151], v[188:191], v[124:127]
	v_mfma_f32_16x16x32_bf16 v[108:111], v[144:147], v[192:195], v[108:111]
	v_mfma_f32_16x16x32_bf16 v[108:111], v[148:151], v[196:199], v[108:111]
	v_mfma_f32_16x16x32_bf16 v[92:95], v[144:147], v[200:203], v[92:95]
	v_mfma_f32_16x16x32_bf16 v[92:95], v[148:151], v[204:207], v[92:95]
	v_mfma_f32_16x16x32_bf16 v[76:79], v[144:147], v[208:211], v[76:79]
	v_mfma_f32_16x16x32_bf16 v[76:79], v[148:151], v[212:215], v[76:79]
	v_mfma_f32_16x16x32_bf16 v[120:123], v[152:155], v[184:187], v[120:123]
	v_mfma_f32_16x16x32_bf16 v[120:123], v[156:159], v[188:191], v[120:123]
	v_mfma_f32_16x16x32_bf16 v[104:107], v[152:155], v[192:195], v[104:107]
	v_mfma_f32_16x16x32_bf16 v[104:107], v[156:159], v[196:199], v[104:107]
	v_mfma_f32_16x16x32_bf16 v[88:91], v[152:155], v[200:203], v[88:91]
	v_mfma_f32_16x16x32_bf16 v[88:91], v[156:159], v[204:207], v[88:91]
	v_mfma_f32_16x16x32_bf16 v[72:75], v[152:155], v[208:211], v[72:75]
	v_mfma_f32_16x16x32_bf16 v[72:75], v[156:159], v[212:215], v[72:75]
	v_mfma_f32_16x16x32_bf16 v[116:119], v[168:171], v[184:187], v[116:119]
	v_mfma_f32_16x16x32_bf16 v[116:119], v[172:175], v[188:191], v[116:119]
	v_mfma_f32_16x16x32_bf16 v[100:103], v[168:171], v[192:195], v[100:103]
	v_mfma_f32_16x16x32_bf16 v[100:103], v[172:175], v[196:199], v[100:103]
	v_mfma_f32_16x16x32_bf16 v[84:87], v[168:171], v[200:203], v[84:87]
	v_mfma_f32_16x16x32_bf16 v[84:87], v[172:175], v[204:207], v[84:87]
	v_mfma_f32_16x16x32_bf16 v[68:71], v[168:171], v[208:211], v[68:71]
	v_mfma_f32_16x16x32_bf16 v[68:71], v[172:175], v[212:215], v[68:71]
	v_mfma_f32_16x16x32_bf16 v[112:115], v[176:179], v[184:187], v[112:115]
	v_mfma_f32_16x16x32_bf16 v[112:115], v[180:183], v[188:191], v[112:115]
	v_mfma_f32_16x16x32_bf16 v[96:99], v[176:179], v[192:195], v[96:99]
	v_mfma_f32_16x16x32_bf16 v[96:99], v[180:183], v[196:199], v[96:99]
	s_setprio 2
	s_barrier
	v_mfma_f32_16x16x32_bf16 v[80:83], v[176:179], v[200:203], v[80:83]
	v_mfma_f32_16x16x32_bf16 v[80:83], v[180:183], v[204:207], v[80:83]
	v_mfma_f32_16x16x32_bf16 v[64:67], v[176:179], v[208:211], v[64:67]
	v_mfma_f32_16x16x32_bf16 v[64:67], v[180:183], v[212:215], v[64:67]
	s_setprio 0
	s_add_i32 s66, s59, s47
	v_lshl_add_u64 v[160:161], s[38:39], 0, v[132:133]
	s_mov_b32 m0, s66
	ds_read_b128 v[184:187], v165 offset:16384
	ds_read_b128 v[188:191], v165 offset:17408
	ds_read_b128 v[192:195], v165 offset:18432
	ds_read_b128 v[196:199], v165 offset:19456
	ds_read_b128 v[200:203], v165 offset:20480
	ds_read_b128 v[204:207], v165 offset:21504
	ds_read_b128 v[208:211], v165 offset:22528
	ds_read_b128 v[212:215], v165 offset:23552
	global_load_lds_dwordx4 v[160:161], off
	s_add_i32 m0, s66, 0x2000
	s_add_u32 s66, s38, 0x40000
	v_lshl_add_u64 v[216:217], s[38:39], 0, v[128:129]
	s_addc_u32 s67, s39, 0
	s_add_i32 s68, s60, s47
	global_load_lds_dwordx4 v[216:217], off
	v_lshl_add_u64 v[218:219], s[66:67], 0, v[132:133]
	s_mov_b32 m0, s68
	v_lshl_add_u64 v[220:221], s[40:41], 0, v[130:131]
	global_load_lds_dwordx4 v[218:219], off
	s_add_i32 m0, s68, 0x2000
	v_lshl_add_u64 v[218:219], s[66:67], 0, v[128:129]
	global_load_lds_dwordx4 v[218:219], off
	s_mov_b32 m0, s50
	v_lshl_add_u64 v[218:219], s[40:41], 0, v[134:135]
	global_load_lds_dwordx4 v[218:219], off
	s_mov_b32 m0, s51
	s_nop 0
	global_load_lds_dwordx4 v[220:221], off
	s_waitcnt vmcnt(8) lgkmcnt(0)
	s_barrier
	s_setprio 1
	v_mfma_f32_16x16x32_bf16 v[60:63], v[144:147], v[184:187], v[60:63]
	v_mfma_f32_16x16x32_bf16 v[60:63], v[148:151], v[188:191], v[60:63]
	v_mfma_f32_16x16x32_bf16 v[44:47], v[144:147], v[192:195], v[44:47]
	v_mfma_f32_16x16x32_bf16 v[44:47], v[148:151], v[196:199], v[44:47]
	v_mfma_f32_16x16x32_bf16 v[28:31], v[144:147], v[200:203], v[28:31]
	v_mfma_f32_16x16x32_bf16 v[28:31], v[148:151], v[204:207], v[28:31]
	v_mfma_f32_16x16x32_bf16 v[12:15], v[144:147], v[208:211], v[12:15]
	v_mfma_f32_16x16x32_bf16 v[12:15], v[148:151], v[212:215], v[12:15]
	v_mfma_f32_16x16x32_bf16 v[56:59], v[152:155], v[184:187], v[56:59]
	v_mfma_f32_16x16x32_bf16 v[56:59], v[156:159], v[188:191], v[56:59]
	v_mfma_f32_16x16x32_bf16 v[40:43], v[152:155], v[192:195], v[40:43]
	v_mfma_f32_16x16x32_bf16 v[40:43], v[156:159], v[196:199], v[40:43]
	v_mfma_f32_16x16x32_bf16 v[24:27], v[152:155], v[200:203], v[24:27]
	v_mfma_f32_16x16x32_bf16 v[24:27], v[156:159], v[204:207], v[24:27]
	v_mfma_f32_16x16x32_bf16 v[8:11], v[152:155], v[208:211], v[8:11]
	v_mfma_f32_16x16x32_bf16 v[8:11], v[156:159], v[212:215], v[8:11]
	v_mfma_f32_16x16x32_bf16 v[52:55], v[168:171], v[184:187], v[52:55]
	v_mfma_f32_16x16x32_bf16 v[52:55], v[172:175], v[188:191], v[52:55]
	v_mfma_f32_16x16x32_bf16 v[36:39], v[168:171], v[192:195], v[36:39]
	v_mfma_f32_16x16x32_bf16 v[36:39], v[172:175], v[196:199], v[36:39]
	v_mfma_f32_16x16x32_bf16 v[20:23], v[168:171], v[200:203], v[20:23]
	v_mfma_f32_16x16x32_bf16 v[20:23], v[172:175], v[204:207], v[20:23]
	v_mfma_f32_16x16x32_bf16 v[4:7], v[168:171], v[208:211], v[4:7]
	v_mfma_f32_16x16x32_bf16 v[4:7], v[172:175], v[212:215], v[4:7]
	v_mfma_f32_16x16x32_bf16 v[48:51], v[176:179], v[184:187], v[48:51]
	v_mfma_f32_16x16x32_bf16 v[48:51], v[180:183], v[188:191], v[48:51]
	v_mfma_f32_16x16x32_bf16 v[32:35], v[176:179], v[192:195], v[32:35]
	v_mfma_f32_16x16x32_bf16 v[32:35], v[180:183], v[196:199], v[32:35]
	s_setprio 2
	s_barrier
	v_mfma_f32_16x16x32_bf16 v[16:19], v[176:179], v[200:203], v[16:19]
	v_mfma_f32_16x16x32_bf16 v[16:19], v[180:183], v[204:207], v[16:19]
	v_mfma_f32_16x16x32_bf16 v[0:3], v[176:179], v[208:211], v[0:3]
	v_mfma_f32_16x16x32_bf16 v[0:3], v[180:183], v[212:215], v[0:3]
	s_setprio 0
	s_add_i32 s66, 0, 0x18000
	s_add_i32 s67, 0, 0x1c000
	v_add_u32_e32 v156, s66, v162
	v_add_u32_e32 v167, s67, v162
	ds_read_b128 v[144:147], v156
	ds_read_b128 v[148:151], v156 offset:1024
	ds_read_b128 v[152:155], v156 offset:2048
	ds_read_b128 v[156:159], v156 offset:3072
	ds_read_b128 v[168:171], v167
	ds_read_b128 v[172:175], v167 offset:1024
	ds_read_b128 v[176:179], v167 offset:2048
	ds_read_b128 v[180:183], v167 offset:3072
	s_add_u32 s40, s40, 0x40000
	s_addc_u32 s41, s41, 0
	s_mov_b32 m0, s54
	v_lshl_add_u64 v[222:223], s[40:41], 0, v[134:135]
	ds_read_b128 v[184:187], v165 offset:32768
	ds_read_b128 v[188:191], v165 offset:33792
	ds_read_b128 v[192:195], v165 offset:34816
	ds_read_b128 v[196:199], v165 offset:35840
	ds_read_b128 v[200:203], v165 offset:36864
	ds_read_b128 v[204:207], v165 offset:37888
	ds_read_b128 v[208:211], v165 offset:38912
	ds_read_b128 v[212:215], v165 offset:39936
	global_load_lds_dwordx4 v[222:223], off
	s_mov_b32 m0, s55
	v_lshl_add_u64 v[222:223], s[40:41], 0, v[130:131]
	global_load_lds_dwordx4 v[222:223], off
	s_waitcnt vmcnt(8) lgkmcnt(0)
	s_barrier
	s_setprio 1
	v_mfma_f32_16x16x32_bf16 v[124:127], v[144:147], v[184:187], v[124:127]
	v_mfma_f32_16x16x32_bf16 v[124:127], v[148:151], v[188:191], v[124:127]
	v_mfma_f32_16x16x32_bf16 v[108:111], v[144:147], v[192:195], v[108:111]
	v_mfma_f32_16x16x32_bf16 v[108:111], v[148:151], v[196:199], v[108:111]
	v_mfma_f32_16x16x32_bf16 v[92:95], v[144:147], v[200:203], v[92:95]
	v_mfma_f32_16x16x32_bf16 v[92:95], v[148:151], v[204:207], v[92:95]
	v_mfma_f32_16x16x32_bf16 v[76:79], v[144:147], v[208:211], v[76:79]
	v_mfma_f32_16x16x32_bf16 v[76:79], v[148:151], v[212:215], v[76:79]
	v_mfma_f32_16x16x32_bf16 v[120:123], v[152:155], v[184:187], v[120:123]
	v_mfma_f32_16x16x32_bf16 v[120:123], v[156:159], v[188:191], v[120:123]
	v_mfma_f32_16x16x32_bf16 v[104:107], v[152:155], v[192:195], v[104:107]
	v_mfma_f32_16x16x32_bf16 v[104:107], v[156:159], v[196:199], v[104:107]
	v_mfma_f32_16x16x32_bf16 v[88:91], v[152:155], v[200:203], v[88:91]
	v_mfma_f32_16x16x32_bf16 v[88:91], v[156:159], v[204:207], v[88:91]
	v_mfma_f32_16x16x32_bf16 v[72:75], v[152:155], v[208:211], v[72:75]
	v_mfma_f32_16x16x32_bf16 v[72:75], v[156:159], v[212:215], v[72:75]
	v_mfma_f32_16x16x32_bf16 v[116:119], v[168:171], v[184:187], v[116:119]
	v_mfma_f32_16x16x32_bf16 v[116:119], v[172:175], v[188:191], v[116:119]
	v_mfma_f32_16x16x32_bf16 v[100:103], v[168:171], v[192:195], v[100:103]
	v_mfma_f32_16x16x32_bf16 v[100:103], v[172:175], v[196:199], v[100:103]
	v_mfma_f32_16x16x32_bf16 v[84:87], v[168:171], v[200:203], v[84:87]
	v_mfma_f32_16x16x32_bf16 v[84:87], v[172:175], v[204:207], v[84:87]
	v_mfma_f32_16x16x32_bf16 v[68:71], v[168:171], v[208:211], v[68:71]
	v_mfma_f32_16x16x32_bf16 v[68:71], v[172:175], v[212:215], v[68:71]
	v_mfma_f32_16x16x32_bf16 v[112:115], v[176:179], v[184:187], v[112:115]
	v_mfma_f32_16x16x32_bf16 v[112:115], v[180:183], v[188:191], v[112:115]
	v_mfma_f32_16x16x32_bf16 v[96:99], v[176:179], v[192:195], v[96:99]
	v_mfma_f32_16x16x32_bf16 v[96:99], v[180:183], v[196:199], v[96:99]
	s_setprio 2
	s_barrier
	v_mfma_f32_16x16x32_bf16 v[80:83], v[176:179], v[200:203], v[80:83]
	v_mfma_f32_16x16x32_bf16 v[80:83], v[180:183], v[204:207], v[80:83]
	v_mfma_f32_16x16x32_bf16 v[64:67], v[176:179], v[208:211], v[64:67]
	v_mfma_f32_16x16x32_bf16 v[64:67], v[180:183], v[212:215], v[64:67]
	s_setprio 0
	s_add_i32 s40, s66, s47
	v_lshl_add_u64 v[160:161], v[160:161], 0, s[16:17]
	s_mov_b32 m0, s40
	ds_read_b128 v[184:187], v165 offset:49152
	ds_read_b128 v[188:191], v165 offset:50176
	ds_read_b128 v[192:195], v165 offset:51200
	ds_read_b128 v[196:199], v165 offset:52224
	ds_read_b128 v[200:203], v165 offset:53248
	ds_read_b128 v[204:207], v165 offset:54272
	ds_read_b128 v[208:211], v165 offset:55296
	ds_read_b128 v[212:215], v165 offset:56320
	global_load_lds_dwordx4 v[160:161], off
	s_add_i32 m0, s40, 0x2000
	s_add_u32 s38, s38, 0x40080
	v_lshl_add_u64 v[160:161], v[216:217], 0, s[16:17]
	s_addc_u32 s39, s39, 0
	s_add_i32 s40, s67, s47
	global_load_lds_dwordx4 v[160:161], off
	s_mov_b32 m0, s40
	v_lshl_add_u64 v[160:161], s[38:39], 0, v[132:133]
	global_load_lds_dwordx4 v[160:161], off
	s_add_i32 m0, s40, 0x2000
	v_lshl_add_u64 v[160:161], s[38:39], 0, v[128:129]
	global_load_lds_dwordx4 v[160:161], off
	s_mov_b32 m0, s57
	v_lshl_add_u64 v[160:161], v[218:219], 0, s[16:17]
	global_load_lds_dwordx4 v[160:161], off
	s_mov_b32 m0, s58
	v_lshl_add_u64 v[160:161], v[220:221], 0, s[16:17]
	global_load_lds_dwordx4 v[160:161], off
	s_waitcnt vmcnt(8) lgkmcnt(0)
	s_barrier
	s_setprio 1
	v_mfma_f32_16x16x32_bf16 v[60:63], v[144:147], v[184:187], v[60:63]
	v_mfma_f32_16x16x32_bf16 v[60:63], v[148:151], v[188:191], v[60:63]
	v_mfma_f32_16x16x32_bf16 v[44:47], v[144:147], v[192:195], v[44:47]
	v_mfma_f32_16x16x32_bf16 v[44:47], v[148:151], v[196:199], v[44:47]
	v_mfma_f32_16x16x32_bf16 v[28:31], v[144:147], v[200:203], v[28:31]
	v_mfma_f32_16x16x32_bf16 v[28:31], v[148:151], v[204:207], v[28:31]
	v_mfma_f32_16x16x32_bf16 v[12:15], v[144:147], v[208:211], v[12:15]
	v_mfma_f32_16x16x32_bf16 v[12:15], v[148:151], v[212:215], v[12:15]
	v_mfma_f32_16x16x32_bf16 v[56:59], v[152:155], v[184:187], v[56:59]
	v_mfma_f32_16x16x32_bf16 v[56:59], v[156:159], v[188:191], v[56:59]
	v_mfma_f32_16x16x32_bf16 v[40:43], v[152:155], v[192:195], v[40:43]
	v_mfma_f32_16x16x32_bf16 v[40:43], v[156:159], v[196:199], v[40:43]
	v_mfma_f32_16x16x32_bf16 v[24:27], v[152:155], v[200:203], v[24:27]
	v_mfma_f32_16x16x32_bf16 v[24:27], v[156:159], v[204:207], v[24:27]
	v_mfma_f32_16x16x32_bf16 v[8:11], v[152:155], v[208:211], v[8:11]
	v_mfma_f32_16x16x32_bf16 v[8:11], v[156:159], v[212:215], v[8:11]
	v_mfma_f32_16x16x32_bf16 v[52:55], v[168:171], v[184:187], v[52:55]
	v_mfma_f32_16x16x32_bf16 v[52:55], v[172:175], v[188:191], v[52:55]
	v_mfma_f32_16x16x32_bf16 v[36:39], v[168:171], v[192:195], v[36:39]
	v_mfma_f32_16x16x32_bf16 v[36:39], v[172:175], v[196:199], v[36:39]
	v_mfma_f32_16x16x32_bf16 v[20:23], v[168:171], v[200:203], v[20:23]
	v_mfma_f32_16x16x32_bf16 v[20:23], v[172:175], v[204:207], v[20:23]
	v_mfma_f32_16x16x32_bf16 v[4:7], v[168:171], v[208:211], v[4:7]
	v_mfma_f32_16x16x32_bf16 v[4:7], v[172:175], v[212:215], v[4:7]
	v_mfma_f32_16x16x32_bf16 v[48:51], v[176:179], v[184:187], v[48:51]
	v_mfma_f32_16x16x32_bf16 v[48:51], v[180:183], v[188:191], v[48:51]
	v_mfma_f32_16x16x32_bf16 v[32:35], v[176:179], v[192:195], v[32:35]
	v_mfma_f32_16x16x32_bf16 v[32:35], v[180:183], v[196:199], v[32:35]
	s_setprio 2
	s_barrier
	v_mfma_f32_16x16x32_bf16 v[16:19], v[176:179], v[200:203], v[16:19]
	v_mfma_f32_16x16x32_bf16 v[16:19], v[180:183], v[204:207], v[16:19]
	v_mfma_f32_16x16x32_bf16 v[0:3], v[176:179], v[208:211], v[0:3]
	v_mfma_f32_16x16x32_bf16 v[0:3], v[180:183], v[212:215], v[0:3]
	s_setprio 0
	s_add_i32 s65, s65, 2
	s_add_u32 s36, s36, 0x100
	s_addc_u32 s37, s37, 0
	s_add_u32 s63, s63, 0x100
	s_addc_u32 s64, s64, 0
	s_cmp_gt_u32 s65, 13
	s_cbranch_scc0 .LBB0_784

.LBB0_865:
	s_add_u32 s62, s28, 0x100
	s_addc_u32 s63, s29, 0
	s_mov_b32 s64, -2
	ds_read_b128 v[120:123], v233
	ds_read_b128 v[124:127], v233 offset:1024
	ds_read_b128 v[136:139], v233 offset:2048
	ds_read_b128 v[140:143], v233 offset:3072
	ds_read_b128 v[144:147], v234
	ds_read_b128 v[148:151], v234 offset:1024
	ds_read_b128 v[152:155], v234 offset:2048
	ds_read_b128 v[156:159], v234 offset:3072
	s_add_u32 s28, s26, 0x100
	s_addc_u32 s29, s27, 0
	s_cmp_eq_u32 s64, 40
	s_cselect_b32 s37, s7, s29
	s_cselect_b32 s36, s6, s28
	s_cselect_b32 s31, s25, s63
	s_cselect_b32 s30, s24, s62
	v_lshl_add_u64 v[208:209], s[26:27], 0, v[192:193]
	s_add_i32 m0, s44, 0xc000
	ds_read_b128 v[160:163], v235
	ds_read_b128 v[164:167], v235 offset:1024
	ds_read_b128 v[168:171], v235 offset:2048
	ds_read_b128 v[172:175], v235 offset:3072
	ds_read_b128 v[176:179], v235 offset:4096
	ds_read_b128 v[180:183], v235 offset:5120
	ds_read_b128 v[200:203], v235 offset:6144
	ds_read_b128 v[204:207], v235 offset:7168
	global_load_lds_dwordx4 v[208:209], off
	s_add_i32 m0, s44, 0xe000
	v_lshl_add_u64 v[208:209], s[26:27], 0, v[194:195]
	global_load_lds_dwordx4 v[208:209], off
	s_waitcnt vmcnt(8) lgkmcnt(0)
	s_barrier
	s_setprio 1
	v_mfma_f32_16x16x32_bf16 v[132:135], v[120:123], v[160:163], 0
	v_mfma_f32_16x16x32_bf16 v[132:135], v[124:127], v[164:167], v[132:135]
	v_mfma_f32_16x16x32_bf16 v[108:111], v[120:123], v[168:171], 0
	v_mfma_f32_16x16x32_bf16 v[108:111], v[124:127], v[172:175], v[108:111]
	v_mfma_f32_16x16x32_bf16 v[92:95], v[120:123], v[176:179], 0
	v_mfma_f32_16x16x32_bf16 v[92:95], v[124:127], v[180:183], v[92:95]
	v_mfma_f32_16x16x32_bf16 v[76:79], v[120:123], v[200:203], 0
	v_mfma_f32_16x16x32_bf16 v[76:79], v[124:127], v[204:207], v[76:79]
	v_mfma_f32_16x16x32_bf16 v[128:131], v[136:139], v[160:163], 0
	v_mfma_f32_16x16x32_bf16 v[128:131], v[140:143], v[164:167], v[128:131]
	v_mfma_f32_16x16x32_bf16 v[104:107], v[136:139], v[168:171], 0
	v_mfma_f32_16x16x32_bf16 v[104:107], v[140:143], v[172:175], v[104:107]
	v_mfma_f32_16x16x32_bf16 v[88:91], v[136:139], v[176:179], 0
	v_mfma_f32_16x16x32_bf16 v[88:91], v[140:143], v[180:183], v[88:91]
	v_mfma_f32_16x16x32_bf16 v[72:75], v[136:139], v[200:203], 0
	v_mfma_f32_16x16x32_bf16 v[72:75], v[140:143], v[204:207], v[72:75]
	v_mfma_f32_16x16x32_bf16 v[116:119], v[144:147], v[160:163], 0
	v_mfma_f32_16x16x32_bf16 v[116:119], v[148:151], v[164:167], v[116:119]
	v_mfma_f32_16x16x32_bf16 v[100:103], v[144:147], v[168:171], 0
	v_mfma_f32_16x16x32_bf16 v[100:103], v[148:151], v[172:175], v[100:103]
	v_mfma_f32_16x16x32_bf16 v[84:87], v[144:147], v[176:179], 0
	v_mfma_f32_16x16x32_bf16 v[84:87], v[148:151], v[180:183], v[84:87]
	v_mfma_f32_16x16x32_bf16 v[68:71], v[144:147], v[200:203], 0
	v_mfma_f32_16x16x32_bf16 v[68:71], v[148:151], v[204:207], v[68:71]
	v_mfma_f32_16x16x32_bf16 v[112:115], v[152:155], v[160:163], 0
	v_mfma_f32_16x16x32_bf16 v[112:115], v[156:159], v[164:167], v[112:115]
	v_mfma_f32_16x16x32_bf16 v[96:99], v[152:155], v[168:171], 0
	v_mfma_f32_16x16x32_bf16 v[96:99], v[156:159], v[172:175], v[96:99]
	s_setprio 2
	s_barrier
	v_mfma_f32_16x16x32_bf16 v[80:83], v[152:155], v[176:179], 0
	v_mfma_f32_16x16x32_bf16 v[80:83], v[156:159], v[180:183], v[80:83]
	v_mfma_f32_16x16x32_bf16 v[64:67], v[152:155], v[200:203], 0
	v_mfma_f32_16x16x32_bf16 v[64:67], v[156:159], v[204:207], v[64:67]
	s_setprio 0
	s_add_i32 s26, s56, s43
	v_lshl_add_u64 v[208:209], s[30:31], 0, v[186:187]
	s_mov_b32 m0, s26
	ds_read_b128 v[160:163], v235 offset:16384
	ds_read_b128 v[164:167], v235 offset:17408
	ds_read_b128 v[168:171], v235 offset:18432
	ds_read_b128 v[172:175], v235 offset:19456
	ds_read_b128 v[176:179], v235 offset:20480
	ds_read_b128 v[180:183], v235 offset:21504
	ds_read_b128 v[200:203], v235 offset:22528
	ds_read_b128 v[204:207], v235 offset:23552
	global_load_lds_dwordx4 v[208:209], off
	s_add_i32 m0, s26, 0x2000
	s_add_u32 s26, s30, 0xb0000
	v_lshl_add_u64 v[210:211], s[30:31], 0, v[190:191]
	s_addc_u32 s27, s31, 0
	s_add_i32 s65, s57, s43
	global_load_lds_dwordx4 v[210:211], off
	v_lshl_add_u64 v[212:213], s[26:27], 0, v[186:187]
	s_mov_b32 m0, s65
	v_lshl_add_u64 v[214:215], s[36:37], 0, v[188:189]
	global_load_lds_dwordx4 v[212:213], off
	s_add_i32 m0, s65, 0x2000
	v_lshl_add_u64 v[212:213], s[26:27], 0, v[190:191]
	global_load_lds_dwordx4 v[212:213], off
	s_mov_b32 m0, s44
	v_lshl_add_u64 v[212:213], s[36:37], 0, v[184:185]
	global_load_lds_dwordx4 v[212:213], off
	s_mov_b32 m0, s45
	s_nop 0
	global_load_lds_dwordx4 v[214:215], off
	s_waitcnt vmcnt(8) lgkmcnt(0)
	s_barrier
	s_setprio 1
	v_mfma_f32_16x16x32_bf16 v[60:63], v[120:123], v[160:163], 0
	v_mfma_f32_16x16x32_bf16 v[60:63], v[124:127], v[164:167], v[60:63]
	v_mfma_f32_16x16x32_bf16 v[44:47], v[120:123], v[168:171], 0
	v_mfma_f32_16x16x32_bf16 v[44:47], v[124:127], v[172:175], v[44:47]
	v_mfma_f32_16x16x32_bf16 v[28:31], v[120:123], v[176:179], 0
	v_mfma_f32_16x16x32_bf16 v[28:31], v[124:127], v[180:183], v[28:31]
	v_mfma_f32_16x16x32_bf16 v[12:15], v[120:123], v[200:203], 0
	v_mfma_f32_16x16x32_bf16 v[12:15], v[124:127], v[204:207], v[12:15]
	v_mfma_f32_16x16x32_bf16 v[56:59], v[136:139], v[160:163], 0
	v_mfma_f32_16x16x32_bf16 v[56:59], v[140:143], v[164:167], v[56:59]
	v_mfma_f32_16x16x32_bf16 v[40:43], v[136:139], v[168:171], 0
	v_mfma_f32_16x16x32_bf16 v[40:43], v[140:143], v[172:175], v[40:43]
	v_mfma_f32_16x16x32_bf16 v[24:27], v[136:139], v[176:179], 0
	v_mfma_f32_16x16x32_bf16 v[24:27], v[140:143], v[180:183], v[24:27]
	v_mfma_f32_16x16x32_bf16 v[8:11], v[136:139], v[200:203], 0
	v_mfma_f32_16x16x32_bf16 v[8:11], v[140:143], v[204:207], v[8:11]
	v_mfma_f32_16x16x32_bf16 v[52:55], v[144:147], v[160:163], 0
	v_mfma_f32_16x16x32_bf16 v[52:55], v[148:151], v[164:167], v[52:55]
	v_mfma_f32_16x16x32_bf16 v[36:39], v[144:147], v[168:171], 0
	v_mfma_f32_16x16x32_bf16 v[36:39], v[148:151], v[172:175], v[36:39]
	v_mfma_f32_16x16x32_bf16 v[20:23], v[144:147], v[176:179], 0
	v_mfma_f32_16x16x32_bf16 v[20:23], v[148:151], v[180:183], v[20:23]
	v_mfma_f32_16x16x32_bf16 v[4:7], v[144:147], v[200:203], 0
	v_mfma_f32_16x16x32_bf16 v[4:7], v[148:151], v[204:207], v[4:7]
	v_mfma_f32_16x16x32_bf16 v[48:51], v[152:155], v[160:163], 0
	v_mfma_f32_16x16x32_bf16 v[48:51], v[156:159], v[164:167], v[48:51]
	v_mfma_f32_16x16x32_bf16 v[32:35], v[152:155], v[168:171], 0
	v_mfma_f32_16x16x32_bf16 v[32:35], v[156:159], v[172:175], v[32:35]
	s_setprio 2
	s_barrier
	v_mfma_f32_16x16x32_bf16 v[16:19], v[152:155], v[176:179], 0
	v_mfma_f32_16x16x32_bf16 v[16:19], v[156:159], v[180:183], v[16:19]
	v_mfma_f32_16x16x32_bf16 v[0:3], v[152:155], v[200:203], 0
	v_mfma_f32_16x16x32_bf16 v[0:3], v[156:159], v[204:207], v[0:3]
	s_setprio 0
	s_add_i32 s65, 0, 0x18000
	s_add_i32 s66, 0, 0x1c000
	v_add_u32_e32 v140, s65, v232
	v_add_u32_e32 v156, s66, v232
	ds_read_b128 v[120:123], v140
	ds_read_b128 v[124:127], v140 offset:1024
	ds_read_b128 v[136:139], v140 offset:2048
	ds_read_b128 v[140:143], v140 offset:3072
	ds_read_b128 v[144:147], v156
	ds_read_b128 v[148:151], v156 offset:1024
	ds_read_b128 v[152:155], v156 offset:2048
	ds_read_b128 v[156:159], v156 offset:3072
	s_add_u32 s26, s36, 0xb0000
	s_addc_u32 s27, s37, 0
	s_mov_b32 m0, s46
	v_lshl_add_u64 v[216:217], s[26:27], 0, v[184:185]
	ds_read_b128 v[160:163], v235 offset:32768
	ds_read_b128 v[164:167], v235 offset:33792
	ds_read_b128 v[168:171], v235 offset:34816
	ds_read_b128 v[172:175], v235 offset:35840
	ds_read_b128 v[176:179], v235 offset:36864
	ds_read_b128 v[180:183], v235 offset:37888
	ds_read_b128 v[200:203], v235 offset:38912
	ds_read_b128 v[204:207], v235 offset:39936
	global_load_lds_dwordx4 v[216:217], off
	s_mov_b32 m0, s47
	v_lshl_add_u64 v[216:217], s[26:27], 0, v[188:189]
	global_load_lds_dwordx4 v[216:217], off
	s_waitcnt vmcnt(8) lgkmcnt(0)
	s_barrier
	s_setprio 1
	v_mfma_f32_16x16x32_bf16 v[132:135], v[120:123], v[160:163], v[132:135]
	v_mfma_f32_16x16x32_bf16 v[132:135], v[124:127], v[164:167], v[132:135]
	v_mfma_f32_16x16x32_bf16 v[108:111], v[120:123], v[168:171], v[108:111]
	v_mfma_f32_16x16x32_bf16 v[108:111], v[124:127], v[172:175], v[108:111]
	v_mfma_f32_16x16x32_bf16 v[92:95], v[120:123], v[176:179], v[92:95]
	v_mfma_f32_16x16x32_bf16 v[92:95], v[124:127], v[180:183], v[92:95]
	v_mfma_f32_16x16x32_bf16 v[76:79], v[120:123], v[200:203], v[76:79]
	v_mfma_f32_16x16x32_bf16 v[76:79], v[124:127], v[204:207], v[76:79]
	v_mfma_f32_16x16x32_bf16 v[128:131], v[136:139], v[160:163], v[128:131]
	v_mfma_f32_16x16x32_bf16 v[128:131], v[140:143], v[164:167], v[128:131]
	v_mfma_f32_16x16x32_bf16 v[104:107], v[136:139], v[168:171], v[104:107]
	v_mfma_f32_16x16x32_bf16 v[104:107], v[140:143], v[172:175], v[104:107]
	v_mfma_f32_16x16x32_bf16 v[88:91], v[136:139], v[176:179], v[88:91]
	v_mfma_f32_16x16x32_bf16 v[88:91], v[140:143], v[180:183], v[88:91]
	v_mfma_f32_16x16x32_bf16 v[72:75], v[136:139], v[200:203], v[72:75]
	v_mfma_f32_16x16x32_bf16 v[72:75], v[140:143], v[204:207], v[72:75]
	v_mfma_f32_16x16x32_bf16 v[116:119], v[144:147], v[160:163], v[116:119]
	v_mfma_f32_16x16x32_bf16 v[116:119], v[148:151], v[164:167], v[116:119]
	v_mfma_f32_16x16x32_bf16 v[100:103], v[144:147], v[168:171], v[100:103]
	v_mfma_f32_16x16x32_bf16 v[100:103], v[148:151], v[172:175], v[100:103]
	v_mfma_f32_16x16x32_bf16 v[84:87], v[144:147], v[176:179], v[84:87]
	v_mfma_f32_16x16x32_bf16 v[84:87], v[148:151], v[180:183], v[84:87]
	v_mfma_f32_16x16x32_bf16 v[68:71], v[144:147], v[200:203], v[68:71]
	v_mfma_f32_16x16x32_bf16 v[68:71], v[148:151], v[204:207], v[68:71]
	v_mfma_f32_16x16x32_bf16 v[112:115], v[152:155], v[160:163], v[112:115]
	v_mfma_f32_16x16x32_bf16 v[112:115], v[156:159], v[164:167], v[112:115]
	v_mfma_f32_16x16x32_bf16 v[96:99], v[152:155], v[168:171], v[96:99]
	v_mfma_f32_16x16x32_bf16 v[96:99], v[156:159], v[172:175], v[96:99]
	s_setprio 2
	s_barrier
	v_mfma_f32_16x16x32_bf16 v[80:83], v[152:155], v[176:179], v[80:83]
	v_mfma_f32_16x16x32_bf16 v[80:83], v[156:159], v[180:183], v[80:83]
	v_mfma_f32_16x16x32_bf16 v[64:67], v[152:155], v[200:203], v[64:67]
	v_mfma_f32_16x16x32_bf16 v[64:67], v[156:159], v[204:207], v[64:67]
	s_setprio 0
	s_add_i32 s26, s65, s43
	v_lshl_add_u64 v[208:209], v[208:209], 0, s[20:21]
	s_mov_b32 m0, s26
	ds_read_b128 v[160:163], v235 offset:49152
	ds_read_b128 v[164:167], v235 offset:50176
	ds_read_b128 v[168:171], v235 offset:51200
	ds_read_b128 v[172:175], v235 offset:52224
	ds_read_b128 v[176:179], v235 offset:53248
	ds_read_b128 v[180:183], v235 offset:54272
	ds_read_b128 v[200:203], v235 offset:55296
	ds_read_b128 v[204:207], v235 offset:56320
	global_load_lds_dwordx4 v[208:209], off
	s_add_i32 m0, s26, 0x2000
	s_add_u32 s26, s30, 0xb0080
	v_lshl_add_u64 v[208:209], v[210:211], 0, s[20:21]
	s_addc_u32 s27, s31, 0
	s_add_i32 s30, s66, s43
	global_load_lds_dwordx4 v[208:209], off
	s_mov_b32 m0, s30
	v_lshl_add_u64 v[208:209], s[26:27], 0, v[186:187]
	global_load_lds_dwordx4 v[208:209], off
	s_add_i32 m0, s30, 0x2000
	v_lshl_add_u64 v[208:209], s[26:27], 0, v[190:191]
	global_load_lds_dwordx4 v[208:209], off
	s_mov_b32 m0, s49
	v_lshl_add_u64 v[208:209], v[212:213], 0, s[20:21]
	global_load_lds_dwordx4 v[208:209], off
	s_mov_b32 m0, s50
	v_lshl_add_u64 v[208:209], v[214:215], 0, s[20:21]
	global_load_lds_dwordx4 v[208:209], off
	s_waitcnt vmcnt(8) lgkmcnt(0)
	s_barrier
	s_setprio 1
	v_mfma_f32_16x16x32_bf16 v[60:63], v[120:123], v[160:163], v[60:63]
	v_mfma_f32_16x16x32_bf16 v[60:63], v[124:127], v[164:167], v[60:63]
	v_mfma_f32_16x16x32_bf16 v[44:47], v[120:123], v[168:171], v[44:47]
	v_mfma_f32_16x16x32_bf16 v[44:47], v[124:127], v[172:175], v[44:47]
	v_mfma_f32_16x16x32_bf16 v[28:31], v[120:123], v[176:179], v[28:31]
	v_mfma_f32_16x16x32_bf16 v[28:31], v[124:127], v[180:183], v[28:31]
	v_mfma_f32_16x16x32_bf16 v[12:15], v[120:123], v[200:203], v[12:15]
	v_mfma_f32_16x16x32_bf16 v[12:15], v[124:127], v[204:207], v[12:15]
	v_mfma_f32_16x16x32_bf16 v[56:59], v[136:139], v[160:163], v[56:59]
	v_mfma_f32_16x16x32_bf16 v[56:59], v[140:143], v[164:167], v[56:59]
	v_mfma_f32_16x16x32_bf16 v[40:43], v[136:139], v[168:171], v[40:43]
	v_mfma_f32_16x16x32_bf16 v[40:43], v[140:143], v[172:175], v[40:43]
	v_mfma_f32_16x16x32_bf16 v[24:27], v[136:139], v[176:179], v[24:27]
	v_mfma_f32_16x16x32_bf16 v[24:27], v[140:143], v[180:183], v[24:27]
	v_mfma_f32_16x16x32_bf16 v[8:11], v[136:139], v[200:203], v[8:11]
	v_mfma_f32_16x16x32_bf16 v[8:11], v[140:143], v[204:207], v[8:11]
	v_mfma_f32_16x16x32_bf16 v[52:55], v[144:147], v[160:163], v[52:55]
	v_mfma_f32_16x16x32_bf16 v[52:55], v[148:151], v[164:167], v[52:55]
	v_mfma_f32_16x16x32_bf16 v[36:39], v[144:147], v[168:171], v[36:39]
	v_mfma_f32_16x16x32_bf16 v[36:39], v[148:151], v[172:175], v[36:39]
	v_mfma_f32_16x16x32_bf16 v[20:23], v[144:147], v[176:179], v[20:23]
	v_mfma_f32_16x16x32_bf16 v[20:23], v[148:151], v[180:183], v[20:23]
	v_mfma_f32_16x16x32_bf16 v[4:7], v[144:147], v[200:203], v[4:7]
	v_mfma_f32_16x16x32_bf16 v[4:7], v[148:151], v[204:207], v[4:7]
	v_mfma_f32_16x16x32_bf16 v[48:51], v[152:155], v[160:163], v[48:51]
	v_mfma_f32_16x16x32_bf16 v[48:51], v[156:159], v[164:167], v[48:51]
	v_mfma_f32_16x16x32_bf16 v[32:35], v[152:155], v[168:171], v[32:35]
	v_mfma_f32_16x16x32_bf16 v[32:35], v[156:159], v[172:175], v[32:35]
	s_setprio 2
	s_barrier
	v_mfma_f32_16x16x32_bf16 v[16:19], v[152:155], v[176:179], v[16:19]
	v_mfma_f32_16x16x32_bf16 v[16:19], v[156:159], v[180:183], v[16:19]
	v_mfma_f32_16x16x32_bf16 v[0:3], v[152:155], v[200:203], v[0:3]
	v_mfma_f32_16x16x32_bf16 v[0:3], v[156:159], v[204:207], v[0:3]
	s_setprio 0
	s_add_i32 s64, s64, 2
	s_add_u32 s62, s62, 0x100
	s_addc_u32 s63, s63, 0
	s_cmp_gt_u32 s64, 41
	s_mov_b64 s[26:27], s[28:29]
.LBB0_866:
	ds_read_b128 v[120:123], v233
	ds_read_b128 v[124:127], v233 offset:1024
	ds_read_b128 v[136:139], v233 offset:2048
	ds_read_b128 v[140:143], v233 offset:3072
	ds_read_b128 v[144:147], v234
	ds_read_b128 v[148:151], v234 offset:1024
	ds_read_b128 v[152:155], v234 offset:2048
	ds_read_b128 v[156:159], v234 offset:3072
	s_add_u32 s28, s26, 0x100
	s_addc_u32 s29, s27, 0
	s_cmp_eq_u32 s64, 40
	s_cselect_b32 s37, s7, s29
	s_cselect_b32 s36, s6, s28
	s_cselect_b32 s31, s25, s63
	s_cselect_b32 s30, s24, s62
	v_lshl_add_u64 v[208:209], s[26:27], 0, v[192:193]
	s_add_i32 m0, s44, 0xc000
	ds_read_b128 v[160:163], v235
	ds_read_b128 v[164:167], v235 offset:1024
	ds_read_b128 v[168:171], v235 offset:2048
	ds_read_b128 v[172:175], v235 offset:3072
	ds_read_b128 v[176:179], v235 offset:4096
	ds_read_b128 v[180:183], v235 offset:5120
	ds_read_b128 v[200:203], v235 offset:6144
	ds_read_b128 v[204:207], v235 offset:7168
	global_load_lds_dwordx4 v[208:209], off
	s_add_i32 m0, s44, 0xe000
	v_lshl_add_u64 v[208:209], s[26:27], 0, v[194:195]
	global_load_lds_dwordx4 v[208:209], off
	s_waitcnt vmcnt(8) lgkmcnt(0)
	s_barrier
	s_setprio 1
	v_mfma_f32_16x16x32_bf16 v[132:135], v[120:123], v[160:163], v[132:135]
	v_mfma_f32_16x16x32_bf16 v[132:135], v[124:127], v[164:167], v[132:135]
	v_mfma_f32_16x16x32_bf16 v[108:111], v[120:123], v[168:171], v[108:111]
	v_mfma_f32_16x16x32_bf16 v[108:111], v[124:127], v[172:175], v[108:111]
	v_mfma_f32_16x16x32_bf16 v[92:95], v[120:123], v[176:179], v[92:95]
	v_mfma_f32_16x16x32_bf16 v[92:95], v[124:127], v[180:183], v[92:95]
	v_mfma_f32_16x16x32_bf16 v[76:79], v[120:123], v[200:203], v[76:79]
	v_mfma_f32_16x16x32_bf16 v[76:79], v[124:127], v[204:207], v[76:79]
	v_mfma_f32_16x16x32_bf16 v[128:131], v[136:139], v[160:163], v[128:131]
	v_mfma_f32_16x16x32_bf16 v[128:131], v[140:143], v[164:167], v[128:131]
	v_mfma_f32_16x16x32_bf16 v[104:107], v[136:139], v[168:171], v[104:107]
	v_mfma_f32_16x16x32_bf16 v[104:107], v[140:143], v[172:175], v[104:107]
	v_mfma_f32_16x16x32_bf16 v[88:91], v[136:139], v[176:179], v[88:91]
	v_mfma_f32_16x16x32_bf16 v[88:91], v[140:143], v[180:183], v[88:91]
	v_mfma_f32_16x16x32_bf16 v[72:75], v[136:139], v[200:203], v[72:75]
	v_mfma_f32_16x16x32_bf16 v[72:75], v[140:143], v[204:207], v[72:75]
	v_mfma_f32_16x16x32_bf16 v[116:119], v[144:147], v[160:163], v[116:119]
	v_mfma_f32_16x16x32_bf16 v[116:119], v[148:151], v[164:167], v[116:119]
	v_mfma_f32_16x16x32_bf16 v[100:103], v[144:147], v[168:171], v[100:103]
	v_mfma_f32_16x16x32_bf16 v[100:103], v[148:151], v[172:175], v[100:103]
	v_mfma_f32_16x16x32_bf16 v[84:87], v[144:147], v[176:179], v[84:87]
	v_mfma_f32_16x16x32_bf16 v[84:87], v[148:151], v[180:183], v[84:87]
	v_mfma_f32_16x16x32_bf16 v[68:71], v[144:147], v[200:203], v[68:71]
	v_mfma_f32_16x16x32_bf16 v[68:71], v[148:151], v[204:207], v[68:71]
	v_mfma_f32_16x16x32_bf16 v[112:115], v[152:155], v[160:163], v[112:115]
	v_mfma_f32_16x16x32_bf16 v[112:115], v[156:159], v[164:167], v[112:115]
	v_mfma_f32_16x16x32_bf16 v[96:99], v[152:155], v[168:171], v[96:99]
	v_mfma_f32_16x16x32_bf16 v[96:99], v[156:159], v[172:175], v[96:99]
	s_setprio 2
	s_barrier
	v_mfma_f32_16x16x32_bf16 v[80:83], v[152:155], v[176:179], v[80:83]
	v_mfma_f32_16x16x32_bf16 v[80:83], v[156:159], v[180:183], v[80:83]
	v_mfma_f32_16x16x32_bf16 v[64:67], v[152:155], v[200:203], v[64:67]
	v_mfma_f32_16x16x32_bf16 v[64:67], v[156:159], v[204:207], v[64:67]
	s_setprio 0
	s_add_i32 s26, s56, s43
	v_lshl_add_u64 v[208:209], s[30:31], 0, v[186:187]
	s_mov_b32 m0, s26
	ds_read_b128 v[160:163], v235 offset:16384
	ds_read_b128 v[164:167], v235 offset:17408
	ds_read_b128 v[168:171], v235 offset:18432
	ds_read_b128 v[172:175], v235 offset:19456
	ds_read_b128 v[176:179], v235 offset:20480
	ds_read_b128 v[180:183], v235 offset:21504
	ds_read_b128 v[200:203], v235 offset:22528
	ds_read_b128 v[204:207], v235 offset:23552
	global_load_lds_dwordx4 v[208:209], off
	s_add_i32 m0, s26, 0x2000
	s_add_u32 s26, s30, 0xb0000
	v_lshl_add_u64 v[210:211], s[30:31], 0, v[190:191]
	s_addc_u32 s27, s31, 0
	s_add_i32 s65, s57, s43
	global_load_lds_dwordx4 v[210:211], off
	v_lshl_add_u64 v[212:213], s[26:27], 0, v[186:187]
	s_mov_b32 m0, s65
	v_lshl_add_u64 v[214:215], s[36:37], 0, v[188:189]
	global_load_lds_dwordx4 v[212:213], off
	s_add_i32 m0, s65, 0x2000
	v_lshl_add_u64 v[212:213], s[26:27], 0, v[190:191]
	global_load_lds_dwordx4 v[212:213], off
	s_mov_b32 m0, s44
	v_lshl_add_u64 v[212:213], s[36:37], 0, v[184:185]
	global_load_lds_dwordx4 v[212:213], off
	s_mov_b32 m0, s45
	s_nop 0
	global_load_lds_dwordx4 v[214:215], off
	s_waitcnt vmcnt(8) lgkmcnt(0)
	s_barrier
	s_setprio 1
	v_mfma_f32_16x16x32_bf16 v[60:63], v[120:123], v[160:163], v[60:63]
	v_mfma_f32_16x16x32_bf16 v[60:63], v[124:127], v[164:167], v[60:63]
	v_mfma_f32_16x16x32_bf16 v[44:47], v[120:123], v[168:171], v[44:47]
	v_mfma_f32_16x16x32_bf16 v[44:47], v[124:127], v[172:175], v[44:47]
	v_mfma_f32_16x16x32_bf16 v[28:31], v[120:123], v[176:179], v[28:31]
	v_mfma_f32_16x16x32_bf16 v[28:31], v[124:127], v[180:183], v[28:31]
	v_mfma_f32_16x16x32_bf16 v[12:15], v[120:123], v[200:203], v[12:15]
	v_mfma_f32_16x16x32_bf16 v[12:15], v[124:127], v[204:207], v[12:15]
	v_mfma_f32_16x16x32_bf16 v[56:59], v[136:139], v[160:163], v[56:59]
	v_mfma_f32_16x16x32_bf16 v[56:59], v[140:143], v[164:167], v[56:59]
	v_mfma_f32_16x16x32_bf16 v[40:43], v[136:139], v[168:171], v[40:43]
	v_mfma_f32_16x16x32_bf16 v[40:43], v[140:143], v[172:175], v[40:43]
	v_mfma_f32_16x16x32_bf16 v[24:27], v[136:139], v[176:179], v[24:27]
	v_mfma_f32_16x16x32_bf16 v[24:27], v[140:143], v[180:183], v[24:27]
	v_mfma_f32_16x16x32_bf16 v[8:11], v[136:139], v[200:203], v[8:11]
	v_mfma_f32_16x16x32_bf16 v[8:11], v[140:143], v[204:207], v[8:11]
	v_mfma_f32_16x16x32_bf16 v[52:55], v[144:147], v[160:163], v[52:55]
	v_mfma_f32_16x16x32_bf16 v[52:55], v[148:151], v[164:167], v[52:55]
	v_mfma_f32_16x16x32_bf16 v[36:39], v[144:147], v[168:171], v[36:39]
	v_mfma_f32_16x16x32_bf16 v[36:39], v[148:151], v[172:175], v[36:39]
	v_mfma_f32_16x16x32_bf16 v[20:23], v[144:147], v[176:179], v[20:23]
	v_mfma_f32_16x16x32_bf16 v[20:23], v[148:151], v[180:183], v[20:23]
	v_mfma_f32_16x16x32_bf16 v[4:7], v[144:147], v[200:203], v[4:7]
	v_mfma_f32_16x16x32_bf16 v[4:7], v[148:151], v[204:207], v[4:7]
	v_mfma_f32_16x16x32_bf16 v[48:51], v[152:155], v[160:163], v[48:51]
	v_mfma_f32_16x16x32_bf16 v[48:51], v[156:159], v[164:167], v[48:51]
	v_mfma_f32_16x16x32_bf16 v[32:35], v[152:155], v[168:171], v[32:35]
	v_mfma_f32_16x16x32_bf16 v[32:35], v[156:159], v[172:175], v[32:35]
	s_setprio 2
	s_barrier
	v_mfma_f32_16x16x32_bf16 v[16:19], v[152:155], v[176:179], v[16:19]
	v_mfma_f32_16x16x32_bf16 v[16:19], v[156:159], v[180:183], v[16:19]
	v_mfma_f32_16x16x32_bf16 v[0:3], v[152:155], v[200:203], v[0:3]
	v_mfma_f32_16x16x32_bf16 v[0:3], v[156:159], v[204:207], v[0:3]
	s_setprio 0
	s_add_i32 s65, 0, 0x18000
	s_add_i32 s66, 0, 0x1c000
	v_add_u32_e32 v140, s65, v232
	v_add_u32_e32 v156, s66, v232
	ds_read_b128 v[120:123], v140
	ds_read_b128 v[124:127], v140 offset:1024
	ds_read_b128 v[136:139], v140 offset:2048
	ds_read_b128 v[140:143], v140 offset:3072
	ds_read_b128 v[144:147], v156
	ds_read_b128 v[148:151], v156 offset:1024
	ds_read_b128 v[152:155], v156 offset:2048
	ds_read_b128 v[156:159], v156 offset:3072
	s_add_u32 s26, s36, 0xb0000
	s_addc_u32 s27, s37, 0
	s_mov_b32 m0, s46
	v_lshl_add_u64 v[216:217], s[26:27], 0, v[184:185]
	ds_read_b128 v[160:163], v235 offset:32768
	ds_read_b128 v[164:167], v235 offset:33792
	ds_read_b128 v[168:171], v235 offset:34816
	ds_read_b128 v[172:175], v235 offset:35840
	ds_read_b128 v[176:179], v235 offset:36864
	ds_read_b128 v[180:183], v235 offset:37888
	ds_read_b128 v[200:203], v235 offset:38912
	ds_read_b128 v[204:207], v235 offset:39936
	global_load_lds_dwordx4 v[216:217], off
	s_mov_b32 m0, s47
	v_lshl_add_u64 v[216:217], s[26:27], 0, v[188:189]
	global_load_lds_dwordx4 v[216:217], off
	s_waitcnt vmcnt(8) lgkmcnt(0)
	s_barrier
	s_setprio 1
	v_mfma_f32_16x16x32_bf16 v[132:135], v[120:123], v[160:163], v[132:135]
	v_mfma_f32_16x16x32_bf16 v[132:135], v[124:127], v[164:167], v[132:135]
	v_mfma_f32_16x16x32_bf16 v[108:111], v[120:123], v[168:171], v[108:111]
	v_mfma_f32_16x16x32_bf16 v[108:111], v[124:127], v[172:175], v[108:111]
	v_mfma_f32_16x16x32_bf16 v[92:95], v[120:123], v[176:179], v[92:95]
	v_mfma_f32_16x16x32_bf16 v[92:95], v[124:127], v[180:183], v[92:95]
	v_mfma_f32_16x16x32_bf16 v[76:79], v[120:123], v[200:203], v[76:79]
	v_mfma_f32_16x16x32_bf16 v[76:79], v[124:127], v[204:207], v[76:79]
	v_mfma_f32_16x16x32_bf16 v[128:131], v[136:139], v[160:163], v[128:131]
	v_mfma_f32_16x16x32_bf16 v[128:131], v[140:143], v[164:167], v[128:131]
	v_mfma_f32_16x16x32_bf16 v[104:107], v[136:139], v[168:171], v[104:107]
	v_mfma_f32_16x16x32_bf16 v[104:107], v[140:143], v[172:175], v[104:107]
	v_mfma_f32_16x16x32_bf16 v[88:91], v[136:139], v[176:179], v[88:91]
	v_mfma_f32_16x16x32_bf16 v[88:91], v[140:143], v[180:183], v[88:91]
	v_mfma_f32_16x16x32_bf16 v[72:75], v[136:139], v[200:203], v[72:75]
	v_mfma_f32_16x16x32_bf16 v[72:75], v[140:143], v[204:207], v[72:75]
	v_mfma_f32_16x16x32_bf16 v[116:119], v[144:147], v[160:163], v[116:119]
	v_mfma_f32_16x16x32_bf16 v[116:119], v[148:151], v[164:167], v[116:119]
	v_mfma_f32_16x16x32_bf16 v[100:103], v[144:147], v[168:171], v[100:103]
	v_mfma_f32_16x16x32_bf16 v[100:103], v[148:151], v[172:175], v[100:103]
	v_mfma_f32_16x16x32_bf16 v[84:87], v[144:147], v[176:179], v[84:87]
	v_mfma_f32_16x16x32_bf16 v[84:87], v[148:151], v[180:183], v[84:87]
	v_mfma_f32_16x16x32_bf16 v[68:71], v[144:147], v[200:203], v[68:71]
	v_mfma_f32_16x16x32_bf16 v[68:71], v[148:151], v[204:207], v[68:71]
	v_mfma_f32_16x16x32_bf16 v[112:115], v[152:155], v[160:163], v[112:115]
	v_mfma_f32_16x16x32_bf16 v[112:115], v[156:159], v[164:167], v[112:115]
	v_mfma_f32_16x16x32_bf16 v[96:99], v[152:155], v[168:171], v[96:99]
	v_mfma_f32_16x16x32_bf16 v[96:99], v[156:159], v[172:175], v[96:99]
	s_setprio 2
	s_barrier
	v_mfma_f32_16x16x32_bf16 v[80:83], v[152:155], v[176:179], v[80:83]
	v_mfma_f32_16x16x32_bf16 v[80:83], v[156:159], v[180:183], v[80:83]
	v_mfma_f32_16x16x32_bf16 v[64:67], v[152:155], v[200:203], v[64:67]
	v_mfma_f32_16x16x32_bf16 v[64:67], v[156:159], v[204:207], v[64:67]
	s_setprio 0
	s_add_i32 s26, s65, s43
	v_lshl_add_u64 v[208:209], v[208:209], 0, s[20:21]
	s_mov_b32 m0, s26
	ds_read_b128 v[160:163], v235 offset:49152
	ds_read_b128 v[164:167], v235 offset:50176
	ds_read_b128 v[168:171], v235 offset:51200
	ds_read_b128 v[172:175], v235 offset:52224
	ds_read_b128 v[176:179], v235 offset:53248
	ds_read_b128 v[180:183], v235 offset:54272
	ds_read_b128 v[200:203], v235 offset:55296
	ds_read_b128 v[204:207], v235 offset:56320
	global_load_lds_dwordx4 v[208:209], off
	s_add_i32 m0, s26, 0x2000
	s_add_u32 s26, s30, 0xb0080
	v_lshl_add_u64 v[208:209], v[210:211], 0, s[20:21]
	s_addc_u32 s27, s31, 0
	s_add_i32 s30, s66, s43
	global_load_lds_dwordx4 v[208:209], off
	s_mov_b32 m0, s30
	v_lshl_add_u64 v[208:209], s[26:27], 0, v[186:187]
	global_load_lds_dwordx4 v[208:209], off
	s_add_i32 m0, s30, 0x2000
	v_lshl_add_u64 v[208:209], s[26:27], 0, v[190:191]
	global_load_lds_dwordx4 v[208:209], off
	s_mov_b32 m0, s49
	v_lshl_add_u64 v[208:209], v[212:213], 0, s[20:21]
	global_load_lds_dwordx4 v[208:209], off
	s_mov_b32 m0, s50
	v_lshl_add_u64 v[208:209], v[214:215], 0, s[20:21]
	global_load_lds_dwordx4 v[208:209], off
	s_waitcnt vmcnt(8) lgkmcnt(0)
	s_barrier
	s_setprio 1
	v_mfma_f32_16x16x32_bf16 v[60:63], v[120:123], v[160:163], v[60:63]
	v_mfma_f32_16x16x32_bf16 v[60:63], v[124:127], v[164:167], v[60:63]
	v_mfma_f32_16x16x32_bf16 v[44:47], v[120:123], v[168:171], v[44:47]
	v_mfma_f32_16x16x32_bf16 v[44:47], v[124:127], v[172:175], v[44:47]
	v_mfma_f32_16x16x32_bf16 v[28:31], v[120:123], v[176:179], v[28:31]
	v_mfma_f32_16x16x32_bf16 v[28:31], v[124:127], v[180:183], v[28:31]
	v_mfma_f32_16x16x32_bf16 v[12:15], v[120:123], v[200:203], v[12:15]
	v_mfma_f32_16x16x32_bf16 v[12:15], v[124:127], v[204:207], v[12:15]
	v_mfma_f32_16x16x32_bf16 v[56:59], v[136:139], v[160:163], v[56:59]
	v_mfma_f32_16x16x32_bf16 v[56:59], v[140:143], v[164:167], v[56:59]
	v_mfma_f32_16x16x32_bf16 v[40:43], v[136:139], v[168:171], v[40:43]
	v_mfma_f32_16x16x32_bf16 v[40:43], v[140:143], v[172:175], v[40:43]
	v_mfma_f32_16x16x32_bf16 v[24:27], v[136:139], v[176:179], v[24:27]
	v_mfma_f32_16x16x32_bf16 v[24:27], v[140:143], v[180:183], v[24:27]
	v_mfma_f32_16x16x32_bf16 v[8:11], v[136:139], v[200:203], v[8:11]
	v_mfma_f32_16x16x32_bf16 v[8:11], v[140:143], v[204:207], v[8:11]
	v_mfma_f32_16x16x32_bf16 v[52:55], v[144:147], v[160:163], v[52:55]
	v_mfma_f32_16x16x32_bf16 v[52:55], v[148:151], v[164:167], v[52:55]
	v_mfma_f32_16x16x32_bf16 v[36:39], v[144:147], v[168:171], v[36:39]
	v_mfma_f32_16x16x32_bf16 v[36:39], v[148:151], v[172:175], v[36:39]
	v_mfma_f32_16x16x32_bf16 v[20:23], v[144:147], v[176:179], v[20:23]
	v_mfma_f32_16x16x32_bf16 v[20:23], v[148:151], v[180:183], v[20:23]
	v_mfma_f32_16x16x32_bf16 v[4:7], v[144:147], v[200:203], v[4:7]
	v_mfma_f32_16x16x32_bf16 v[4:7], v[148:151], v[204:207], v[4:7]
	v_mfma_f32_16x16x32_bf16 v[48:51], v[152:155], v[160:163], v[48:51]
	v_mfma_f32_16x16x32_bf16 v[48:51], v[156:159], v[164:167], v[48:51]
	v_mfma_f32_16x16x32_bf16 v[32:35], v[152:155], v[168:171], v[32:35]
	v_mfma_f32_16x16x32_bf16 v[32:35], v[156:159], v[172:175], v[32:35]
	s_setprio 2
	s_barrier
	v_mfma_f32_16x16x32_bf16 v[16:19], v[152:155], v[176:179], v[16:19]
	v_mfma_f32_16x16x32_bf16 v[16:19], v[156:159], v[180:183], v[16:19]
	v_mfma_f32_16x16x32_bf16 v[0:3], v[152:155], v[200:203], v[0:3]
	v_mfma_f32_16x16x32_bf16 v[0:3], v[156:159], v[204:207], v[0:3]
	s_setprio 0
	s_add_i32 s64, s64, 2
	s_add_u32 s62, s62, 0x100
	s_addc_u32 s63, s63, 0
	s_cmp_gt_u32 s64, 41
	s_mov_b64 s[26:27], s[28:29]
	s_cbranch_scc0 .LBB0_866

.LBB0_951:
	s_ashr_i32 s27, s26, 31
	s_lshl_b64 s[30:31], s[26:27], 19
	s_add_u32 s30, s47, s30
	s_addc_u32 s31, s48, s31
	s_and_b64 s[36:37], s[4:5], exec
	s_cselect_b32 s27, s31, s7
	s_cselect_b32 s39, s30, s6
	s_ashr_i32 s29, s28, 31
	s_lshl_b64 s[36:37], s[28:29], 19
	s_add_u32 s36, s49, s36
	s_addc_u32 s37, s50, s37
	s_and_b64 s[44:45], s[4:5], exec
	s_cselect_b32 s29, s37, s41
	s_cselect_b32 s43, s36, s40
	s_add_u32 s6, s6, 0x40080
	s_addc_u32 s7, s7, 0
	s_add_u32 s71, s40, 0x100
	s_addc_u32 s72, s41, 0
	s_mov_b32 s73, -2
	ds_read_b128 v[144:147], v179
	ds_read_b128 v[148:151], v179 offset:1024
	ds_read_b128 v[152:155], v179 offset:2048
	ds_read_b128 v[156:159], v179 offset:3072
	ds_read_b128 v[160:163], v180
	ds_read_b128 v[164:167], v180 offset:1024
	ds_read_b128 v[168:171], v180 offset:2048
	ds_read_b128 v[172:175], v180 offset:3072
	s_add_u32 s40, s6, 0xfffc0080
	s_addc_u32 s41, s7, -1
	s_cmp_eq_u32 s73, 12
	s_cselect_b32 s45, s27, s41
	s_cselect_b32 s44, s39, s40
	s_cselect_b32 s41, s29, s72
	s_cselect_b32 s40, s43, s71
	v_lshl_add_u64 v[176:177], s[6:7], 0, v[136:137]
	s_add_i32 m0, s54, 0xc000
	ds_read_b128 v[184:187], v181
	ds_read_b128 v[188:191], v181 offset:1024
	ds_read_b128 v[192:195], v181 offset:2048
	ds_read_b128 v[196:199], v181 offset:3072
	ds_read_b128 v[200:203], v181 offset:4096
	ds_read_b128 v[204:207], v181 offset:5120
	ds_read_b128 v[208:211], v181 offset:6144
	ds_read_b128 v[212:215], v181 offset:7168
	global_load_lds_dwordx4 v[176:177], off
	s_add_i32 m0, s54, 0xe000
	v_lshl_add_u64 v[176:177], s[6:7], 0, v[138:139]
	global_load_lds_dwordx4 v[176:177], off
	s_waitcnt vmcnt(8) lgkmcnt(0)
	s_barrier
	s_setprio 1
	v_mfma_f32_16x16x32_bf16 v[124:127], v[144:147], v[184:187], 0
	v_mfma_f32_16x16x32_bf16 v[124:127], v[148:151], v[188:191], v[124:127]
	v_mfma_f32_16x16x32_bf16 v[108:111], v[144:147], v[192:195], 0
	v_mfma_f32_16x16x32_bf16 v[108:111], v[148:151], v[196:199], v[108:111]
	v_mfma_f32_16x16x32_bf16 v[92:95], v[144:147], v[200:203], 0
	v_mfma_f32_16x16x32_bf16 v[92:95], v[148:151], v[204:207], v[92:95]
	v_mfma_f32_16x16x32_bf16 v[76:79], v[144:147], v[208:211], 0
	v_mfma_f32_16x16x32_bf16 v[76:79], v[148:151], v[212:215], v[76:79]
	v_mfma_f32_16x16x32_bf16 v[120:123], v[152:155], v[184:187], 0
	v_mfma_f32_16x16x32_bf16 v[120:123], v[156:159], v[188:191], v[120:123]
	v_mfma_f32_16x16x32_bf16 v[104:107], v[152:155], v[192:195], 0
	v_mfma_f32_16x16x32_bf16 v[104:107], v[156:159], v[196:199], v[104:107]
	v_mfma_f32_16x16x32_bf16 v[88:91], v[152:155], v[200:203], 0
	v_mfma_f32_16x16x32_bf16 v[88:91], v[156:159], v[204:207], v[88:91]
	v_mfma_f32_16x16x32_bf16 v[72:75], v[152:155], v[208:211], 0
	v_mfma_f32_16x16x32_bf16 v[72:75], v[156:159], v[212:215], v[72:75]
	v_mfma_f32_16x16x32_bf16 v[116:119], v[160:163], v[184:187], 0
	v_mfma_f32_16x16x32_bf16 v[116:119], v[164:167], v[188:191], v[116:119]
	v_mfma_f32_16x16x32_bf16 v[100:103], v[160:163], v[192:195], 0
	v_mfma_f32_16x16x32_bf16 v[100:103], v[164:167], v[196:199], v[100:103]
	v_mfma_f32_16x16x32_bf16 v[84:87], v[160:163], v[200:203], 0
	v_mfma_f32_16x16x32_bf16 v[84:87], v[164:167], v[204:207], v[84:87]
	v_mfma_f32_16x16x32_bf16 v[68:71], v[160:163], v[208:211], 0
	v_mfma_f32_16x16x32_bf16 v[68:71], v[164:167], v[212:215], v[68:71]
	v_mfma_f32_16x16x32_bf16 v[112:115], v[168:171], v[184:187], 0
	v_mfma_f32_16x16x32_bf16 v[112:115], v[172:175], v[188:191], v[112:115]
	v_mfma_f32_16x16x32_bf16 v[96:99], v[168:171], v[192:195], 0
	v_mfma_f32_16x16x32_bf16 v[96:99], v[172:175], v[196:199], v[96:99]
	s_setprio 2
	s_barrier
	v_mfma_f32_16x16x32_bf16 v[80:83], v[168:171], v[200:203], 0
	v_mfma_f32_16x16x32_bf16 v[80:83], v[172:175], v[204:207], v[80:83]
	v_mfma_f32_16x16x32_bf16 v[64:67], v[168:171], v[208:211], 0
	v_mfma_f32_16x16x32_bf16 v[64:67], v[172:175], v[212:215], v[64:67]
	s_setprio 0
	s_add_i32 s74, s69, s51
	v_lshl_add_u64 v[176:177], s[40:41], 0, v[130:131]
	s_mov_b32 m0, s74
	ds_read_b128 v[184:187], v181 offset:16384
	ds_read_b128 v[188:191], v181 offset:17408
	ds_read_b128 v[192:195], v181 offset:18432
	ds_read_b128 v[196:199], v181 offset:19456
	ds_read_b128 v[200:203], v181 offset:20480
	ds_read_b128 v[204:207], v181 offset:21504
	ds_read_b128 v[208:211], v181 offset:22528
	ds_read_b128 v[212:215], v181 offset:23552
	global_load_lds_dwordx4 v[176:177], off
	s_add_i32 m0, s74, 0x2000
	s_add_u32 s74, s40, 0x40000
	v_lshl_add_u64 v[216:217], s[40:41], 0, v[134:135]
	s_addc_u32 s75, s41, 0
	s_add_i32 s76, s70, s51
	global_load_lds_dwordx4 v[216:217], off
	v_lshl_add_u64 v[218:219], s[74:75], 0, v[130:131]
	s_mov_b32 m0, s76
	v_lshl_add_u64 v[220:221], s[44:45], 0, v[132:133]
	global_load_lds_dwordx4 v[218:219], off
	s_add_i32 m0, s76, 0x2000
	v_lshl_add_u64 v[218:219], s[74:75], 0, v[134:135]
	global_load_lds_dwordx4 v[218:219], off
	s_mov_b32 m0, s54
	v_lshl_add_u64 v[218:219], s[44:45], 0, v[128:129]
	global_load_lds_dwordx4 v[218:219], off
	s_mov_b32 m0, s55
	s_nop 0
	global_load_lds_dwordx4 v[220:221], off
	s_waitcnt vmcnt(8) lgkmcnt(0)
	s_barrier
	s_setprio 1
	v_mfma_f32_16x16x32_bf16 v[60:63], v[144:147], v[184:187], 0
	v_mfma_f32_16x16x32_bf16 v[60:63], v[148:151], v[188:191], v[60:63]
	v_mfma_f32_16x16x32_bf16 v[44:47], v[144:147], v[192:195], 0
	v_mfma_f32_16x16x32_bf16 v[44:47], v[148:151], v[196:199], v[44:47]
	v_mfma_f32_16x16x32_bf16 v[28:31], v[144:147], v[200:203], 0
	v_mfma_f32_16x16x32_bf16 v[28:31], v[148:151], v[204:207], v[28:31]
	v_mfma_f32_16x16x32_bf16 v[12:15], v[144:147], v[208:211], 0
	v_mfma_f32_16x16x32_bf16 v[12:15], v[148:151], v[212:215], v[12:15]
	v_mfma_f32_16x16x32_bf16 v[56:59], v[152:155], v[184:187], 0
	v_mfma_f32_16x16x32_bf16 v[56:59], v[156:159], v[188:191], v[56:59]
	v_mfma_f32_16x16x32_bf16 v[40:43], v[152:155], v[192:195], 0
	v_mfma_f32_16x16x32_bf16 v[40:43], v[156:159], v[196:199], v[40:43]
	v_mfma_f32_16x16x32_bf16 v[24:27], v[152:155], v[200:203], 0
	v_mfma_f32_16x16x32_bf16 v[24:27], v[156:159], v[204:207], v[24:27]
	v_mfma_f32_16x16x32_bf16 v[8:11], v[152:155], v[208:211], 0
	v_mfma_f32_16x16x32_bf16 v[8:11], v[156:159], v[212:215], v[8:11]
	v_mfma_f32_16x16x32_bf16 v[52:55], v[160:163], v[184:187], 0
	v_mfma_f32_16x16x32_bf16 v[52:55], v[164:167], v[188:191], v[52:55]
	v_mfma_f32_16x16x32_bf16 v[36:39], v[160:163], v[192:195], 0
	v_mfma_f32_16x16x32_bf16 v[36:39], v[164:167], v[196:199], v[36:39]
	v_mfma_f32_16x16x32_bf16 v[20:23], v[160:163], v[200:203], 0
	v_mfma_f32_16x16x32_bf16 v[20:23], v[164:167], v[204:207], v[20:23]
	v_mfma_f32_16x16x32_bf16 v[4:7], v[160:163], v[208:211], 0
	v_mfma_f32_16x16x32_bf16 v[4:7], v[164:167], v[212:215], v[4:7]
	v_mfma_f32_16x16x32_bf16 v[48:51], v[168:171], v[184:187], 0
	v_mfma_f32_16x16x32_bf16 v[48:51], v[172:175], v[188:191], v[48:51]
	v_mfma_f32_16x16x32_bf16 v[32:35], v[168:171], v[192:195], 0
	v_mfma_f32_16x16x32_bf16 v[32:35], v[172:175], v[196:199], v[32:35]
	s_setprio 2
	s_barrier
	v_mfma_f32_16x16x32_bf16 v[16:19], v[168:171], v[200:203], 0
	v_mfma_f32_16x16x32_bf16 v[16:19], v[172:175], v[204:207], v[16:19]
	v_mfma_f32_16x16x32_bf16 v[0:3], v[168:171], v[208:211], 0
	v_mfma_f32_16x16x32_bf16 v[0:3], v[172:175], v[212:215], v[0:3]
	s_setprio 0
	s_add_i32 s74, 0, 0x18000
	s_add_i32 s75, 0, 0x1c000
	v_add_u32_e32 v156, s74, v178
	v_add_u32_e32 v172, s75, v178
	ds_read_b128 v[144:147], v156
	ds_read_b128 v[148:151], v156 offset:1024
	ds_read_b128 v[152:155], v156 offset:2048
	ds_read_b128 v[156:159], v156 offset:3072
	ds_read_b128 v[160:163], v172
	ds_read_b128 v[164:167], v172 offset:1024
	ds_read_b128 v[168:171], v172 offset:2048
	ds_read_b128 v[172:175], v172 offset:3072
	s_add_u32 s44, s44, 0x40000
	s_addc_u32 s45, s45, 0
	s_mov_b32 m0, s56
	v_lshl_add_u64 v[222:223], s[44:45], 0, v[128:129]
	ds_read_b128 v[184:187], v181 offset:32768
	ds_read_b128 v[188:191], v181 offset:33792
	ds_read_b128 v[192:195], v181 offset:34816
	ds_read_b128 v[196:199], v181 offset:35840
	ds_read_b128 v[200:203], v181 offset:36864
	ds_read_b128 v[204:207], v181 offset:37888
	ds_read_b128 v[208:211], v181 offset:38912
	ds_read_b128 v[212:215], v181 offset:39936
	global_load_lds_dwordx4 v[222:223], off
	s_mov_b32 m0, s57
	v_lshl_add_u64 v[222:223], s[44:45], 0, v[132:133]
	global_load_lds_dwordx4 v[222:223], off
	s_waitcnt vmcnt(8) lgkmcnt(0)
	s_barrier
	s_setprio 1
	v_mfma_f32_16x16x32_bf16 v[124:127], v[144:147], v[184:187], v[124:127]
	v_mfma_f32_16x16x32_bf16 v[124:127], v[148:151], v[188:191], v[124:127]
	v_mfma_f32_16x16x32_bf16 v[108:111], v[144:147], v[192:195], v[108:111]
	v_mfma_f32_16x16x32_bf16 v[108:111], v[148:151], v[196:199], v[108:111]
	v_mfma_f32_16x16x32_bf16 v[92:95], v[144:147], v[200:203], v[92:95]
	v_mfma_f32_16x16x32_bf16 v[92:95], v[148:151], v[204:207], v[92:95]
	v_mfma_f32_16x16x32_bf16 v[76:79], v[144:147], v[208:211], v[76:79]
	v_mfma_f32_16x16x32_bf16 v[76:79], v[148:151], v[212:215], v[76:79]
	v_mfma_f32_16x16x32_bf16 v[120:123], v[152:155], v[184:187], v[120:123]
	v_mfma_f32_16x16x32_bf16 v[120:123], v[156:159], v[188:191], v[120:123]
	v_mfma_f32_16x16x32_bf16 v[104:107], v[152:155], v[192:195], v[104:107]
	v_mfma_f32_16x16x32_bf16 v[104:107], v[156:159], v[196:199], v[104:107]
	v_mfma_f32_16x16x32_bf16 v[88:91], v[152:155], v[200:203], v[88:91]
	v_mfma_f32_16x16x32_bf16 v[88:91], v[156:159], v[204:207], v[88:91]
	v_mfma_f32_16x16x32_bf16 v[72:75], v[152:155], v[208:211], v[72:75]
	v_mfma_f32_16x16x32_bf16 v[72:75], v[156:159], v[212:215], v[72:75]
	v_mfma_f32_16x16x32_bf16 v[116:119], v[160:163], v[184:187], v[116:119]
	v_mfma_f32_16x16x32_bf16 v[116:119], v[164:167], v[188:191], v[116:119]
	v_mfma_f32_16x16x32_bf16 v[100:103], v[160:163], v[192:195], v[100:103]
	v_mfma_f32_16x16x32_bf16 v[100:103], v[164:167], v[196:199], v[100:103]
	v_mfma_f32_16x16x32_bf16 v[84:87], v[160:163], v[200:203], v[84:87]
	v_mfma_f32_16x16x32_bf16 v[84:87], v[164:167], v[204:207], v[84:87]
	v_mfma_f32_16x16x32_bf16 v[68:71], v[160:163], v[208:211], v[68:71]
	v_mfma_f32_16x16x32_bf16 v[68:71], v[164:167], v[212:215], v[68:71]
	v_mfma_f32_16x16x32_bf16 v[112:115], v[168:171], v[184:187], v[112:115]
	v_mfma_f32_16x16x32_bf16 v[112:115], v[172:175], v[188:191], v[112:115]
	v_mfma_f32_16x16x32_bf16 v[96:99], v[168:171], v[192:195], v[96:99]
	v_mfma_f32_16x16x32_bf16 v[96:99], v[172:175], v[196:199], v[96:99]
	s_setprio 2
	s_barrier
	v_mfma_f32_16x16x32_bf16 v[80:83], v[168:171], v[200:203], v[80:83]
	v_mfma_f32_16x16x32_bf16 v[80:83], v[172:175], v[204:207], v[80:83]
	v_mfma_f32_16x16x32_bf16 v[64:67], v[168:171], v[208:211], v[64:67]
	v_mfma_f32_16x16x32_bf16 v[64:67], v[172:175], v[212:215], v[64:67]
	s_setprio 0
	s_add_i32 s44, s74, s51
	v_lshl_add_u64 v[176:177], v[176:177], 0, s[22:23]
	s_mov_b32 m0, s44
	ds_read_b128 v[184:187], v181 offset:49152
	ds_read_b128 v[188:191], v181 offset:50176
	ds_read_b128 v[192:195], v181 offset:51200
	ds_read_b128 v[196:199], v181 offset:52224
	ds_read_b128 v[200:203], v181 offset:53248
	ds_read_b128 v[204:207], v181 offset:54272
	ds_read_b128 v[208:211], v181 offset:55296
	ds_read_b128 v[212:215], v181 offset:56320
	global_load_lds_dwordx4 v[176:177], off
	s_add_i32 m0, s44, 0x2000
	s_add_u32 s40, s40, 0x40080
	v_lshl_add_u64 v[176:177], v[216:217], 0, s[22:23]
	s_addc_u32 s41, s41, 0
	s_add_i32 s44, s75, s51
	global_load_lds_dwordx4 v[176:177], off
	s_mov_b32 m0, s44
	v_lshl_add_u64 v[176:177], s[40:41], 0, v[130:131]
	global_load_lds_dwordx4 v[176:177], off
	s_add_i32 m0, s44, 0x2000
	v_lshl_add_u64 v[176:177], s[40:41], 0, v[134:135]
	global_load_lds_dwordx4 v[176:177], off
	s_mov_b32 m0, s64
	v_lshl_add_u64 v[176:177], v[218:219], 0, s[22:23]
	global_load_lds_dwordx4 v[176:177], off
	s_mov_b32 m0, s65
	v_lshl_add_u64 v[176:177], v[220:221], 0, s[22:23]
	global_load_lds_dwordx4 v[176:177], off
	s_waitcnt vmcnt(8) lgkmcnt(0)
	s_barrier
	s_setprio 1
	v_mfma_f32_16x16x32_bf16 v[60:63], v[144:147], v[184:187], v[60:63]
	v_mfma_f32_16x16x32_bf16 v[60:63], v[148:151], v[188:191], v[60:63]
	v_mfma_f32_16x16x32_bf16 v[44:47], v[144:147], v[192:195], v[44:47]
	v_mfma_f32_16x16x32_bf16 v[44:47], v[148:151], v[196:199], v[44:47]
	v_mfma_f32_16x16x32_bf16 v[28:31], v[144:147], v[200:203], v[28:31]
	v_mfma_f32_16x16x32_bf16 v[28:31], v[148:151], v[204:207], v[28:31]
	v_mfma_f32_16x16x32_bf16 v[12:15], v[144:147], v[208:211], v[12:15]
	v_mfma_f32_16x16x32_bf16 v[12:15], v[148:151], v[212:215], v[12:15]
	v_mfma_f32_16x16x32_bf16 v[56:59], v[152:155], v[184:187], v[56:59]
	v_mfma_f32_16x16x32_bf16 v[56:59], v[156:159], v[188:191], v[56:59]
	v_mfma_f32_16x16x32_bf16 v[40:43], v[152:155], v[192:195], v[40:43]
	v_mfma_f32_16x16x32_bf16 v[40:43], v[156:159], v[196:199], v[40:43]
	v_mfma_f32_16x16x32_bf16 v[24:27], v[152:155], v[200:203], v[24:27]
	v_mfma_f32_16x16x32_bf16 v[24:27], v[156:159], v[204:207], v[24:27]
	v_mfma_f32_16x16x32_bf16 v[8:11], v[152:155], v[208:211], v[8:11]
	v_mfma_f32_16x16x32_bf16 v[8:11], v[156:159], v[212:215], v[8:11]
	v_mfma_f32_16x16x32_bf16 v[52:55], v[160:163], v[184:187], v[52:55]
	v_mfma_f32_16x16x32_bf16 v[52:55], v[164:167], v[188:191], v[52:55]
	v_mfma_f32_16x16x32_bf16 v[36:39], v[160:163], v[192:195], v[36:39]
	v_mfma_f32_16x16x32_bf16 v[36:39], v[164:167], v[196:199], v[36:39]
	v_mfma_f32_16x16x32_bf16 v[20:23], v[160:163], v[200:203], v[20:23]
	v_mfma_f32_16x16x32_bf16 v[20:23], v[164:167], v[204:207], v[20:23]
	v_mfma_f32_16x16x32_bf16 v[4:7], v[160:163], v[208:211], v[4:7]
	v_mfma_f32_16x16x32_bf16 v[4:7], v[164:167], v[212:215], v[4:7]
	v_mfma_f32_16x16x32_bf16 v[48:51], v[168:171], v[184:187], v[48:51]
	v_mfma_f32_16x16x32_bf16 v[48:51], v[172:175], v[188:191], v[48:51]
	v_mfma_f32_16x16x32_bf16 v[32:35], v[168:171], v[192:195], v[32:35]
	v_mfma_f32_16x16x32_bf16 v[32:35], v[172:175], v[196:199], v[32:35]
	s_setprio 2
	s_barrier
	v_mfma_f32_16x16x32_bf16 v[16:19], v[168:171], v[200:203], v[16:19]
	v_mfma_f32_16x16x32_bf16 v[16:19], v[172:175], v[204:207], v[16:19]
	v_mfma_f32_16x16x32_bf16 v[0:3], v[168:171], v[208:211], v[0:3]
	v_mfma_f32_16x16x32_bf16 v[0:3], v[172:175], v[212:215], v[0:3]
	s_setprio 0
	s_add_i32 s73, s73, 2
	s_add_u32 s6, s6, 0x100
	s_addc_u32 s7, s7, 0
	s_add_u32 s71, s71, 0x100
	s_addc_u32 s72, s72, 0
	s_cmp_gt_u32 s73, 13
.LBB0_952:
	ds_read_b128 v[144:147], v179
	ds_read_b128 v[148:151], v179 offset:1024
	ds_read_b128 v[152:155], v179 offset:2048
	ds_read_b128 v[156:159], v179 offset:3072
	ds_read_b128 v[160:163], v180
	ds_read_b128 v[164:167], v180 offset:1024
	ds_read_b128 v[168:171], v180 offset:2048
	ds_read_b128 v[172:175], v180 offset:3072
	s_add_u32 s40, s6, 0xfffc0080
	s_addc_u32 s41, s7, -1
	s_cmp_eq_u32 s73, 12
	s_cselect_b32 s45, s27, s41
	s_cselect_b32 s44, s39, s40
	s_cselect_b32 s41, s29, s72
	s_cselect_b32 s40, s43, s71
	v_lshl_add_u64 v[176:177], s[6:7], 0, v[136:137]
	s_add_i32 m0, s54, 0xc000
	ds_read_b128 v[184:187], v181
	ds_read_b128 v[188:191], v181 offset:1024
	ds_read_b128 v[192:195], v181 offset:2048
	ds_read_b128 v[196:199], v181 offset:3072
	ds_read_b128 v[200:203], v181 offset:4096
	ds_read_b128 v[204:207], v181 offset:5120
	ds_read_b128 v[208:211], v181 offset:6144
	ds_read_b128 v[212:215], v181 offset:7168
	global_load_lds_dwordx4 v[176:177], off
	s_add_i32 m0, s54, 0xe000
	v_lshl_add_u64 v[176:177], s[6:7], 0, v[138:139]
	global_load_lds_dwordx4 v[176:177], off
	s_waitcnt vmcnt(8) lgkmcnt(0)
	s_barrier
	s_setprio 1
	v_mfma_f32_16x16x32_bf16 v[124:127], v[144:147], v[184:187], v[124:127]
	v_mfma_f32_16x16x32_bf16 v[124:127], v[148:151], v[188:191], v[124:127]
	v_mfma_f32_16x16x32_bf16 v[108:111], v[144:147], v[192:195], v[108:111]
	v_mfma_f32_16x16x32_bf16 v[108:111], v[148:151], v[196:199], v[108:111]
	v_mfma_f32_16x16x32_bf16 v[92:95], v[144:147], v[200:203], v[92:95]
	v_mfma_f32_16x16x32_bf16 v[92:95], v[148:151], v[204:207], v[92:95]
	v_mfma_f32_16x16x32_bf16 v[76:79], v[144:147], v[208:211], v[76:79]
	v_mfma_f32_16x16x32_bf16 v[76:79], v[148:151], v[212:215], v[76:79]
	v_mfma_f32_16x16x32_bf16 v[120:123], v[152:155], v[184:187], v[120:123]
	v_mfma_f32_16x16x32_bf16 v[120:123], v[156:159], v[188:191], v[120:123]
	v_mfma_f32_16x16x32_bf16 v[104:107], v[152:155], v[192:195], v[104:107]
	v_mfma_f32_16x16x32_bf16 v[104:107], v[156:159], v[196:199], v[104:107]
	v_mfma_f32_16x16x32_bf16 v[88:91], v[152:155], v[200:203], v[88:91]
	v_mfma_f32_16x16x32_bf16 v[88:91], v[156:159], v[204:207], v[88:91]
	v_mfma_f32_16x16x32_bf16 v[72:75], v[152:155], v[208:211], v[72:75]
	v_mfma_f32_16x16x32_bf16 v[72:75], v[156:159], v[212:215], v[72:75]
	v_mfma_f32_16x16x32_bf16 v[116:119], v[160:163], v[184:187], v[116:119]
	v_mfma_f32_16x16x32_bf16 v[116:119], v[164:167], v[188:191], v[116:119]
	v_mfma_f32_16x16x32_bf16 v[100:103], v[160:163], v[192:195], v[100:103]
	v_mfma_f32_16x16x32_bf16 v[100:103], v[164:167], v[196:199], v[100:103]
	v_mfma_f32_16x16x32_bf16 v[84:87], v[160:163], v[200:203], v[84:87]
	v_mfma_f32_16x16x32_bf16 v[84:87], v[164:167], v[204:207], v[84:87]
	v_mfma_f32_16x16x32_bf16 v[68:71], v[160:163], v[208:211], v[68:71]
	v_mfma_f32_16x16x32_bf16 v[68:71], v[164:167], v[212:215], v[68:71]
	v_mfma_f32_16x16x32_bf16 v[112:115], v[168:171], v[184:187], v[112:115]
	v_mfma_f32_16x16x32_bf16 v[112:115], v[172:175], v[188:191], v[112:115]
	v_mfma_f32_16x16x32_bf16 v[96:99], v[168:171], v[192:195], v[96:99]
	v_mfma_f32_16x16x32_bf16 v[96:99], v[172:175], v[196:199], v[96:99]
	s_setprio 2
	s_barrier
	v_mfma_f32_16x16x32_bf16 v[80:83], v[168:171], v[200:203], v[80:83]
	v_mfma_f32_16x16x32_bf16 v[80:83], v[172:175], v[204:207], v[80:83]
	v_mfma_f32_16x16x32_bf16 v[64:67], v[168:171], v[208:211], v[64:67]
	v_mfma_f32_16x16x32_bf16 v[64:67], v[172:175], v[212:215], v[64:67]
	s_setprio 0
	s_add_i32 s74, s69, s51
	v_lshl_add_u64 v[176:177], s[40:41], 0, v[130:131]
	s_mov_b32 m0, s74
	ds_read_b128 v[184:187], v181 offset:16384
	ds_read_b128 v[188:191], v181 offset:17408
	ds_read_b128 v[192:195], v181 offset:18432
	ds_read_b128 v[196:199], v181 offset:19456
	ds_read_b128 v[200:203], v181 offset:20480
	ds_read_b128 v[204:207], v181 offset:21504
	ds_read_b128 v[208:211], v181 offset:22528
	ds_read_b128 v[212:215], v181 offset:23552
	global_load_lds_dwordx4 v[176:177], off
	s_add_i32 m0, s74, 0x2000
	s_add_u32 s74, s40, 0x40000
	v_lshl_add_u64 v[216:217], s[40:41], 0, v[134:135]
	s_addc_u32 s75, s41, 0
	s_add_i32 s76, s70, s51
	global_load_lds_dwordx4 v[216:217], off
	v_lshl_add_u64 v[218:219], s[74:75], 0, v[130:131]
	s_mov_b32 m0, s76
	v_lshl_add_u64 v[220:221], s[44:45], 0, v[132:133]
	global_load_lds_dwordx4 v[218:219], off
	s_add_i32 m0, s76, 0x2000
	v_lshl_add_u64 v[218:219], s[74:75], 0, v[134:135]
	global_load_lds_dwordx4 v[218:219], off
	s_mov_b32 m0, s54
	v_lshl_add_u64 v[218:219], s[44:45], 0, v[128:129]
	global_load_lds_dwordx4 v[218:219], off
	s_mov_b32 m0, s55
	s_nop 0
	global_load_lds_dwordx4 v[220:221], off
	s_waitcnt vmcnt(8) lgkmcnt(0)
	s_barrier
	s_setprio 1
	v_mfma_f32_16x16x32_bf16 v[60:63], v[144:147], v[184:187], v[60:63]
	v_mfma_f32_16x16x32_bf16 v[60:63], v[148:151], v[188:191], v[60:63]
	v_mfma_f32_16x16x32_bf16 v[44:47], v[144:147], v[192:195], v[44:47]
	v_mfma_f32_16x16x32_bf16 v[44:47], v[148:151], v[196:199], v[44:47]
	v_mfma_f32_16x16x32_bf16 v[28:31], v[144:147], v[200:203], v[28:31]
	v_mfma_f32_16x16x32_bf16 v[28:31], v[148:151], v[204:207], v[28:31]
	v_mfma_f32_16x16x32_bf16 v[12:15], v[144:147], v[208:211], v[12:15]
	v_mfma_f32_16x16x32_bf16 v[12:15], v[148:151], v[212:215], v[12:15]
	v_mfma_f32_16x16x32_bf16 v[56:59], v[152:155], v[184:187], v[56:59]
	v_mfma_f32_16x16x32_bf16 v[56:59], v[156:159], v[188:191], v[56:59]
	v_mfma_f32_16x16x32_bf16 v[40:43], v[152:155], v[192:195], v[40:43]
	v_mfma_f32_16x16x32_bf16 v[40:43], v[156:159], v[196:199], v[40:43]
	v_mfma_f32_16x16x32_bf16 v[24:27], v[152:155], v[200:203], v[24:27]
	v_mfma_f32_16x16x32_bf16 v[24:27], v[156:159], v[204:207], v[24:27]
	v_mfma_f32_16x16x32_bf16 v[8:11], v[152:155], v[208:211], v[8:11]
	v_mfma_f32_16x16x32_bf16 v[8:11], v[156:159], v[212:215], v[8:11]
	v_mfma_f32_16x16x32_bf16 v[52:55], v[160:163], v[184:187], v[52:55]
	v_mfma_f32_16x16x32_bf16 v[52:55], v[164:167], v[188:191], v[52:55]
	v_mfma_f32_16x16x32_bf16 v[36:39], v[160:163], v[192:195], v[36:39]
	v_mfma_f32_16x16x32_bf16 v[36:39], v[164:167], v[196:199], v[36:39]
	v_mfma_f32_16x16x32_bf16 v[20:23], v[160:163], v[200:203], v[20:23]
	v_mfma_f32_16x16x32_bf16 v[20:23], v[164:167], v[204:207], v[20:23]
	v_mfma_f32_16x16x32_bf16 v[4:7], v[160:163], v[208:211], v[4:7]
	v_mfma_f32_16x16x32_bf16 v[4:7], v[164:167], v[212:215], v[4:7]
	v_mfma_f32_16x16x32_bf16 v[48:51], v[168:171], v[184:187], v[48:51]
	v_mfma_f32_16x16x32_bf16 v[48:51], v[172:175], v[188:191], v[48:51]
	v_mfma_f32_16x16x32_bf16 v[32:35], v[168:171], v[192:195], v[32:35]
	v_mfma_f32_16x16x32_bf16 v[32:35], v[172:175], v[196:199], v[32:35]
	s_setprio 2
	s_barrier
	v_mfma_f32_16x16x32_bf16 v[16:19], v[168:171], v[200:203], v[16:19]
	v_mfma_f32_16x16x32_bf16 v[16:19], v[172:175], v[204:207], v[16:19]
	v_mfma_f32_16x16x32_bf16 v[0:3], v[168:171], v[208:211], v[0:3]
	v_mfma_f32_16x16x32_bf16 v[0:3], v[172:175], v[212:215], v[0:3]
	s_setprio 0
	s_add_i32 s74, 0, 0x18000
	s_add_i32 s75, 0, 0x1c000
	v_add_u32_e32 v156, s74, v178
	v_add_u32_e32 v172, s75, v178
	ds_read_b128 v[144:147], v156
	ds_read_b128 v[148:151], v156 offset:1024
	ds_read_b128 v[152:155], v156 offset:2048
	ds_read_b128 v[156:159], v156 offset:3072
	ds_read_b128 v[160:163], v172
	ds_read_b128 v[164:167], v172 offset:1024
	ds_read_b128 v[168:171], v172 offset:2048
	ds_read_b128 v[172:175], v172 offset:3072
	s_add_u32 s44, s44, 0x40000
	s_addc_u32 s45, s45, 0
	s_mov_b32 m0, s56
	v_lshl_add_u64 v[222:223], s[44:45], 0, v[128:129]
	ds_read_b128 v[184:187], v181 offset:32768
	ds_read_b128 v[188:191], v181 offset:33792
	ds_read_b128 v[192:195], v181 offset:34816
	ds_read_b128 v[196:199], v181 offset:35840
	ds_read_b128 v[200:203], v181 offset:36864
	ds_read_b128 v[204:207], v181 offset:37888
	ds_read_b128 v[208:211], v181 offset:38912
	ds_read_b128 v[212:215], v181 offset:39936
	global_load_lds_dwordx4 v[222:223], off
	s_mov_b32 m0, s57
	v_lshl_add_u64 v[222:223], s[44:45], 0, v[132:133]
	global_load_lds_dwordx4 v[222:223], off
	s_waitcnt vmcnt(8) lgkmcnt(0)
	s_barrier
	s_setprio 1
	v_mfma_f32_16x16x32_bf16 v[124:127], v[144:147], v[184:187], v[124:127]
	v_mfma_f32_16x16x32_bf16 v[124:127], v[148:151], v[188:191], v[124:127]
	v_mfma_f32_16x16x32_bf16 v[108:111], v[144:147], v[192:195], v[108:111]
	v_mfma_f32_16x16x32_bf16 v[108:111], v[148:151], v[196:199], v[108:111]
	v_mfma_f32_16x16x32_bf16 v[92:95], v[144:147], v[200:203], v[92:95]
	v_mfma_f32_16x16x32_bf16 v[92:95], v[148:151], v[204:207], v[92:95]
	v_mfma_f32_16x16x32_bf16 v[76:79], v[144:147], v[208:211], v[76:79]
	v_mfma_f32_16x16x32_bf16 v[76:79], v[148:151], v[212:215], v[76:79]
	v_mfma_f32_16x16x32_bf16 v[120:123], v[152:155], v[184:187], v[120:123]
	v_mfma_f32_16x16x32_bf16 v[120:123], v[156:159], v[188:191], v[120:123]
	v_mfma_f32_16x16x32_bf16 v[104:107], v[152:155], v[192:195], v[104:107]
	v_mfma_f32_16x16x32_bf16 v[104:107], v[156:159], v[196:199], v[104:107]
	v_mfma_f32_16x16x32_bf16 v[88:91], v[152:155], v[200:203], v[88:91]
	v_mfma_f32_16x16x32_bf16 v[88:91], v[156:159], v[204:207], v[88:91]
	v_mfma_f32_16x16x32_bf16 v[72:75], v[152:155], v[208:211], v[72:75]
	v_mfma_f32_16x16x32_bf16 v[72:75], v[156:159], v[212:215], v[72:75]
	v_mfma_f32_16x16x32_bf16 v[116:119], v[160:163], v[184:187], v[116:119]
	v_mfma_f32_16x16x32_bf16 v[116:119], v[164:167], v[188:191], v[116:119]
	v_mfma_f32_16x16x32_bf16 v[100:103], v[160:163], v[192:195], v[100:103]
	v_mfma_f32_16x16x32_bf16 v[100:103], v[164:167], v[196:199], v[100:103]
	v_mfma_f32_16x16x32_bf16 v[84:87], v[160:163], v[200:203], v[84:87]
	v_mfma_f32_16x16x32_bf16 v[84:87], v[164:167], v[204:207], v[84:87]
	v_mfma_f32_16x16x32_bf16 v[68:71], v[160:163], v[208:211], v[68:71]
	v_mfma_f32_16x16x32_bf16 v[68:71], v[164:167], v[212:215], v[68:71]
	v_mfma_f32_16x16x32_bf16 v[112:115], v[168:171], v[184:187], v[112:115]
	v_mfma_f32_16x16x32_bf16 v[112:115], v[172:175], v[188:191], v[112:115]
	v_mfma_f32_16x16x32_bf16 v[96:99], v[168:171], v[192:195], v[96:99]
	v_mfma_f32_16x16x32_bf16 v[96:99], v[172:175], v[196:199], v[96:99]
	s_setprio 2
	s_barrier
	v_mfma_f32_16x16x32_bf16 v[80:83], v[168:171], v[200:203], v[80:83]
	v_mfma_f32_16x16x32_bf16 v[80:83], v[172:175], v[204:207], v[80:83]
	v_mfma_f32_16x16x32_bf16 v[64:67], v[168:171], v[208:211], v[64:67]
	v_mfma_f32_16x16x32_bf16 v[64:67], v[172:175], v[212:215], v[64:67]
	s_setprio 0
	s_add_i32 s44, s74, s51
	v_lshl_add_u64 v[176:177], v[176:177], 0, s[22:23]
	s_mov_b32 m0, s44
	ds_read_b128 v[184:187], v181 offset:49152
	ds_read_b128 v[188:191], v181 offset:50176
	ds_read_b128 v[192:195], v181 offset:51200
	ds_read_b128 v[196:199], v181 offset:52224
	ds_read_b128 v[200:203], v181 offset:53248
	ds_read_b128 v[204:207], v181 offset:54272
	ds_read_b128 v[208:211], v181 offset:55296
	ds_read_b128 v[212:215], v181 offset:56320
	global_load_lds_dwordx4 v[176:177], off
	s_add_i32 m0, s44, 0x2000
	s_add_u32 s40, s40, 0x40080
	v_lshl_add_u64 v[176:177], v[216:217], 0, s[22:23]
	s_addc_u32 s41, s41, 0
	s_add_i32 s44, s75, s51
	global_load_lds_dwordx4 v[176:177], off
	s_mov_b32 m0, s44
	v_lshl_add_u64 v[176:177], s[40:41], 0, v[130:131]
	global_load_lds_dwordx4 v[176:177], off
	s_add_i32 m0, s44, 0x2000
	v_lshl_add_u64 v[176:177], s[40:41], 0, v[134:135]
	global_load_lds_dwordx4 v[176:177], off
	s_mov_b32 m0, s64
	v_lshl_add_u64 v[176:177], v[218:219], 0, s[22:23]
	global_load_lds_dwordx4 v[176:177], off
	s_mov_b32 m0, s65
	v_lshl_add_u64 v[176:177], v[220:221], 0, s[22:23]
	global_load_lds_dwordx4 v[176:177], off
	s_waitcnt vmcnt(8) lgkmcnt(0)
	s_barrier
	s_setprio 1
	v_mfma_f32_16x16x32_bf16 v[60:63], v[144:147], v[184:187], v[60:63]
	v_mfma_f32_16x16x32_bf16 v[60:63], v[148:151], v[188:191], v[60:63]
	v_mfma_f32_16x16x32_bf16 v[44:47], v[144:147], v[192:195], v[44:47]
	v_mfma_f32_16x16x32_bf16 v[44:47], v[148:151], v[196:199], v[44:47]
	v_mfma_f32_16x16x32_bf16 v[28:31], v[144:147], v[200:203], v[28:31]
	v_mfma_f32_16x16x32_bf16 v[28:31], v[148:151], v[204:207], v[28:31]
	v_mfma_f32_16x16x32_bf16 v[12:15], v[144:147], v[208:211], v[12:15]
	v_mfma_f32_16x16x32_bf16 v[12:15], v[148:151], v[212:215], v[12:15]
	v_mfma_f32_16x16x32_bf16 v[56:59], v[152:155], v[184:187], v[56:59]
	v_mfma_f32_16x16x32_bf16 v[56:59], v[156:159], v[188:191], v[56:59]
	v_mfma_f32_16x16x32_bf16 v[40:43], v[152:155], v[192:195], v[40:43]
	v_mfma_f32_16x16x32_bf16 v[40:43], v[156:159], v[196:199], v[40:43]
	v_mfma_f32_16x16x32_bf16 v[24:27], v[152:155], v[200:203], v[24:27]
	v_mfma_f32_16x16x32_bf16 v[24:27], v[156:159], v[204:207], v[24:27]
	v_mfma_f32_16x16x32_bf16 v[8:11], v[152:155], v[208:211], v[8:11]
	v_mfma_f32_16x16x32_bf16 v[8:11], v[156:159], v[212:215], v[8:11]
	v_mfma_f32_16x16x32_bf16 v[52:55], v[160:163], v[184:187], v[52:55]
	v_mfma_f32_16x16x32_bf16 v[52:55], v[164:167], v[188:191], v[52:55]
	v_mfma_f32_16x16x32_bf16 v[36:39], v[160:163], v[192:195], v[36:39]
	v_mfma_f32_16x16x32_bf16 v[36:39], v[164:167], v[196:199], v[36:39]
	v_mfma_f32_16x16x32_bf16 v[20:23], v[160:163], v[200:203], v[20:23]
	v_mfma_f32_16x16x32_bf16 v[20:23], v[164:167], v[204:207], v[20:23]
	v_mfma_f32_16x16x32_bf16 v[4:7], v[160:163], v[208:211], v[4:7]
	v_mfma_f32_16x16x32_bf16 v[4:7], v[164:167], v[212:215], v[4:7]
	v_mfma_f32_16x16x32_bf16 v[48:51], v[168:171], v[184:187], v[48:51]
	v_mfma_f32_16x16x32_bf16 v[48:51], v[172:175], v[188:191], v[48:51]
	v_mfma_f32_16x16x32_bf16 v[32:35], v[168:171], v[192:195], v[32:35]
	v_mfma_f32_16x16x32_bf16 v[32:35], v[172:175], v[196:199], v[32:35]
	s_setprio 2
	s_barrier
	v_mfma_f32_16x16x32_bf16 v[16:19], v[168:171], v[200:203], v[16:19]
	v_mfma_f32_16x16x32_bf16 v[16:19], v[172:175], v[204:207], v[16:19]
	v_mfma_f32_16x16x32_bf16 v[0:3], v[168:171], v[208:211], v[0:3]
	v_mfma_f32_16x16x32_bf16 v[0:3], v[172:175], v[212:215], v[0:3]
	s_setprio 0
	s_add_i32 s73, s73, 2
	s_add_u32 s6, s6, 0x100
	s_addc_u32 s7, s7, 0
	s_add_u32 s71, s71, 0x100
	s_addc_u32 s72, s72, 0
	s_cmp_gt_u32 s73, 13
	s_cbranch_scc0 .LBB0_952

.LBB0_1145:
	s_ashr_i32 s23, s22, 31
	s_lshl_b64 s[26:27], s[22:23], 19
	s_add_u32 s26, s45, s26
	s_addc_u32 s27, s46, s27
	s_and_b64 s[28:29], s[4:5], exec
	s_cselect_b32 s23, s27, s39
	s_cselect_b32 s31, s26, s38
	s_ashr_i32 s25, s24, 31
	s_lshl_b64 s[28:29], s[24:25], 19
	s_add_u32 s28, s47, s28
	s_addc_u32 s29, s48, s29
	s_and_b64 s[42:43], s[4:5], exec
	s_cselect_b32 s25, s29, s41
	s_cselect_b32 s37, s28, s40
	s_add_u32 s38, s38, 0x40080
	s_addc_u32 s39, s39, 0
	s_add_u32 s64, s40, 0x100
	s_addc_u32 s65, s41, 0
	s_mov_b32 s66, -2
	ds_read_b128 v[120:123], v233
	ds_read_b128 v[132:135], v233 offset:1024
	ds_read_b128 v[136:139], v233 offset:2048
	ds_read_b128 v[140:143], v233 offset:3072
	ds_read_b128 v[144:147], v234
	ds_read_b128 v[148:151], v234 offset:1024
	ds_read_b128 v[152:155], v234 offset:2048
	ds_read_b128 v[156:159], v234 offset:3072
	s_add_u32 s40, s38, 0xfffc0080
	s_addc_u32 s41, s39, -1
	s_cmp_eq_u32 s66, 12
	s_cselect_b32 s43, s23, s41
	s_cselect_b32 s42, s31, s40
	s_cselect_b32 s41, s25, s65
	s_cselect_b32 s40, s37, s64
	v_lshl_add_u64 v[208:209], s[38:39], 0, v[192:193]
	s_add_i32 m0, s50, 0xc000
	ds_read_b128 v[160:163], v235
	ds_read_b128 v[164:167], v235 offset:1024
	ds_read_b128 v[168:171], v235 offset:2048
	ds_read_b128 v[172:175], v235 offset:3072
	ds_read_b128 v[176:179], v235 offset:4096
	ds_read_b128 v[180:183], v235 offset:5120
	ds_read_b128 v[200:203], v235 offset:6144
	ds_read_b128 v[204:207], v235 offset:7168
	global_load_lds_dwordx4 v[208:209], off
	s_add_i32 m0, s50, 0xe000
	v_lshl_add_u64 v[208:209], s[38:39], 0, v[194:195]
	global_load_lds_dwordx4 v[208:209], off
	s_waitcnt vmcnt(8) lgkmcnt(0)
	s_barrier
	s_setprio 1
	v_mfma_f32_16x16x32_bf16 v[128:131], v[120:123], v[160:163], 0
	v_mfma_f32_16x16x32_bf16 v[128:131], v[132:135], v[164:167], v[128:131]
	v_mfma_f32_16x16x32_bf16 v[108:111], v[120:123], v[168:171], 0
	v_mfma_f32_16x16x32_bf16 v[108:111], v[132:135], v[172:175], v[108:111]
	v_mfma_f32_16x16x32_bf16 v[92:95], v[120:123], v[176:179], 0
	v_mfma_f32_16x16x32_bf16 v[92:95], v[132:135], v[180:183], v[92:95]
	v_mfma_f32_16x16x32_bf16 v[76:79], v[120:123], v[200:203], 0
	v_mfma_f32_16x16x32_bf16 v[76:79], v[132:135], v[204:207], v[76:79]
	v_mfma_f32_16x16x32_bf16 v[124:127], v[136:139], v[160:163], 0
	v_mfma_f32_16x16x32_bf16 v[124:127], v[140:143], v[164:167], v[124:127]
	v_mfma_f32_16x16x32_bf16 v[104:107], v[136:139], v[168:171], 0
	v_mfma_f32_16x16x32_bf16 v[104:107], v[140:143], v[172:175], v[104:107]
	v_mfma_f32_16x16x32_bf16 v[88:91], v[136:139], v[176:179], 0
	v_mfma_f32_16x16x32_bf16 v[88:91], v[140:143], v[180:183], v[88:91]
	v_mfma_f32_16x16x32_bf16 v[72:75], v[136:139], v[200:203], 0
	v_mfma_f32_16x16x32_bf16 v[72:75], v[140:143], v[204:207], v[72:75]
	v_mfma_f32_16x16x32_bf16 v[116:119], v[144:147], v[160:163], 0
	v_mfma_f32_16x16x32_bf16 v[116:119], v[148:151], v[164:167], v[116:119]
	v_mfma_f32_16x16x32_bf16 v[100:103], v[144:147], v[168:171], 0
	v_mfma_f32_16x16x32_bf16 v[100:103], v[148:151], v[172:175], v[100:103]
	v_mfma_f32_16x16x32_bf16 v[84:87], v[144:147], v[176:179], 0
	v_mfma_f32_16x16x32_bf16 v[84:87], v[148:151], v[180:183], v[84:87]
	v_mfma_f32_16x16x32_bf16 v[68:71], v[144:147], v[200:203], 0
	v_mfma_f32_16x16x32_bf16 v[68:71], v[148:151], v[204:207], v[68:71]
	v_mfma_f32_16x16x32_bf16 v[112:115], v[152:155], v[160:163], 0
	v_mfma_f32_16x16x32_bf16 v[112:115], v[156:159], v[164:167], v[112:115]
	v_mfma_f32_16x16x32_bf16 v[96:99], v[152:155], v[168:171], 0
	v_mfma_f32_16x16x32_bf16 v[96:99], v[156:159], v[172:175], v[96:99]
	s_setprio 2
	s_barrier
	v_mfma_f32_16x16x32_bf16 v[80:83], v[152:155], v[176:179], 0
	v_mfma_f32_16x16x32_bf16 v[80:83], v[156:159], v[180:183], v[80:83]
	v_mfma_f32_16x16x32_bf16 v[64:67], v[152:155], v[200:203], 0
	v_mfma_f32_16x16x32_bf16 v[64:67], v[156:159], v[204:207], v[64:67]
	s_setprio 0
	s_add_i32 s67, s62, s49
	v_lshl_add_u64 v[208:209], s[40:41], 0, v[186:187]
	s_mov_b32 m0, s67
	ds_read_b128 v[160:163], v235 offset:16384
	ds_read_b128 v[164:167], v235 offset:17408
	ds_read_b128 v[168:171], v235 offset:18432
	ds_read_b128 v[172:175], v235 offset:19456
	ds_read_b128 v[176:179], v235 offset:20480
	ds_read_b128 v[180:183], v235 offset:21504
	ds_read_b128 v[200:203], v235 offset:22528
	ds_read_b128 v[204:207], v235 offset:23552
	global_load_lds_dwordx4 v[208:209], off
	s_add_i32 m0, s67, 0x2000
	s_add_u32 s68, s40, 0x40000
	v_lshl_add_u64 v[210:211], s[40:41], 0, v[190:191]
	s_addc_u32 s69, s41, 0
	s_add_i32 s67, s63, s49
	global_load_lds_dwordx4 v[210:211], off
	v_lshl_add_u64 v[212:213], s[68:69], 0, v[186:187]
	s_mov_b32 m0, s67
	v_lshl_add_u64 v[214:215], s[42:43], 0, v[188:189]
	global_load_lds_dwordx4 v[212:213], off
	s_add_i32 m0, s67, 0x2000
	v_lshl_add_u64 v[212:213], s[68:69], 0, v[190:191]
	global_load_lds_dwordx4 v[212:213], off
	s_mov_b32 m0, s50
	v_lshl_add_u64 v[212:213], s[42:43], 0, v[184:185]
	global_load_lds_dwordx4 v[212:213], off
	s_mov_b32 m0, s51
	s_nop 0
	global_load_lds_dwordx4 v[214:215], off
	s_waitcnt vmcnt(8) lgkmcnt(0)
	s_barrier
	s_setprio 1
	v_mfma_f32_16x16x32_bf16 v[60:63], v[120:123], v[160:163], 0
	v_mfma_f32_16x16x32_bf16 v[60:63], v[132:135], v[164:167], v[60:63]
	v_mfma_f32_16x16x32_bf16 v[44:47], v[120:123], v[168:171], 0
	v_mfma_f32_16x16x32_bf16 v[44:47], v[132:135], v[172:175], v[44:47]
	v_mfma_f32_16x16x32_bf16 v[28:31], v[120:123], v[176:179], 0
	v_mfma_f32_16x16x32_bf16 v[28:31], v[132:135], v[180:183], v[28:31]
	v_mfma_f32_16x16x32_bf16 v[12:15], v[120:123], v[200:203], 0
	v_mfma_f32_16x16x32_bf16 v[12:15], v[132:135], v[204:207], v[12:15]
	v_mfma_f32_16x16x32_bf16 v[56:59], v[136:139], v[160:163], 0
	v_mfma_f32_16x16x32_bf16 v[56:59], v[140:143], v[164:167], v[56:59]
	v_mfma_f32_16x16x32_bf16 v[40:43], v[136:139], v[168:171], 0
	v_mfma_f32_16x16x32_bf16 v[40:43], v[140:143], v[172:175], v[40:43]
	v_mfma_f32_16x16x32_bf16 v[24:27], v[136:139], v[176:179], 0
	v_mfma_f32_16x16x32_bf16 v[24:27], v[140:143], v[180:183], v[24:27]
	v_mfma_f32_16x16x32_bf16 v[8:11], v[136:139], v[200:203], 0
	v_mfma_f32_16x16x32_bf16 v[8:11], v[140:143], v[204:207], v[8:11]
	v_mfma_f32_16x16x32_bf16 v[52:55], v[144:147], v[160:163], 0
	v_mfma_f32_16x16x32_bf16 v[52:55], v[148:151], v[164:167], v[52:55]
	v_mfma_f32_16x16x32_bf16 v[36:39], v[144:147], v[168:171], 0
	v_mfma_f32_16x16x32_bf16 v[36:39], v[148:151], v[172:175], v[36:39]
	v_mfma_f32_16x16x32_bf16 v[20:23], v[144:147], v[176:179], 0
	v_mfma_f32_16x16x32_bf16 v[20:23], v[148:151], v[180:183], v[20:23]
	v_mfma_f32_16x16x32_bf16 v[4:7], v[144:147], v[200:203], 0
	v_mfma_f32_16x16x32_bf16 v[4:7], v[148:151], v[204:207], v[4:7]
	v_mfma_f32_16x16x32_bf16 v[48:51], v[152:155], v[160:163], 0
	v_mfma_f32_16x16x32_bf16 v[48:51], v[156:159], v[164:167], v[48:51]
	v_mfma_f32_16x16x32_bf16 v[32:35], v[152:155], v[168:171], 0
	v_mfma_f32_16x16x32_bf16 v[32:35], v[156:159], v[172:175], v[32:35]
	s_setprio 2
	s_barrier
	v_mfma_f32_16x16x32_bf16 v[16:19], v[152:155], v[176:179], 0
	v_mfma_f32_16x16x32_bf16 v[16:19], v[156:159], v[180:183], v[16:19]
	v_mfma_f32_16x16x32_bf16 v[0:3], v[152:155], v[200:203], 0
	v_mfma_f32_16x16x32_bf16 v[0:3], v[156:159], v[204:207], v[0:3]
	s_setprio 0
	s_add_i32 s67, 0, 0x18000
	s_add_i32 s68, 0, 0x1c000
	v_add_u32_e32 v140, s67, v232
	v_add_u32_e32 v156, s68, v232
	ds_read_b128 v[120:123], v140
	ds_read_b128 v[132:135], v140 offset:1024
	ds_read_b128 v[136:139], v140 offset:2048
	ds_read_b128 v[140:143], v140 offset:3072
	ds_read_b128 v[144:147], v156
	ds_read_b128 v[148:151], v156 offset:1024
	ds_read_b128 v[152:155], v156 offset:2048
	ds_read_b128 v[156:159], v156 offset:3072
	s_add_u32 s42, s42, 0x40000
	s_addc_u32 s43, s43, 0
	s_mov_b32 m0, s54
	v_lshl_add_u64 v[216:217], s[42:43], 0, v[184:185]
	ds_read_b128 v[160:163], v235 offset:32768
	ds_read_b128 v[164:167], v235 offset:33792
	ds_read_b128 v[168:171], v235 offset:34816
	ds_read_b128 v[172:175], v235 offset:35840
	ds_read_b128 v[176:179], v235 offset:36864
	ds_read_b128 v[180:183], v235 offset:37888
	ds_read_b128 v[200:203], v235 offset:38912
	ds_read_b128 v[204:207], v235 offset:39936
	global_load_lds_dwordx4 v[216:217], off
	s_mov_b32 m0, s55
	v_lshl_add_u64 v[216:217], s[42:43], 0, v[188:189]
	global_load_lds_dwordx4 v[216:217], off
	s_waitcnt vmcnt(8) lgkmcnt(0)
	s_barrier
	s_setprio 1
	v_mfma_f32_16x16x32_bf16 v[128:131], v[120:123], v[160:163], v[128:131]
	v_mfma_f32_16x16x32_bf16 v[128:131], v[132:135], v[164:167], v[128:131]
	v_mfma_f32_16x16x32_bf16 v[108:111], v[120:123], v[168:171], v[108:111]
	v_mfma_f32_16x16x32_bf16 v[108:111], v[132:135], v[172:175], v[108:111]
	v_mfma_f32_16x16x32_bf16 v[92:95], v[120:123], v[176:179], v[92:95]
	v_mfma_f32_16x16x32_bf16 v[92:95], v[132:135], v[180:183], v[92:95]
	v_mfma_f32_16x16x32_bf16 v[76:79], v[120:123], v[200:203], v[76:79]
	v_mfma_f32_16x16x32_bf16 v[76:79], v[132:135], v[204:207], v[76:79]
	v_mfma_f32_16x16x32_bf16 v[124:127], v[136:139], v[160:163], v[124:127]
	v_mfma_f32_16x16x32_bf16 v[124:127], v[140:143], v[164:167], v[124:127]
	v_mfma_f32_16x16x32_bf16 v[104:107], v[136:139], v[168:171], v[104:107]
	v_mfma_f32_16x16x32_bf16 v[104:107], v[140:143], v[172:175], v[104:107]
	v_mfma_f32_16x16x32_bf16 v[88:91], v[136:139], v[176:179], v[88:91]
	v_mfma_f32_16x16x32_bf16 v[88:91], v[140:143], v[180:183], v[88:91]
	v_mfma_f32_16x16x32_bf16 v[72:75], v[136:139], v[200:203], v[72:75]
	v_mfma_f32_16x16x32_bf16 v[72:75], v[140:143], v[204:207], v[72:75]
	v_mfma_f32_16x16x32_bf16 v[116:119], v[144:147], v[160:163], v[116:119]
	v_mfma_f32_16x16x32_bf16 v[116:119], v[148:151], v[164:167], v[116:119]
	v_mfma_f32_16x16x32_bf16 v[100:103], v[144:147], v[168:171], v[100:103]
	v_mfma_f32_16x16x32_bf16 v[100:103], v[148:151], v[172:175], v[100:103]
	v_mfma_f32_16x16x32_bf16 v[84:87], v[144:147], v[176:179], v[84:87]
	v_mfma_f32_16x16x32_bf16 v[84:87], v[148:151], v[180:183], v[84:87]
	v_mfma_f32_16x16x32_bf16 v[68:71], v[144:147], v[200:203], v[68:71]
	v_mfma_f32_16x16x32_bf16 v[68:71], v[148:151], v[204:207], v[68:71]
	v_mfma_f32_16x16x32_bf16 v[112:115], v[152:155], v[160:163], v[112:115]
	v_mfma_f32_16x16x32_bf16 v[112:115], v[156:159], v[164:167], v[112:115]
	v_mfma_f32_16x16x32_bf16 v[96:99], v[152:155], v[168:171], v[96:99]
	v_mfma_f32_16x16x32_bf16 v[96:99], v[156:159], v[172:175], v[96:99]
	s_setprio 2
	s_barrier
	v_mfma_f32_16x16x32_bf16 v[80:83], v[152:155], v[176:179], v[80:83]
	v_mfma_f32_16x16x32_bf16 v[80:83], v[156:159], v[180:183], v[80:83]
	v_mfma_f32_16x16x32_bf16 v[64:67], v[152:155], v[200:203], v[64:67]
	v_mfma_f32_16x16x32_bf16 v[64:67], v[156:159], v[204:207], v[64:67]
	s_setprio 0
	s_add_i32 s42, s67, s49
	v_lshl_add_u64 v[208:209], v[208:209], 0, s[18:19]
	s_mov_b32 m0, s42
	ds_read_b128 v[160:163], v235 offset:49152
	ds_read_b128 v[164:167], v235 offset:50176
	ds_read_b128 v[168:171], v235 offset:51200
	ds_read_b128 v[172:175], v235 offset:52224
	ds_read_b128 v[176:179], v235 offset:53248
	ds_read_b128 v[180:183], v235 offset:54272
	ds_read_b128 v[200:203], v235 offset:55296
	ds_read_b128 v[204:207], v235 offset:56320
	global_load_lds_dwordx4 v[208:209], off
	s_add_i32 m0, s42, 0x2000
	s_add_u32 s40, s40, 0x40080
	v_lshl_add_u64 v[208:209], v[210:211], 0, s[18:19]
	s_addc_u32 s41, s41, 0
	s_add_i32 s42, s68, s49
	global_load_lds_dwordx4 v[208:209], off
	s_mov_b32 m0, s42
	v_lshl_add_u64 v[208:209], s[40:41], 0, v[186:187]
	global_load_lds_dwordx4 v[208:209], off
	s_add_i32 m0, s42, 0x2000
	v_lshl_add_u64 v[208:209], s[40:41], 0, v[190:191]
	global_load_lds_dwordx4 v[208:209], off
	s_mov_b32 m0, s57
	v_lshl_add_u64 v[208:209], v[212:213], 0, s[18:19]
	global_load_lds_dwordx4 v[208:209], off
	s_mov_b32 m0, s58
	v_lshl_add_u64 v[208:209], v[214:215], 0, s[18:19]
	global_load_lds_dwordx4 v[208:209], off
	s_waitcnt vmcnt(8) lgkmcnt(0)
	s_barrier
	s_setprio 1
	v_mfma_f32_16x16x32_bf16 v[60:63], v[120:123], v[160:163], v[60:63]
	v_mfma_f32_16x16x32_bf16 v[60:63], v[132:135], v[164:167], v[60:63]
	v_mfma_f32_16x16x32_bf16 v[44:47], v[120:123], v[168:171], v[44:47]
	v_mfma_f32_16x16x32_bf16 v[44:47], v[132:135], v[172:175], v[44:47]
	v_mfma_f32_16x16x32_bf16 v[28:31], v[120:123], v[176:179], v[28:31]
	v_mfma_f32_16x16x32_bf16 v[28:31], v[132:135], v[180:183], v[28:31]
	v_mfma_f32_16x16x32_bf16 v[12:15], v[120:123], v[200:203], v[12:15]
	v_mfma_f32_16x16x32_bf16 v[12:15], v[132:135], v[204:207], v[12:15]
	v_mfma_f32_16x16x32_bf16 v[56:59], v[136:139], v[160:163], v[56:59]
	v_mfma_f32_16x16x32_bf16 v[56:59], v[140:143], v[164:167], v[56:59]
	v_mfma_f32_16x16x32_bf16 v[40:43], v[136:139], v[168:171], v[40:43]
	v_mfma_f32_16x16x32_bf16 v[40:43], v[140:143], v[172:175], v[40:43]
	v_mfma_f32_16x16x32_bf16 v[24:27], v[136:139], v[176:179], v[24:27]
	v_mfma_f32_16x16x32_bf16 v[24:27], v[140:143], v[180:183], v[24:27]
	v_mfma_f32_16x16x32_bf16 v[8:11], v[136:139], v[200:203], v[8:11]
	v_mfma_f32_16x16x32_bf16 v[8:11], v[140:143], v[204:207], v[8:11]
	v_mfma_f32_16x16x32_bf16 v[52:55], v[144:147], v[160:163], v[52:55]
	v_mfma_f32_16x16x32_bf16 v[52:55], v[148:151], v[164:167], v[52:55]
	v_mfma_f32_16x16x32_bf16 v[36:39], v[144:147], v[168:171], v[36:39]
	v_mfma_f32_16x16x32_bf16 v[36:39], v[148:151], v[172:175], v[36:39]
	v_mfma_f32_16x16x32_bf16 v[20:23], v[144:147], v[176:179], v[20:23]
	v_mfma_f32_16x16x32_bf16 v[20:23], v[148:151], v[180:183], v[20:23]
	v_mfma_f32_16x16x32_bf16 v[4:7], v[144:147], v[200:203], v[4:7]
	v_mfma_f32_16x16x32_bf16 v[4:7], v[148:151], v[204:207], v[4:7]
	v_mfma_f32_16x16x32_bf16 v[48:51], v[152:155], v[160:163], v[48:51]
	v_mfma_f32_16x16x32_bf16 v[48:51], v[156:159], v[164:167], v[48:51]
	v_mfma_f32_16x16x32_bf16 v[32:35], v[152:155], v[168:171], v[32:35]
	v_mfma_f32_16x16x32_bf16 v[32:35], v[156:159], v[172:175], v[32:35]
	s_setprio 2
	s_barrier
	v_mfma_f32_16x16x32_bf16 v[16:19], v[152:155], v[176:179], v[16:19]
	v_mfma_f32_16x16x32_bf16 v[16:19], v[156:159], v[180:183], v[16:19]
	v_mfma_f32_16x16x32_bf16 v[0:3], v[152:155], v[200:203], v[0:3]
	v_mfma_f32_16x16x32_bf16 v[0:3], v[156:159], v[204:207], v[0:3]
	s_setprio 0
	s_add_i32 s66, s66, 2
	s_add_u32 s38, s38, 0x100
	s_addc_u32 s39, s39, 0
	s_add_u32 s64, s64, 0x100
	s_addc_u32 s65, s65, 0
	s_cmp_gt_u32 s66, 13
.LBB0_1146:
	ds_read_b128 v[120:123], v233
	ds_read_b128 v[132:135], v233 offset:1024
	ds_read_b128 v[136:139], v233 offset:2048
	ds_read_b128 v[140:143], v233 offset:3072
	ds_read_b128 v[144:147], v234
	ds_read_b128 v[148:151], v234 offset:1024
	ds_read_b128 v[152:155], v234 offset:2048
	ds_read_b128 v[156:159], v234 offset:3072
	s_add_u32 s40, s38, 0xfffc0080
	s_addc_u32 s41, s39, -1
	s_cmp_eq_u32 s66, 12
	s_cselect_b32 s43, s23, s41
	s_cselect_b32 s42, s31, s40
	s_cselect_b32 s41, s25, s65
	s_cselect_b32 s40, s37, s64
	v_lshl_add_u64 v[208:209], s[38:39], 0, v[192:193]
	s_add_i32 m0, s50, 0xc000
	ds_read_b128 v[160:163], v235
	ds_read_b128 v[164:167], v235 offset:1024
	ds_read_b128 v[168:171], v235 offset:2048
	ds_read_b128 v[172:175], v235 offset:3072
	ds_read_b128 v[176:179], v235 offset:4096
	ds_read_b128 v[180:183], v235 offset:5120
	ds_read_b128 v[200:203], v235 offset:6144
	ds_read_b128 v[204:207], v235 offset:7168
	global_load_lds_dwordx4 v[208:209], off
	s_add_i32 m0, s50, 0xe000
	v_lshl_add_u64 v[208:209], s[38:39], 0, v[194:195]
	global_load_lds_dwordx4 v[208:209], off
	s_waitcnt vmcnt(8) lgkmcnt(0)
	s_barrier
	s_setprio 1
	v_mfma_f32_16x16x32_bf16 v[128:131], v[120:123], v[160:163], v[128:131]
	v_mfma_f32_16x16x32_bf16 v[128:131], v[132:135], v[164:167], v[128:131]
	v_mfma_f32_16x16x32_bf16 v[108:111], v[120:123], v[168:171], v[108:111]
	v_mfma_f32_16x16x32_bf16 v[108:111], v[132:135], v[172:175], v[108:111]
	v_mfma_f32_16x16x32_bf16 v[92:95], v[120:123], v[176:179], v[92:95]
	v_mfma_f32_16x16x32_bf16 v[92:95], v[132:135], v[180:183], v[92:95]
	v_mfma_f32_16x16x32_bf16 v[76:79], v[120:123], v[200:203], v[76:79]
	v_mfma_f32_16x16x32_bf16 v[76:79], v[132:135], v[204:207], v[76:79]
	v_mfma_f32_16x16x32_bf16 v[124:127], v[136:139], v[160:163], v[124:127]
	v_mfma_f32_16x16x32_bf16 v[124:127], v[140:143], v[164:167], v[124:127]
	v_mfma_f32_16x16x32_bf16 v[104:107], v[136:139], v[168:171], v[104:107]
	v_mfma_f32_16x16x32_bf16 v[104:107], v[140:143], v[172:175], v[104:107]
	v_mfma_f32_16x16x32_bf16 v[88:91], v[136:139], v[176:179], v[88:91]
	v_mfma_f32_16x16x32_bf16 v[88:91], v[140:143], v[180:183], v[88:91]
	v_mfma_f32_16x16x32_bf16 v[72:75], v[136:139], v[200:203], v[72:75]
	v_mfma_f32_16x16x32_bf16 v[72:75], v[140:143], v[204:207], v[72:75]
	v_mfma_f32_16x16x32_bf16 v[116:119], v[144:147], v[160:163], v[116:119]
	v_mfma_f32_16x16x32_bf16 v[116:119], v[148:151], v[164:167], v[116:119]
	v_mfma_f32_16x16x32_bf16 v[100:103], v[144:147], v[168:171], v[100:103]
	v_mfma_f32_16x16x32_bf16 v[100:103], v[148:151], v[172:175], v[100:103]
	v_mfma_f32_16x16x32_bf16 v[84:87], v[144:147], v[176:179], v[84:87]
	v_mfma_f32_16x16x32_bf16 v[84:87], v[148:151], v[180:183], v[84:87]
	v_mfma_f32_16x16x32_bf16 v[68:71], v[144:147], v[200:203], v[68:71]
	v_mfma_f32_16x16x32_bf16 v[68:71], v[148:151], v[204:207], v[68:71]
	v_mfma_f32_16x16x32_bf16 v[112:115], v[152:155], v[160:163], v[112:115]
	v_mfma_f32_16x16x32_bf16 v[112:115], v[156:159], v[164:167], v[112:115]
	v_mfma_f32_16x16x32_bf16 v[96:99], v[152:155], v[168:171], v[96:99]
	v_mfma_f32_16x16x32_bf16 v[96:99], v[156:159], v[172:175], v[96:99]
	s_setprio 2
	s_barrier
	v_mfma_f32_16x16x32_bf16 v[80:83], v[152:155], v[176:179], v[80:83]
	v_mfma_f32_16x16x32_bf16 v[80:83], v[156:159], v[180:183], v[80:83]
	v_mfma_f32_16x16x32_bf16 v[64:67], v[152:155], v[200:203], v[64:67]
	v_mfma_f32_16x16x32_bf16 v[64:67], v[156:159], v[204:207], v[64:67]
	s_setprio 0
	s_add_i32 s67, s62, s49
	v_lshl_add_u64 v[208:209], s[40:41], 0, v[186:187]
	s_mov_b32 m0, s67
	ds_read_b128 v[160:163], v235 offset:16384
	ds_read_b128 v[164:167], v235 offset:17408
	ds_read_b128 v[168:171], v235 offset:18432
	ds_read_b128 v[172:175], v235 offset:19456
	ds_read_b128 v[176:179], v235 offset:20480
	ds_read_b128 v[180:183], v235 offset:21504
	ds_read_b128 v[200:203], v235 offset:22528
	ds_read_b128 v[204:207], v235 offset:23552
	global_load_lds_dwordx4 v[208:209], off
	s_add_i32 m0, s67, 0x2000
	s_add_u32 s68, s40, 0x40000
	v_lshl_add_u64 v[210:211], s[40:41], 0, v[190:191]
	s_addc_u32 s69, s41, 0
	s_add_i32 s67, s63, s49
	global_load_lds_dwordx4 v[210:211], off
	v_lshl_add_u64 v[212:213], s[68:69], 0, v[186:187]
	s_mov_b32 m0, s67
	v_lshl_add_u64 v[214:215], s[42:43], 0, v[188:189]
	global_load_lds_dwordx4 v[212:213], off
	s_add_i32 m0, s67, 0x2000
	v_lshl_add_u64 v[212:213], s[68:69], 0, v[190:191]
	global_load_lds_dwordx4 v[212:213], off
	s_mov_b32 m0, s50
	v_lshl_add_u64 v[212:213], s[42:43], 0, v[184:185]
	global_load_lds_dwordx4 v[212:213], off
	s_mov_b32 m0, s51
	s_nop 0
	global_load_lds_dwordx4 v[214:215], off
	s_waitcnt vmcnt(8) lgkmcnt(0)
	s_barrier
	s_setprio 1
	v_mfma_f32_16x16x32_bf16 v[60:63], v[120:123], v[160:163], v[60:63]
	v_mfma_f32_16x16x32_bf16 v[60:63], v[132:135], v[164:167], v[60:63]
	v_mfma_f32_16x16x32_bf16 v[44:47], v[120:123], v[168:171], v[44:47]
	v_mfma_f32_16x16x32_bf16 v[44:47], v[132:135], v[172:175], v[44:47]
	v_mfma_f32_16x16x32_bf16 v[28:31], v[120:123], v[176:179], v[28:31]
	v_mfma_f32_16x16x32_bf16 v[28:31], v[132:135], v[180:183], v[28:31]
	v_mfma_f32_16x16x32_bf16 v[12:15], v[120:123], v[200:203], v[12:15]
	v_mfma_f32_16x16x32_bf16 v[12:15], v[132:135], v[204:207], v[12:15]
	v_mfma_f32_16x16x32_bf16 v[56:59], v[136:139], v[160:163], v[56:59]
	v_mfma_f32_16x16x32_bf16 v[56:59], v[140:143], v[164:167], v[56:59]
	v_mfma_f32_16x16x32_bf16 v[40:43], v[136:139], v[168:171], v[40:43]
	v_mfma_f32_16x16x32_bf16 v[40:43], v[140:143], v[172:175], v[40:43]
	v_mfma_f32_16x16x32_bf16 v[24:27], v[136:139], v[176:179], v[24:27]
	v_mfma_f32_16x16x32_bf16 v[24:27], v[140:143], v[180:183], v[24:27]
	v_mfma_f32_16x16x32_bf16 v[8:11], v[136:139], v[200:203], v[8:11]
	v_mfma_f32_16x16x32_bf16 v[8:11], v[140:143], v[204:207], v[8:11]
	v_mfma_f32_16x16x32_bf16 v[52:55], v[144:147], v[160:163], v[52:55]
	v_mfma_f32_16x16x32_bf16 v[52:55], v[148:151], v[164:167], v[52:55]
	v_mfma_f32_16x16x32_bf16 v[36:39], v[144:147], v[168:171], v[36:39]
	v_mfma_f32_16x16x32_bf16 v[36:39], v[148:151], v[172:175], v[36:39]
	v_mfma_f32_16x16x32_bf16 v[20:23], v[144:147], v[176:179], v[20:23]
	v_mfma_f32_16x16x32_bf16 v[20:23], v[148:151], v[180:183], v[20:23]
	v_mfma_f32_16x16x32_bf16 v[4:7], v[144:147], v[200:203], v[4:7]
	v_mfma_f32_16x16x32_bf16 v[4:7], v[148:151], v[204:207], v[4:7]
	v_mfma_f32_16x16x32_bf16 v[48:51], v[152:155], v[160:163], v[48:51]
	v_mfma_f32_16x16x32_bf16 v[48:51], v[156:159], v[164:167], v[48:51]
	v_mfma_f32_16x16x32_bf16 v[32:35], v[152:155], v[168:171], v[32:35]
	v_mfma_f32_16x16x32_bf16 v[32:35], v[156:159], v[172:175], v[32:35]
	s_setprio 2
	s_barrier
	v_mfma_f32_16x16x32_bf16 v[16:19], v[152:155], v[176:179], v[16:19]
	v_mfma_f32_16x16x32_bf16 v[16:19], v[156:159], v[180:183], v[16:19]
	v_mfma_f32_16x16x32_bf16 v[0:3], v[152:155], v[200:203], v[0:3]
	v_mfma_f32_16x16x32_bf16 v[0:3], v[156:159], v[204:207], v[0:3]
	s_setprio 0
	s_add_i32 s67, 0, 0x18000
	s_add_i32 s68, 0, 0x1c000
	v_add_u32_e32 v140, s67, v232
	v_add_u32_e32 v156, s68, v232
	ds_read_b128 v[120:123], v140
	ds_read_b128 v[132:135], v140 offset:1024
	ds_read_b128 v[136:139], v140 offset:2048
	ds_read_b128 v[140:143], v140 offset:3072
	ds_read_b128 v[144:147], v156
	ds_read_b128 v[148:151], v156 offset:1024
	ds_read_b128 v[152:155], v156 offset:2048
	ds_read_b128 v[156:159], v156 offset:3072
	s_add_u32 s42, s42, 0x40000
	s_addc_u32 s43, s43, 0
	s_mov_b32 m0, s54
	v_lshl_add_u64 v[216:217], s[42:43], 0, v[184:185]
	ds_read_b128 v[160:163], v235 offset:32768
	ds_read_b128 v[164:167], v235 offset:33792
	ds_read_b128 v[168:171], v235 offset:34816
	ds_read_b128 v[172:175], v235 offset:35840
	ds_read_b128 v[176:179], v235 offset:36864
	ds_read_b128 v[180:183], v235 offset:37888
	ds_read_b128 v[200:203], v235 offset:38912
	ds_read_b128 v[204:207], v235 offset:39936
	global_load_lds_dwordx4 v[216:217], off
	s_mov_b32 m0, s55
	v_lshl_add_u64 v[216:217], s[42:43], 0, v[188:189]
	global_load_lds_dwordx4 v[216:217], off
	s_waitcnt vmcnt(8) lgkmcnt(0)
	s_barrier
	s_setprio 1
	v_mfma_f32_16x16x32_bf16 v[128:131], v[120:123], v[160:163], v[128:131]
	v_mfma_f32_16x16x32_bf16 v[128:131], v[132:135], v[164:167], v[128:131]
	v_mfma_f32_16x16x32_bf16 v[108:111], v[120:123], v[168:171], v[108:111]
	v_mfma_f32_16x16x32_bf16 v[108:111], v[132:135], v[172:175], v[108:111]
	v_mfma_f32_16x16x32_bf16 v[92:95], v[120:123], v[176:179], v[92:95]
	v_mfma_f32_16x16x32_bf16 v[92:95], v[132:135], v[180:183], v[92:95]
	v_mfma_f32_16x16x32_bf16 v[76:79], v[120:123], v[200:203], v[76:79]
	v_mfma_f32_16x16x32_bf16 v[76:79], v[132:135], v[204:207], v[76:79]
	v_mfma_f32_16x16x32_bf16 v[124:127], v[136:139], v[160:163], v[124:127]
	v_mfma_f32_16x16x32_bf16 v[124:127], v[140:143], v[164:167], v[124:127]
	v_mfma_f32_16x16x32_bf16 v[104:107], v[136:139], v[168:171], v[104:107]
	v_mfma_f32_16x16x32_bf16 v[104:107], v[140:143], v[172:175], v[104:107]
	v_mfma_f32_16x16x32_bf16 v[88:91], v[136:139], v[176:179], v[88:91]
	v_mfma_f32_16x16x32_bf16 v[88:91], v[140:143], v[180:183], v[88:91]
	v_mfma_f32_16x16x32_bf16 v[72:75], v[136:139], v[200:203], v[72:75]
	v_mfma_f32_16x16x32_bf16 v[72:75], v[140:143], v[204:207], v[72:75]
	v_mfma_f32_16x16x32_bf16 v[116:119], v[144:147], v[160:163], v[116:119]
	v_mfma_f32_16x16x32_bf16 v[116:119], v[148:151], v[164:167], v[116:119]
	v_mfma_f32_16x16x32_bf16 v[100:103], v[144:147], v[168:171], v[100:103]
	v_mfma_f32_16x16x32_bf16 v[100:103], v[148:151], v[172:175], v[100:103]
	v_mfma_f32_16x16x32_bf16 v[84:87], v[144:147], v[176:179], v[84:87]
	v_mfma_f32_16x16x32_bf16 v[84:87], v[148:151], v[180:183], v[84:87]
	v_mfma_f32_16x16x32_bf16 v[68:71], v[144:147], v[200:203], v[68:71]
	v_mfma_f32_16x16x32_bf16 v[68:71], v[148:151], v[204:207], v[68:71]
	v_mfma_f32_16x16x32_bf16 v[112:115], v[152:155], v[160:163], v[112:115]
	v_mfma_f32_16x16x32_bf16 v[112:115], v[156:159], v[164:167], v[112:115]
	v_mfma_f32_16x16x32_bf16 v[96:99], v[152:155], v[168:171], v[96:99]
	v_mfma_f32_16x16x32_bf16 v[96:99], v[156:159], v[172:175], v[96:99]
	s_setprio 2
	s_barrier
	v_mfma_f32_16x16x32_bf16 v[80:83], v[152:155], v[176:179], v[80:83]
	v_mfma_f32_16x16x32_bf16 v[80:83], v[156:159], v[180:183], v[80:83]
	v_mfma_f32_16x16x32_bf16 v[64:67], v[152:155], v[200:203], v[64:67]
	v_mfma_f32_16x16x32_bf16 v[64:67], v[156:159], v[204:207], v[64:67]
	s_setprio 0
	s_add_i32 s42, s67, s49
	v_lshl_add_u64 v[208:209], v[208:209], 0, s[18:19]
	s_mov_b32 m0, s42
	ds_read_b128 v[160:163], v235 offset:49152
	ds_read_b128 v[164:167], v235 offset:50176
	ds_read_b128 v[168:171], v235 offset:51200
	ds_read_b128 v[172:175], v235 offset:52224
	ds_read_b128 v[176:179], v235 offset:53248
	ds_read_b128 v[180:183], v235 offset:54272
	ds_read_b128 v[200:203], v235 offset:55296
	ds_read_b128 v[204:207], v235 offset:56320
	global_load_lds_dwordx4 v[208:209], off
	s_add_i32 m0, s42, 0x2000
	s_add_u32 s40, s40, 0x40080
	v_lshl_add_u64 v[208:209], v[210:211], 0, s[18:19]
	s_addc_u32 s41, s41, 0
	s_add_i32 s42, s68, s49
	global_load_lds_dwordx4 v[208:209], off
	s_mov_b32 m0, s42
	v_lshl_add_u64 v[208:209], s[40:41], 0, v[186:187]
	global_load_lds_dwordx4 v[208:209], off
	s_add_i32 m0, s42, 0x2000
	v_lshl_add_u64 v[208:209], s[40:41], 0, v[190:191]
	global_load_lds_dwordx4 v[208:209], off
	s_mov_b32 m0, s57
	v_lshl_add_u64 v[208:209], v[212:213], 0, s[18:19]
	global_load_lds_dwordx4 v[208:209], off
	s_mov_b32 m0, s58
	v_lshl_add_u64 v[208:209], v[214:215], 0, s[18:19]
	global_load_lds_dwordx4 v[208:209], off
	s_waitcnt vmcnt(8) lgkmcnt(0)
	s_barrier
	s_setprio 1
	v_mfma_f32_16x16x32_bf16 v[60:63], v[120:123], v[160:163], v[60:63]
	v_mfma_f32_16x16x32_bf16 v[60:63], v[132:135], v[164:167], v[60:63]
	v_mfma_f32_16x16x32_bf16 v[44:47], v[120:123], v[168:171], v[44:47]
	v_mfma_f32_16x16x32_bf16 v[44:47], v[132:135], v[172:175], v[44:47]
	v_mfma_f32_16x16x32_bf16 v[28:31], v[120:123], v[176:179], v[28:31]
	v_mfma_f32_16x16x32_bf16 v[28:31], v[132:135], v[180:183], v[28:31]
	v_mfma_f32_16x16x32_bf16 v[12:15], v[120:123], v[200:203], v[12:15]
	v_mfma_f32_16x16x32_bf16 v[12:15], v[132:135], v[204:207], v[12:15]
	v_mfma_f32_16x16x32_bf16 v[56:59], v[136:139], v[160:163], v[56:59]
	v_mfma_f32_16x16x32_bf16 v[56:59], v[140:143], v[164:167], v[56:59]
	v_mfma_f32_16x16x32_bf16 v[40:43], v[136:139], v[168:171], v[40:43]
	v_mfma_f32_16x16x32_bf16 v[40:43], v[140:143], v[172:175], v[40:43]
	v_mfma_f32_16x16x32_bf16 v[24:27], v[136:139], v[176:179], v[24:27]
	v_mfma_f32_16x16x32_bf16 v[24:27], v[140:143], v[180:183], v[24:27]
	v_mfma_f32_16x16x32_bf16 v[8:11], v[136:139], v[200:203], v[8:11]
	v_mfma_f32_16x16x32_bf16 v[8:11], v[140:143], v[204:207], v[8:11]
	v_mfma_f32_16x16x32_bf16 v[52:55], v[144:147], v[160:163], v[52:55]
	v_mfma_f32_16x16x32_bf16 v[52:55], v[148:151], v[164:167], v[52:55]
	v_mfma_f32_16x16x32_bf16 v[36:39], v[144:147], v[168:171], v[36:39]
	v_mfma_f32_16x16x32_bf16 v[36:39], v[148:151], v[172:175], v[36:39]
	v_mfma_f32_16x16x32_bf16 v[20:23], v[144:147], v[176:179], v[20:23]
	v_mfma_f32_16x16x32_bf16 v[20:23], v[148:151], v[180:183], v[20:23]
	v_mfma_f32_16x16x32_bf16 v[4:7], v[144:147], v[200:203], v[4:7]
	v_mfma_f32_16x16x32_bf16 v[4:7], v[148:151], v[204:207], v[4:7]
	v_mfma_f32_16x16x32_bf16 v[48:51], v[152:155], v[160:163], v[48:51]
	v_mfma_f32_16x16x32_bf16 v[48:51], v[156:159], v[164:167], v[48:51]
	v_mfma_f32_16x16x32_bf16 v[32:35], v[152:155], v[168:171], v[32:35]
	v_mfma_f32_16x16x32_bf16 v[32:35], v[156:159], v[172:175], v[32:35]
	s_setprio 2
	s_barrier
	v_mfma_f32_16x16x32_bf16 v[16:19], v[152:155], v[176:179], v[16:19]
	v_mfma_f32_16x16x32_bf16 v[16:19], v[156:159], v[180:183], v[16:19]
	v_mfma_f32_16x16x32_bf16 v[0:3], v[152:155], v[200:203], v[0:3]
	v_mfma_f32_16x16x32_bf16 v[0:3], v[156:159], v[204:207], v[0:3]
	s_setprio 0
	s_add_i32 s66, s66, 2
	s_add_u32 s38, s38, 0x100
	s_addc_u32 s39, s39, 0
	s_add_u32 s64, s64, 0x100
	s_addc_u32 s65, s65, 0
	s_cmp_gt_u32 s66, 13
	s_cbranch_scc0 .LBB0_1146

.LBB0_1309:
	s_add_u32 s51, s26, 0x100
	s_addc_u32 s52, s27, 0
	s_mov_b32 s53, -2
	ds_read_b128 v[128:131], v197
	ds_read_b128 v[132:135], v197 offset:1024
	ds_read_b128 v[136:139], v197 offset:2048
	ds_read_b128 v[140:143], v197 offset:3072
	ds_read_b128 v[144:147], v198
	ds_read_b128 v[148:151], v198 offset:1024
	ds_read_b128 v[152:155], v198 offset:2048
	ds_read_b128 v[156:159], v198 offset:3072
	s_add_u32 s4, s24, 0x100
	s_addc_u32 s5, s25, 0
	s_cmp_eq_u32 s53, 40
	s_cselect_b32 s29, s21, s5
	s_cselect_b32 s28, s20, s4
	s_cselect_b32 s27, s23, s52
	s_cselect_b32 s26, s22, s51
	v_lshl_add_u64 v[212:213], s[24:25], 0, v[172:173]
	s_add_i32 m0, s36, 0xc000
	ds_read_b128 v[160:163], v199
	ds_read_b128 v[180:183], v199 offset:1024
	ds_read_b128 v[184:187], v199 offset:2048
	ds_read_b128 v[188:191], v199 offset:3072
	ds_read_b128 v[192:195], v199 offset:4096
	ds_read_b128 v[200:203], v199 offset:5120
	ds_read_b128 v[204:207], v199 offset:6144
	ds_read_b128 v[208:211], v199 offset:7168
	global_load_lds_dwordx4 v[212:213], off
	s_add_i32 m0, s36, 0xe000
	v_lshl_add_u64 v[212:213], s[24:25], 0, v[174:175]
	global_load_lds_dwordx4 v[212:213], off
	s_waitcnt vmcnt(8) lgkmcnt(0)
	s_barrier
	s_setprio 1
	v_mfma_f32_16x16x32_bf16 v[124:127], v[128:131], v[160:163], 0
	v_mfma_f32_16x16x32_bf16 v[124:127], v[132:135], v[180:183], v[124:127]
	v_mfma_f32_16x16x32_bf16 v[116:119], v[128:131], v[184:187], 0
	v_mfma_f32_16x16x32_bf16 v[116:119], v[132:135], v[188:191], v[116:119]
	v_mfma_f32_16x16x32_bf16 v[88:91], v[128:131], v[192:195], 0
	v_mfma_f32_16x16x32_bf16 v[88:91], v[132:135], v[200:203], v[88:91]
	v_mfma_f32_16x16x32_bf16 v[72:75], v[128:131], v[204:207], 0
	v_mfma_f32_16x16x32_bf16 v[72:75], v[132:135], v[208:211], v[72:75]
	v_mfma_f32_16x16x32_bf16 v[120:123], v[136:139], v[160:163], 0
	v_mfma_f32_16x16x32_bf16 v[120:123], v[140:143], v[180:183], v[120:123]
	v_mfma_f32_16x16x32_bf16 v[108:111], v[136:139], v[184:187], 0
	v_mfma_f32_16x16x32_bf16 v[108:111], v[140:143], v[188:191], v[108:111]
	v_mfma_f32_16x16x32_bf16 v[100:103], v[136:139], v[192:195], 0
	v_mfma_f32_16x16x32_bf16 v[100:103], v[140:143], v[200:203], v[100:103]
	v_mfma_f32_16x16x32_bf16 v[76:79], v[136:139], v[204:207], 0
	v_mfma_f32_16x16x32_bf16 v[76:79], v[140:143], v[208:211], v[76:79]
	v_mfma_f32_16x16x32_bf16 v[112:115], v[144:147], v[160:163], 0
	v_mfma_f32_16x16x32_bf16 v[112:115], v[148:151], v[180:183], v[112:115]
	v_mfma_f32_16x16x32_bf16 v[96:99], v[144:147], v[184:187], 0
	v_mfma_f32_16x16x32_bf16 v[96:99], v[148:151], v[188:191], v[96:99]
	v_mfma_f32_16x16x32_bf16 v[80:83], v[144:147], v[192:195], 0
	v_mfma_f32_16x16x32_bf16 v[80:83], v[148:151], v[200:203], v[80:83]
	v_mfma_f32_16x16x32_bf16 v[64:67], v[144:147], v[204:207], 0
	v_mfma_f32_16x16x32_bf16 v[64:67], v[148:151], v[208:211], v[64:67]
	v_mfma_f32_16x16x32_bf16 v[104:107], v[152:155], v[160:163], 0
	v_mfma_f32_16x16x32_bf16 v[104:107], v[156:159], v[180:183], v[104:107]
	v_mfma_f32_16x16x32_bf16 v[92:95], v[152:155], v[184:187], 0
	v_mfma_f32_16x16x32_bf16 v[92:95], v[156:159], v[188:191], v[92:95]
	s_setprio 2
	s_barrier
	v_mfma_f32_16x16x32_bf16 v[84:87], v[152:155], v[192:195], 0
	v_mfma_f32_16x16x32_bf16 v[84:87], v[156:159], v[200:203], v[84:87]
	v_mfma_f32_16x16x32_bf16 v[68:71], v[152:155], v[204:207], 0
	v_mfma_f32_16x16x32_bf16 v[68:71], v[156:159], v[208:211], v[68:71]
	s_setprio 0
	s_add_i32 s24, s45, s35
	v_lshl_add_u64 v[212:213], s[26:27], 0, v[166:167]
	s_mov_b32 m0, s24
	ds_read_b128 v[160:163], v199 offset:16384
	ds_read_b128 v[180:183], v199 offset:17408
	ds_read_b128 v[184:187], v199 offset:18432
	ds_read_b128 v[188:191], v199 offset:19456
	ds_read_b128 v[192:195], v199 offset:20480
	ds_read_b128 v[200:203], v199 offset:21504
	ds_read_b128 v[204:207], v199 offset:22528
	ds_read_b128 v[208:211], v199 offset:23552
	global_load_lds_dwordx4 v[212:213], off
	s_add_i32 m0, s24, 0x2000
	s_add_u32 s24, s26, 0xb0000
	v_lshl_add_u64 v[214:215], s[26:27], 0, v[170:171]
	s_addc_u32 s25, s27, 0
	s_add_i32 s54, s46, s35
	global_load_lds_dwordx4 v[214:215], off
	v_lshl_add_u64 v[216:217], s[24:25], 0, v[166:167]
	s_mov_b32 m0, s54
	v_lshl_add_u64 v[218:219], s[28:29], 0, v[168:169]
	global_load_lds_dwordx4 v[216:217], off
	s_add_i32 m0, s54, 0x2000
	v_lshl_add_u64 v[216:217], s[24:25], 0, v[170:171]
	global_load_lds_dwordx4 v[216:217], off
	s_mov_b32 m0, s36
	v_lshl_add_u64 v[216:217], s[28:29], 0, v[164:165]
	global_load_lds_dwordx4 v[216:217], off
	s_mov_b32 m0, s37
	s_nop 0
	global_load_lds_dwordx4 v[218:219], off
	s_waitcnt vmcnt(8) lgkmcnt(0)
	s_barrier
	s_setprio 1
	v_mfma_f32_16x16x32_bf16 v[56:59], v[128:131], v[160:163], 0
	v_mfma_f32_16x16x32_bf16 v[56:59], v[132:135], v[180:183], v[56:59]
	v_mfma_f32_16x16x32_bf16 v[40:43], v[128:131], v[184:187], 0
	v_mfma_f32_16x16x32_bf16 v[40:43], v[132:135], v[188:191], v[40:43]
	v_mfma_f32_16x16x32_bf16 v[24:27], v[128:131], v[192:195], 0
	v_mfma_f32_16x16x32_bf16 v[24:27], v[132:135], v[200:203], v[24:27]
	v_mfma_f32_16x16x32_bf16 v[8:11], v[128:131], v[204:207], 0
	v_mfma_f32_16x16x32_bf16 v[8:11], v[132:135], v[208:211], v[8:11]
	v_mfma_f32_16x16x32_bf16 v[60:63], v[136:139], v[160:163], 0
	v_mfma_f32_16x16x32_bf16 v[60:63], v[140:143], v[180:183], v[60:63]
	v_mfma_f32_16x16x32_bf16 v[44:47], v[136:139], v[184:187], 0
	v_mfma_f32_16x16x32_bf16 v[44:47], v[140:143], v[188:191], v[44:47]
	v_mfma_f32_16x16x32_bf16 v[28:31], v[136:139], v[192:195], 0
	v_mfma_f32_16x16x32_bf16 v[28:31], v[140:143], v[200:203], v[28:31]
	v_mfma_f32_16x16x32_bf16 v[12:15], v[136:139], v[204:207], 0
	v_mfma_f32_16x16x32_bf16 v[12:15], v[140:143], v[208:211], v[12:15]
	v_mfma_f32_16x16x32_bf16 v[48:51], v[144:147], v[160:163], 0
	v_mfma_f32_16x16x32_bf16 v[48:51], v[148:151], v[180:183], v[48:51]
	v_mfma_f32_16x16x32_bf16 v[32:35], v[144:147], v[184:187], 0
	v_mfma_f32_16x16x32_bf16 v[32:35], v[148:151], v[188:191], v[32:35]
	v_mfma_f32_16x16x32_bf16 v[16:19], v[144:147], v[192:195], 0
	v_mfma_f32_16x16x32_bf16 v[16:19], v[148:151], v[200:203], v[16:19]
	v_mfma_f32_16x16x32_bf16 v[0:3], v[144:147], v[204:207], 0
	v_mfma_f32_16x16x32_bf16 v[0:3], v[148:151], v[208:211], v[0:3]
	v_mfma_f32_16x16x32_bf16 v[52:55], v[152:155], v[160:163], 0
	v_mfma_f32_16x16x32_bf16 v[52:55], v[156:159], v[180:183], v[52:55]
	v_mfma_f32_16x16x32_bf16 v[36:39], v[152:155], v[184:187], 0
	v_mfma_f32_16x16x32_bf16 v[36:39], v[156:159], v[188:191], v[36:39]
	s_setprio 2
	s_barrier
	v_mfma_f32_16x16x32_bf16 v[20:23], v[152:155], v[192:195], 0
	v_mfma_f32_16x16x32_bf16 v[20:23], v[156:159], v[200:203], v[20:23]
	v_mfma_f32_16x16x32_bf16 v[4:7], v[152:155], v[204:207], 0
	v_mfma_f32_16x16x32_bf16 v[4:7], v[156:159], v[208:211], v[4:7]
	s_setprio 0
	s_add_i32 s54, 0, 0x18000
	s_add_i32 s55, 0, 0x1c000
	v_add_u32_e32 v140, s54, v196
	v_add_u32_e32 v156, s55, v196
	ds_read_b128 v[128:131], v140
	ds_read_b128 v[132:135], v140 offset:1024
	ds_read_b128 v[136:139], v140 offset:2048
	ds_read_b128 v[140:143], v140 offset:3072
	ds_read_b128 v[144:147], v156
	ds_read_b128 v[148:151], v156 offset:1024
	ds_read_b128 v[152:155], v156 offset:2048
	ds_read_b128 v[156:159], v156 offset:3072
	s_add_u32 s24, s28, 0xb0000
	s_addc_u32 s25, s29, 0
	s_mov_b32 m0, s38
	v_lshl_add_u64 v[220:221], s[24:25], 0, v[164:165]
	ds_read_b128 v[160:163], v199 offset:32768
	ds_read_b128 v[180:183], v199 offset:33792
	ds_read_b128 v[184:187], v199 offset:34816
	ds_read_b128 v[188:191], v199 offset:35840
	ds_read_b128 v[192:195], v199 offset:36864
	ds_read_b128 v[200:203], v199 offset:37888
	ds_read_b128 v[204:207], v199 offset:38912
	ds_read_b128 v[208:211], v199 offset:39936
	global_load_lds_dwordx4 v[220:221], off
	s_mov_b32 m0, s39
	v_lshl_add_u64 v[220:221], s[24:25], 0, v[168:169]
	global_load_lds_dwordx4 v[220:221], off
	s_waitcnt vmcnt(8) lgkmcnt(0)
	s_barrier
	s_setprio 1
	v_mfma_f32_16x16x32_bf16 v[124:127], v[128:131], v[160:163], v[124:127]
	v_mfma_f32_16x16x32_bf16 v[124:127], v[132:135], v[180:183], v[124:127]
	v_mfma_f32_16x16x32_bf16 v[116:119], v[128:131], v[184:187], v[116:119]
	v_mfma_f32_16x16x32_bf16 v[116:119], v[132:135], v[188:191], v[116:119]
	v_mfma_f32_16x16x32_bf16 v[88:91], v[128:131], v[192:195], v[88:91]
	v_mfma_f32_16x16x32_bf16 v[88:91], v[132:135], v[200:203], v[88:91]
	v_mfma_f32_16x16x32_bf16 v[72:75], v[128:131], v[204:207], v[72:75]
	v_mfma_f32_16x16x32_bf16 v[72:75], v[132:135], v[208:211], v[72:75]
	v_mfma_f32_16x16x32_bf16 v[120:123], v[136:139], v[160:163], v[120:123]
	v_mfma_f32_16x16x32_bf16 v[120:123], v[140:143], v[180:183], v[120:123]
	v_mfma_f32_16x16x32_bf16 v[108:111], v[136:139], v[184:187], v[108:111]
	v_mfma_f32_16x16x32_bf16 v[108:111], v[140:143], v[188:191], v[108:111]
	v_mfma_f32_16x16x32_bf16 v[100:103], v[136:139], v[192:195], v[100:103]
	v_mfma_f32_16x16x32_bf16 v[100:103], v[140:143], v[200:203], v[100:103]
	v_mfma_f32_16x16x32_bf16 v[76:79], v[136:139], v[204:207], v[76:79]
	v_mfma_f32_16x16x32_bf16 v[76:79], v[140:143], v[208:211], v[76:79]
	v_mfma_f32_16x16x32_bf16 v[112:115], v[144:147], v[160:163], v[112:115]
	v_mfma_f32_16x16x32_bf16 v[112:115], v[148:151], v[180:183], v[112:115]
	v_mfma_f32_16x16x32_bf16 v[96:99], v[144:147], v[184:187], v[96:99]
	v_mfma_f32_16x16x32_bf16 v[96:99], v[148:151], v[188:191], v[96:99]
	v_mfma_f32_16x16x32_bf16 v[80:83], v[144:147], v[192:195], v[80:83]
	v_mfma_f32_16x16x32_bf16 v[80:83], v[148:151], v[200:203], v[80:83]
	v_mfma_f32_16x16x32_bf16 v[64:67], v[144:147], v[204:207], v[64:67]
	v_mfma_f32_16x16x32_bf16 v[64:67], v[148:151], v[208:211], v[64:67]
	v_mfma_f32_16x16x32_bf16 v[104:107], v[152:155], v[160:163], v[104:107]
	v_mfma_f32_16x16x32_bf16 v[104:107], v[156:159], v[180:183], v[104:107]
	v_mfma_f32_16x16x32_bf16 v[92:95], v[152:155], v[184:187], v[92:95]
	v_mfma_f32_16x16x32_bf16 v[92:95], v[156:159], v[188:191], v[92:95]
	s_setprio 2
	s_barrier
	v_mfma_f32_16x16x32_bf16 v[84:87], v[152:155], v[192:195], v[84:87]
	v_mfma_f32_16x16x32_bf16 v[84:87], v[156:159], v[200:203], v[84:87]
	v_mfma_f32_16x16x32_bf16 v[68:71], v[152:155], v[204:207], v[68:71]
	v_mfma_f32_16x16x32_bf16 v[68:71], v[156:159], v[208:211], v[68:71]
	s_setprio 0
	s_add_i32 s24, s54, s35
	v_lshl_add_u64 v[212:213], v[212:213], 0, s[16:17]
	s_mov_b32 m0, s24
	ds_read_b128 v[160:163], v199 offset:49152
	ds_read_b128 v[180:183], v199 offset:50176
	ds_read_b128 v[184:187], v199 offset:51200
	ds_read_b128 v[188:191], v199 offset:52224
	ds_read_b128 v[192:195], v199 offset:53248
	ds_read_b128 v[200:203], v199 offset:54272
	ds_read_b128 v[204:207], v199 offset:55296
	ds_read_b128 v[208:211], v199 offset:56320
	global_load_lds_dwordx4 v[212:213], off
	s_add_i32 m0, s24, 0x2000
	s_add_u32 s24, s26, 0xb0080
	v_lshl_add_u64 v[212:213], v[214:215], 0, s[16:17]
	s_addc_u32 s25, s27, 0
	s_add_i32 s26, s55, s35
	global_load_lds_dwordx4 v[212:213], off
	s_mov_b32 m0, s26
	v_lshl_add_u64 v[212:213], s[24:25], 0, v[166:167]
	global_load_lds_dwordx4 v[212:213], off
	s_add_i32 m0, s26, 0x2000
	v_lshl_add_u64 v[212:213], s[24:25], 0, v[170:171]
	global_load_lds_dwordx4 v[212:213], off
	s_mov_b32 m0, s41
	v_lshl_add_u64 v[212:213], v[216:217], 0, s[16:17]
	global_load_lds_dwordx4 v[212:213], off
	s_mov_b32 m0, s42
	v_lshl_add_u64 v[212:213], v[218:219], 0, s[16:17]
	global_load_lds_dwordx4 v[212:213], off
	s_waitcnt vmcnt(8) lgkmcnt(0)
	s_barrier
	s_setprio 1
	v_mfma_f32_16x16x32_bf16 v[56:59], v[128:131], v[160:163], v[56:59]
	v_mfma_f32_16x16x32_bf16 v[56:59], v[132:135], v[180:183], v[56:59]
	v_mfma_f32_16x16x32_bf16 v[40:43], v[128:131], v[184:187], v[40:43]
	v_mfma_f32_16x16x32_bf16 v[40:43], v[132:135], v[188:191], v[40:43]
	v_mfma_f32_16x16x32_bf16 v[24:27], v[128:131], v[192:195], v[24:27]
	v_mfma_f32_16x16x32_bf16 v[24:27], v[132:135], v[200:203], v[24:27]
	v_mfma_f32_16x16x32_bf16 v[8:11], v[128:131], v[204:207], v[8:11]
	v_mfma_f32_16x16x32_bf16 v[8:11], v[132:135], v[208:211], v[8:11]
	v_mfma_f32_16x16x32_bf16 v[60:63], v[136:139], v[160:163], v[60:63]
	v_mfma_f32_16x16x32_bf16 v[60:63], v[140:143], v[180:183], v[60:63]
	v_mfma_f32_16x16x32_bf16 v[44:47], v[136:139], v[184:187], v[44:47]
	v_mfma_f32_16x16x32_bf16 v[44:47], v[140:143], v[188:191], v[44:47]
	v_mfma_f32_16x16x32_bf16 v[28:31], v[136:139], v[192:195], v[28:31]
	v_mfma_f32_16x16x32_bf16 v[28:31], v[140:143], v[200:203], v[28:31]
	v_mfma_f32_16x16x32_bf16 v[12:15], v[136:139], v[204:207], v[12:15]
	v_mfma_f32_16x16x32_bf16 v[12:15], v[140:143], v[208:211], v[12:15]
	v_mfma_f32_16x16x32_bf16 v[48:51], v[144:147], v[160:163], v[48:51]
	v_mfma_f32_16x16x32_bf16 v[48:51], v[148:151], v[180:183], v[48:51]
	v_mfma_f32_16x16x32_bf16 v[32:35], v[144:147], v[184:187], v[32:35]
	v_mfma_f32_16x16x32_bf16 v[32:35], v[148:151], v[188:191], v[32:35]
	v_mfma_f32_16x16x32_bf16 v[16:19], v[144:147], v[192:195], v[16:19]
	v_mfma_f32_16x16x32_bf16 v[16:19], v[148:151], v[200:203], v[16:19]
	v_mfma_f32_16x16x32_bf16 v[0:3], v[144:147], v[204:207], v[0:3]
	v_mfma_f32_16x16x32_bf16 v[0:3], v[148:151], v[208:211], v[0:3]
	v_mfma_f32_16x16x32_bf16 v[52:55], v[152:155], v[160:163], v[52:55]
	v_mfma_f32_16x16x32_bf16 v[52:55], v[156:159], v[180:183], v[52:55]
	v_mfma_f32_16x16x32_bf16 v[36:39], v[152:155], v[184:187], v[36:39]
	v_mfma_f32_16x16x32_bf16 v[36:39], v[156:159], v[188:191], v[36:39]
	s_setprio 2
	s_barrier
	v_mfma_f32_16x16x32_bf16 v[20:23], v[152:155], v[192:195], v[20:23]
	v_mfma_f32_16x16x32_bf16 v[20:23], v[156:159], v[200:203], v[20:23]
	v_mfma_f32_16x16x32_bf16 v[4:7], v[152:155], v[204:207], v[4:7]
	v_mfma_f32_16x16x32_bf16 v[4:7], v[156:159], v[208:211], v[4:7]
	s_setprio 0
	s_add_i32 s53, s53, 2
	s_add_u32 s51, s51, 0x100
	s_addc_u32 s52, s52, 0
	s_cmp_gt_u32 s53, 41
	s_mov_b64 s[24:25], s[4:5]
.LBB0_1310:
	ds_read_b128 v[128:131], v197
	ds_read_b128 v[132:135], v197 offset:1024
	ds_read_b128 v[136:139], v197 offset:2048
	ds_read_b128 v[140:143], v197 offset:3072
	ds_read_b128 v[144:147], v198
	ds_read_b128 v[148:151], v198 offset:1024
	ds_read_b128 v[152:155], v198 offset:2048
	ds_read_b128 v[156:159], v198 offset:3072
	s_add_u32 s4, s24, 0x100
	s_addc_u32 s5, s25, 0
	s_cmp_eq_u32 s53, 40
	s_cselect_b32 s29, s21, s5
	s_cselect_b32 s28, s20, s4
	s_cselect_b32 s27, s23, s52
	s_cselect_b32 s26, s22, s51
	v_lshl_add_u64 v[212:213], s[24:25], 0, v[172:173]
	s_add_i32 m0, s36, 0xc000
	ds_read_b128 v[160:163], v199
	ds_read_b128 v[180:183], v199 offset:1024
	ds_read_b128 v[184:187], v199 offset:2048
	ds_read_b128 v[188:191], v199 offset:3072
	ds_read_b128 v[192:195], v199 offset:4096
	ds_read_b128 v[200:203], v199 offset:5120
	ds_read_b128 v[204:207], v199 offset:6144
	ds_read_b128 v[208:211], v199 offset:7168
	global_load_lds_dwordx4 v[212:213], off
	s_add_i32 m0, s36, 0xe000
	v_lshl_add_u64 v[212:213], s[24:25], 0, v[174:175]
	global_load_lds_dwordx4 v[212:213], off
	s_waitcnt vmcnt(8) lgkmcnt(0)
	s_barrier
	s_setprio 1
	v_mfma_f32_16x16x32_bf16 v[124:127], v[128:131], v[160:163], v[124:127]
	v_mfma_f32_16x16x32_bf16 v[124:127], v[132:135], v[180:183], v[124:127]
	v_mfma_f32_16x16x32_bf16 v[116:119], v[128:131], v[184:187], v[116:119]
	v_mfma_f32_16x16x32_bf16 v[116:119], v[132:135], v[188:191], v[116:119]
	v_mfma_f32_16x16x32_bf16 v[88:91], v[128:131], v[192:195], v[88:91]
	v_mfma_f32_16x16x32_bf16 v[88:91], v[132:135], v[200:203], v[88:91]
	v_mfma_f32_16x16x32_bf16 v[72:75], v[128:131], v[204:207], v[72:75]
	v_mfma_f32_16x16x32_bf16 v[72:75], v[132:135], v[208:211], v[72:75]
	v_mfma_f32_16x16x32_bf16 v[120:123], v[136:139], v[160:163], v[120:123]
	v_mfma_f32_16x16x32_bf16 v[120:123], v[140:143], v[180:183], v[120:123]
	v_mfma_f32_16x16x32_bf16 v[108:111], v[136:139], v[184:187], v[108:111]
	v_mfma_f32_16x16x32_bf16 v[108:111], v[140:143], v[188:191], v[108:111]
	v_mfma_f32_16x16x32_bf16 v[100:103], v[136:139], v[192:195], v[100:103]
	v_mfma_f32_16x16x32_bf16 v[100:103], v[140:143], v[200:203], v[100:103]
	v_mfma_f32_16x16x32_bf16 v[76:79], v[136:139], v[204:207], v[76:79]
	v_mfma_f32_16x16x32_bf16 v[76:79], v[140:143], v[208:211], v[76:79]
	v_mfma_f32_16x16x32_bf16 v[112:115], v[144:147], v[160:163], v[112:115]
	v_mfma_f32_16x16x32_bf16 v[112:115], v[148:151], v[180:183], v[112:115]
	v_mfma_f32_16x16x32_bf16 v[96:99], v[144:147], v[184:187], v[96:99]
	v_mfma_f32_16x16x32_bf16 v[96:99], v[148:151], v[188:191], v[96:99]
	v_mfma_f32_16x16x32_bf16 v[80:83], v[144:147], v[192:195], v[80:83]
	v_mfma_f32_16x16x32_bf16 v[80:83], v[148:151], v[200:203], v[80:83]
	v_mfma_f32_16x16x32_bf16 v[64:67], v[144:147], v[204:207], v[64:67]
	v_mfma_f32_16x16x32_bf16 v[64:67], v[148:151], v[208:211], v[64:67]
	v_mfma_f32_16x16x32_bf16 v[104:107], v[152:155], v[160:163], v[104:107]
	v_mfma_f32_16x16x32_bf16 v[104:107], v[156:159], v[180:183], v[104:107]
	v_mfma_f32_16x16x32_bf16 v[92:95], v[152:155], v[184:187], v[92:95]
	v_mfma_f32_16x16x32_bf16 v[92:95], v[156:159], v[188:191], v[92:95]
	s_setprio 2
	s_barrier
	v_mfma_f32_16x16x32_bf16 v[84:87], v[152:155], v[192:195], v[84:87]
	v_mfma_f32_16x16x32_bf16 v[84:87], v[156:159], v[200:203], v[84:87]
	v_mfma_f32_16x16x32_bf16 v[68:71], v[152:155], v[204:207], v[68:71]
	v_mfma_f32_16x16x32_bf16 v[68:71], v[156:159], v[208:211], v[68:71]
	s_setprio 0
	s_add_i32 s24, s45, s35
	v_lshl_add_u64 v[212:213], s[26:27], 0, v[166:167]
	s_mov_b32 m0, s24
	ds_read_b128 v[160:163], v199 offset:16384
	ds_read_b128 v[180:183], v199 offset:17408
	ds_read_b128 v[184:187], v199 offset:18432
	ds_read_b128 v[188:191], v199 offset:19456
	ds_read_b128 v[192:195], v199 offset:20480
	ds_read_b128 v[200:203], v199 offset:21504
	ds_read_b128 v[204:207], v199 offset:22528
	ds_read_b128 v[208:211], v199 offset:23552
	global_load_lds_dwordx4 v[212:213], off
	s_add_i32 m0, s24, 0x2000
	s_add_u32 s24, s26, 0xb0000
	v_lshl_add_u64 v[214:215], s[26:27], 0, v[170:171]
	s_addc_u32 s25, s27, 0
	s_add_i32 s54, s46, s35
	global_load_lds_dwordx4 v[214:215], off
	v_lshl_add_u64 v[216:217], s[24:25], 0, v[166:167]
	s_mov_b32 m0, s54
	v_lshl_add_u64 v[218:219], s[28:29], 0, v[168:169]
	global_load_lds_dwordx4 v[216:217], off
	s_add_i32 m0, s54, 0x2000
	v_lshl_add_u64 v[216:217], s[24:25], 0, v[170:171]
	global_load_lds_dwordx4 v[216:217], off
	s_mov_b32 m0, s36
	v_lshl_add_u64 v[216:217], s[28:29], 0, v[164:165]
	global_load_lds_dwordx4 v[216:217], off
	s_mov_b32 m0, s37
	s_nop 0
	global_load_lds_dwordx4 v[218:219], off
	s_waitcnt vmcnt(8) lgkmcnt(0)
	s_barrier
	s_setprio 1
	v_mfma_f32_16x16x32_bf16 v[56:59], v[128:131], v[160:163], v[56:59]
	v_mfma_f32_16x16x32_bf16 v[56:59], v[132:135], v[180:183], v[56:59]
	v_mfma_f32_16x16x32_bf16 v[40:43], v[128:131], v[184:187], v[40:43]
	v_mfma_f32_16x16x32_bf16 v[40:43], v[132:135], v[188:191], v[40:43]
	v_mfma_f32_16x16x32_bf16 v[24:27], v[128:131], v[192:195], v[24:27]
	v_mfma_f32_16x16x32_bf16 v[24:27], v[132:135], v[200:203], v[24:27]
	v_mfma_f32_16x16x32_bf16 v[8:11], v[128:131], v[204:207], v[8:11]
	v_mfma_f32_16x16x32_bf16 v[8:11], v[132:135], v[208:211], v[8:11]
	v_mfma_f32_16x16x32_bf16 v[60:63], v[136:139], v[160:163], v[60:63]
	v_mfma_f32_16x16x32_bf16 v[60:63], v[140:143], v[180:183], v[60:63]
	v_mfma_f32_16x16x32_bf16 v[44:47], v[136:139], v[184:187], v[44:47]
	v_mfma_f32_16x16x32_bf16 v[44:47], v[140:143], v[188:191], v[44:47]
	v_mfma_f32_16x16x32_bf16 v[28:31], v[136:139], v[192:195], v[28:31]
	v_mfma_f32_16x16x32_bf16 v[28:31], v[140:143], v[200:203], v[28:31]
	v_mfma_f32_16x16x32_bf16 v[12:15], v[136:139], v[204:207], v[12:15]
	v_mfma_f32_16x16x32_bf16 v[12:15], v[140:143], v[208:211], v[12:15]
	v_mfma_f32_16x16x32_bf16 v[48:51], v[144:147], v[160:163], v[48:51]
	v_mfma_f32_16x16x32_bf16 v[48:51], v[148:151], v[180:183], v[48:51]
	v_mfma_f32_16x16x32_bf16 v[32:35], v[144:147], v[184:187], v[32:35]
	v_mfma_f32_16x16x32_bf16 v[32:35], v[148:151], v[188:191], v[32:35]
	v_mfma_f32_16x16x32_bf16 v[16:19], v[144:147], v[192:195], v[16:19]
	v_mfma_f32_16x16x32_bf16 v[16:19], v[148:151], v[200:203], v[16:19]
	v_mfma_f32_16x16x32_bf16 v[0:3], v[144:147], v[204:207], v[0:3]
	v_mfma_f32_16x16x32_bf16 v[0:3], v[148:151], v[208:211], v[0:3]
	v_mfma_f32_16x16x32_bf16 v[52:55], v[152:155], v[160:163], v[52:55]
	v_mfma_f32_16x16x32_bf16 v[52:55], v[156:159], v[180:183], v[52:55]
	v_mfma_f32_16x16x32_bf16 v[36:39], v[152:155], v[184:187], v[36:39]
	v_mfma_f32_16x16x32_bf16 v[36:39], v[156:159], v[188:191], v[36:39]
	s_setprio 2
	s_barrier
	v_mfma_f32_16x16x32_bf16 v[20:23], v[152:155], v[192:195], v[20:23]
	v_mfma_f32_16x16x32_bf16 v[20:23], v[156:159], v[200:203], v[20:23]
	v_mfma_f32_16x16x32_bf16 v[4:7], v[152:155], v[204:207], v[4:7]
	v_mfma_f32_16x16x32_bf16 v[4:7], v[156:159], v[208:211], v[4:7]
	s_setprio 0
	s_add_i32 s54, 0, 0x18000
	s_add_i32 s55, 0, 0x1c000
	v_add_u32_e32 v140, s54, v196
	v_add_u32_e32 v156, s55, v196
	ds_read_b128 v[128:131], v140
	ds_read_b128 v[132:135], v140 offset:1024
	ds_read_b128 v[136:139], v140 offset:2048
	ds_read_b128 v[140:143], v140 offset:3072
	ds_read_b128 v[144:147], v156
	ds_read_b128 v[148:151], v156 offset:1024
	ds_read_b128 v[152:155], v156 offset:2048
	ds_read_b128 v[156:159], v156 offset:3072
	s_add_u32 s24, s28, 0xb0000
	s_addc_u32 s25, s29, 0
	s_mov_b32 m0, s38
	v_lshl_add_u64 v[220:221], s[24:25], 0, v[164:165]
	ds_read_b128 v[160:163], v199 offset:32768
	ds_read_b128 v[180:183], v199 offset:33792
	ds_read_b128 v[184:187], v199 offset:34816
	ds_read_b128 v[188:191], v199 offset:35840
	ds_read_b128 v[192:195], v199 offset:36864
	ds_read_b128 v[200:203], v199 offset:37888
	ds_read_b128 v[204:207], v199 offset:38912
	ds_read_b128 v[208:211], v199 offset:39936
	global_load_lds_dwordx4 v[220:221], off
	s_mov_b32 m0, s39
	v_lshl_add_u64 v[220:221], s[24:25], 0, v[168:169]
	global_load_lds_dwordx4 v[220:221], off
	s_waitcnt vmcnt(8) lgkmcnt(0)
	s_barrier
	s_setprio 1
	v_mfma_f32_16x16x32_bf16 v[124:127], v[128:131], v[160:163], v[124:127]
	v_mfma_f32_16x16x32_bf16 v[124:127], v[132:135], v[180:183], v[124:127]
	v_mfma_f32_16x16x32_bf16 v[116:119], v[128:131], v[184:187], v[116:119]
	v_mfma_f32_16x16x32_bf16 v[116:119], v[132:135], v[188:191], v[116:119]
	v_mfma_f32_16x16x32_bf16 v[88:91], v[128:131], v[192:195], v[88:91]
	v_mfma_f32_16x16x32_bf16 v[88:91], v[132:135], v[200:203], v[88:91]
	v_mfma_f32_16x16x32_bf16 v[72:75], v[128:131], v[204:207], v[72:75]
	v_mfma_f32_16x16x32_bf16 v[72:75], v[132:135], v[208:211], v[72:75]
	v_mfma_f32_16x16x32_bf16 v[120:123], v[136:139], v[160:163], v[120:123]
	v_mfma_f32_16x16x32_bf16 v[120:123], v[140:143], v[180:183], v[120:123]
	v_mfma_f32_16x16x32_bf16 v[108:111], v[136:139], v[184:187], v[108:111]
	v_mfma_f32_16x16x32_bf16 v[108:111], v[140:143], v[188:191], v[108:111]
	v_mfma_f32_16x16x32_bf16 v[100:103], v[136:139], v[192:195], v[100:103]
	v_mfma_f32_16x16x32_bf16 v[100:103], v[140:143], v[200:203], v[100:103]
	v_mfma_f32_16x16x32_bf16 v[76:79], v[136:139], v[204:207], v[76:79]
	v_mfma_f32_16x16x32_bf16 v[76:79], v[140:143], v[208:211], v[76:79]
	v_mfma_f32_16x16x32_bf16 v[112:115], v[144:147], v[160:163], v[112:115]
	v_mfma_f32_16x16x32_bf16 v[112:115], v[148:151], v[180:183], v[112:115]
	v_mfma_f32_16x16x32_bf16 v[96:99], v[144:147], v[184:187], v[96:99]
	v_mfma_f32_16x16x32_bf16 v[96:99], v[148:151], v[188:191], v[96:99]
	v_mfma_f32_16x16x32_bf16 v[80:83], v[144:147], v[192:195], v[80:83]
	v_mfma_f32_16x16x32_bf16 v[80:83], v[148:151], v[200:203], v[80:83]
	v_mfma_f32_16x16x32_bf16 v[64:67], v[144:147], v[204:207], v[64:67]
	v_mfma_f32_16x16x32_bf16 v[64:67], v[148:151], v[208:211], v[64:67]
	v_mfma_f32_16x16x32_bf16 v[104:107], v[152:155], v[160:163], v[104:107]
	v_mfma_f32_16x16x32_bf16 v[104:107], v[156:159], v[180:183], v[104:107]
	v_mfma_f32_16x16x32_bf16 v[92:95], v[152:155], v[184:187], v[92:95]
	v_mfma_f32_16x16x32_bf16 v[92:95], v[156:159], v[188:191], v[92:95]
	s_setprio 2
	s_barrier
	v_mfma_f32_16x16x32_bf16 v[84:87], v[152:155], v[192:195], v[84:87]
	v_mfma_f32_16x16x32_bf16 v[84:87], v[156:159], v[200:203], v[84:87]
	v_mfma_f32_16x16x32_bf16 v[68:71], v[152:155], v[204:207], v[68:71]
	v_mfma_f32_16x16x32_bf16 v[68:71], v[156:159], v[208:211], v[68:71]
	s_setprio 0
	s_add_i32 s24, s54, s35
	v_lshl_add_u64 v[212:213], v[212:213], 0, s[16:17]
	s_mov_b32 m0, s24
	ds_read_b128 v[160:163], v199 offset:49152
	ds_read_b128 v[180:183], v199 offset:50176
	ds_read_b128 v[184:187], v199 offset:51200
	ds_read_b128 v[188:191], v199 offset:52224
	ds_read_b128 v[192:195], v199 offset:53248
	ds_read_b128 v[200:203], v199 offset:54272
	ds_read_b128 v[204:207], v199 offset:55296
	ds_read_b128 v[208:211], v199 offset:56320
	global_load_lds_dwordx4 v[212:213], off
	s_add_i32 m0, s24, 0x2000
	s_add_u32 s24, s26, 0xb0080
	v_lshl_add_u64 v[212:213], v[214:215], 0, s[16:17]
	s_addc_u32 s25, s27, 0
	s_add_i32 s26, s55, s35
	global_load_lds_dwordx4 v[212:213], off
	s_mov_b32 m0, s26
	v_lshl_add_u64 v[212:213], s[24:25], 0, v[166:167]
	global_load_lds_dwordx4 v[212:213], off
	s_add_i32 m0, s26, 0x2000
	v_lshl_add_u64 v[212:213], s[24:25], 0, v[170:171]
	global_load_lds_dwordx4 v[212:213], off
	s_mov_b32 m0, s41
	v_lshl_add_u64 v[212:213], v[216:217], 0, s[16:17]
	global_load_lds_dwordx4 v[212:213], off
	s_mov_b32 m0, s42
	v_lshl_add_u64 v[212:213], v[218:219], 0, s[16:17]
	global_load_lds_dwordx4 v[212:213], off
	s_waitcnt vmcnt(8) lgkmcnt(0)
	s_barrier
	s_setprio 1
	v_mfma_f32_16x16x32_bf16 v[56:59], v[128:131], v[160:163], v[56:59]
	v_mfma_f32_16x16x32_bf16 v[56:59], v[132:135], v[180:183], v[56:59]
	v_mfma_f32_16x16x32_bf16 v[40:43], v[128:131], v[184:187], v[40:43]
	v_mfma_f32_16x16x32_bf16 v[40:43], v[132:135], v[188:191], v[40:43]
	v_mfma_f32_16x16x32_bf16 v[24:27], v[128:131], v[192:195], v[24:27]
	v_mfma_f32_16x16x32_bf16 v[24:27], v[132:135], v[200:203], v[24:27]
	v_mfma_f32_16x16x32_bf16 v[8:11], v[128:131], v[204:207], v[8:11]
	v_mfma_f32_16x16x32_bf16 v[8:11], v[132:135], v[208:211], v[8:11]
	v_mfma_f32_16x16x32_bf16 v[60:63], v[136:139], v[160:163], v[60:63]
	v_mfma_f32_16x16x32_bf16 v[60:63], v[140:143], v[180:183], v[60:63]
	v_mfma_f32_16x16x32_bf16 v[44:47], v[136:139], v[184:187], v[44:47]
	v_mfma_f32_16x16x32_bf16 v[44:47], v[140:143], v[188:191], v[44:47]
	v_mfma_f32_16x16x32_bf16 v[28:31], v[136:139], v[192:195], v[28:31]
	v_mfma_f32_16x16x32_bf16 v[28:31], v[140:143], v[200:203], v[28:31]
	v_mfma_f32_16x16x32_bf16 v[12:15], v[136:139], v[204:207], v[12:15]
	v_mfma_f32_16x16x32_bf16 v[12:15], v[140:143], v[208:211], v[12:15]
	v_mfma_f32_16x16x32_bf16 v[48:51], v[144:147], v[160:163], v[48:51]
	v_mfma_f32_16x16x32_bf16 v[48:51], v[148:151], v[180:183], v[48:51]
	v_mfma_f32_16x16x32_bf16 v[32:35], v[144:147], v[184:187], v[32:35]
	v_mfma_f32_16x16x32_bf16 v[32:35], v[148:151], v[188:191], v[32:35]
	v_mfma_f32_16x16x32_bf16 v[16:19], v[144:147], v[192:195], v[16:19]
	v_mfma_f32_16x16x32_bf16 v[16:19], v[148:151], v[200:203], v[16:19]
	v_mfma_f32_16x16x32_bf16 v[0:3], v[144:147], v[204:207], v[0:3]
	v_mfma_f32_16x16x32_bf16 v[0:3], v[148:151], v[208:211], v[0:3]
	v_mfma_f32_16x16x32_bf16 v[52:55], v[152:155], v[160:163], v[52:55]
	v_mfma_f32_16x16x32_bf16 v[52:55], v[156:159], v[180:183], v[52:55]
	v_mfma_f32_16x16x32_bf16 v[36:39], v[152:155], v[184:187], v[36:39]
	v_mfma_f32_16x16x32_bf16 v[36:39], v[156:159], v[188:191], v[36:39]
	s_setprio 2
	s_barrier
	v_mfma_f32_16x16x32_bf16 v[20:23], v[152:155], v[192:195], v[20:23]
	v_mfma_f32_16x16x32_bf16 v[20:23], v[156:159], v[200:203], v[20:23]
	v_mfma_f32_16x16x32_bf16 v[4:7], v[152:155], v[204:207], v[4:7]
	v_mfma_f32_16x16x32_bf16 v[4:7], v[156:159], v[208:211], v[4:7]
	s_setprio 0
	s_add_i32 s53, s53, 2
	s_add_u32 s51, s51, 0x100
	s_addc_u32 s52, s52, 0
	s_cmp_gt_u32 s53, 41
	s_mov_b64 s[24:25], s[4:5]
	s_cbranch_scc0 .LBB0_1310
